# stack3: stack2 + first 2 MFMAs of each K-loop block before the block barrier
# speedup vs baseline: 1.0089x; 1.0089x over previous
; #define PG8_STAGE(bufoff, gbase, voff) do { _Pragma("unroll") for (int _i = 0; _i < 2; ++_i) \
;         __builtin_amdgcn_global_load_lds((const unsigned*)((const char*)(gbase) + (voff)[_i]), (PG8_LAS unsigned*)(lds + (bufoff) + ldsw + _i * 8192), 16, 0, 0); } while (0)
; #define PG8_LDA(dst, b, h) do { _Pragma("unroll") for (int m = 0; m < 4; ++m) _Pragma("unroll") for (int k = 0; k < 2; ++k) dst[m][k] = *(const PG8_LAS bf16x8*)(lds + PG8_SA(b, h) + aoff + m * 2048 + k * 1024); } while (0)
; #define PG8_LDB(dst, b, h) do { _Pragma("unroll") for (int n = 0; n < 2; ++n) _Pragma("unroll") for (int k = 0; k < 2; ++k) dst[n][k] = *(const PG8_LAS bf16x8*)(lds + PG8_SB(b, h) + boff + n * 2048 + k * 1024); } while (0)
; #define PG8_MMA(ai, bj, At, Bt) do { __builtin_amdgcn_s_setprio(1); _Pragma("unroll") for (int m = 0; m < 4; ++m) _Pragma("unroll") for (int n = 0; n < 2; ++n) _Pragma("unroll") for (int k = 0; k < 2; ++k) \
;         acc[ai][bj][m][n] = __builtin_amdgcn_mfma_f32_16x16x32_bf16(Bt[n][k], At[m][k], acc[ai][bj][m][n], 0, 0, 0); __builtin_amdgcn_s_setprio(0); } while (0)
; #define PG8_WAIT_V(n) asm volatile("s_waitcnt vmcnt(" #n ")" ::: "memory")
; #define PG8_WAIT_L(n) asm volatile("s_waitcnt lgkmcnt(" #n ")" ::: "memory")
; #define PG8_BAR __builtin_amdgcn_s_barrier()
; #define PG8_SCHED __builtin_amdgcn_sched_barrier(0)
; template <class Epi, class Sched, bool ALIGN_EPI = false, bool SP2 = false>
; __device__ __forceinline__ void gemm_phase(PG8_LAS unsigned char* lds, const Gemm g, const Sched& S, const Epi& E) {
;     ...
;             PG8_LDB(B0, 0, 0); PG8_LDB(B1, 0, 1); PG8_SCHED; PG8_LDA(At, 0, 0); PG8_STAGE(PG8_SA(1, 1), a1 + hstep, voffA);
;             PG8_WAIT_V(8); PG8_WAIT_L(0); PG8_BAR; PG8_MMA(0, 0, At, B0); PG8_MMA(0, 1, At, B1); PG8_BAR; PG8_SCHED;
;             PG8_LDA(At, 0, 1); PG8_STAGE(PG8_SB(0, 0), b2, voffB); PG8_STAGE(PG8_SB(0, 1), b2 + hstep, voffB); PG8_STAGE(PG8_SA(0, 0), a2, voffA);
;             PG8_WAIT_V(8); PG8_WAIT_L(0); PG8_BAR; PG8_MMA(1, 0, At, B0); PG8_MMA(1, 1, At, B1); PG8_BAR; PG8_SCHED;
.LBB0_289:
	ds_read_b128 v[146:149], v156
	ds_read_b128 v[160:163], v156 offset:1024
	ds_read_b128 v[164:167], v156 offset:2048
	ds_read_b128 v[168:171], v156 offset:3072
	ds_read_b128 v[180:183], v157
	ds_read_b128 v[184:187], v157 offset:1024
	ds_read_b128 v[188:191], v157 offset:2048
	ds_read_b128 v[192:195], v157 offset:3072
	s_add_u32 s24, s22, 0xfff80080
	s_addc_u32 s25, s23, -1
	s_cmp_eq_u32 s50, 28
	s_cselect_b32 s27, s15, s25
	s_cselect_b32 s26, s46, s24
	s_cselect_b32 s25, s13, s49
	s_cselect_b32 s24, s47, s48
	v_lshl_add_u64 v[150:151], s[22:23], 0, v[138:139]
	s_add_i32 m0, s21, 0xc000
	ds_read_b128 v[196:199], v158
	ds_read_b128 v[200:203], v158 offset:1024
	ds_read_b128 v[204:207], v158 offset:2048
	ds_read_b128 v[208:211], v158 offset:3072
	ds_read_b128 v[212:215], v158 offset:4096
	ds_read_b128 v[216:219], v158 offset:5120
	ds_read_b128 v[220:223], v158 offset:6144
	ds_read_b128 v[224:227], v158 offset:7168
	global_load_lds_dwordx4 v[150:151], off
	v_lshl_add_u64 v[150:151], s[22:23], 0, v[140:141]
	s_add_i32 m0, s21, 0xe000
	s_nop 0
	global_load_lds_dwordx4 v[150:151], off
	s_waitcnt vmcnt(8)
	s_waitcnt lgkmcnt(0)
	v_mfma_f32_16x16x32_bf16 v[124:127], v[146:149], v[196:199], v[124:127]
	v_mfma_f32_16x16x32_bf16 v[120:123], v[164:167], v[196:199], v[120:123]
	s_barrier
	s_waitcnt lgkmcnt(0)
	v_mfma_f32_16x16x32_bf16 v[116:119], v[146:149], v[204:207], v[116:119]
	v_mfma_f32_16x16x32_bf16 v[108:111], v[164:167], v[204:207], v[108:111]
	v_mfma_f32_16x16x32_bf16 v[100:103], v[146:149], v[212:215], v[100:103]
	v_mfma_f32_16x16x32_bf16 v[92:95], v[164:167], v[212:215], v[92:95]
	v_mfma_f32_16x16x32_bf16 v[84:87], v[146:149], v[220:223], v[84:87]
	v_mfma_f32_16x16x32_bf16 v[76:79], v[164:167], v[220:223], v[76:79]
	v_mfma_f32_16x16x32_bf16 v[124:127], v[160:163], v[200:203], v[124:127]
	v_mfma_f32_16x16x32_bf16 v[120:123], v[168:171], v[200:203], v[120:123]
	v_mfma_f32_16x16x32_bf16 v[116:119], v[160:163], v[208:211], v[116:119]
	v_mfma_f32_16x16x32_bf16 v[108:111], v[168:171], v[208:211], v[108:111]
	v_mfma_f32_16x16x32_bf16 v[100:103], v[160:163], v[216:219], v[100:103]
	v_mfma_f32_16x16x32_bf16 v[92:95], v[168:171], v[216:219], v[92:95]
	v_mfma_f32_16x16x32_bf16 v[84:87], v[160:163], v[224:227], v[84:87]
	v_mfma_f32_16x16x32_bf16 v[76:79], v[168:171], v[224:227], v[76:79]
	v_mfma_f32_16x16x32_bf16 v[112:115], v[180:183], v[196:199], v[112:115]
	v_mfma_f32_16x16x32_bf16 v[104:107], v[188:191], v[196:199], v[104:107]
	v_mfma_f32_16x16x32_bf16 v[96:99], v[180:183], v[204:207], v[96:99]
	v_mfma_f32_16x16x32_bf16 v[88:91], v[188:191], v[204:207], v[88:91]
	v_mfma_f32_16x16x32_bf16 v[80:83], v[180:183], v[212:215], v[80:83]
	v_mfma_f32_16x16x32_bf16 v[72:75], v[188:191], v[212:215], v[72:75]
	v_mfma_f32_16x16x32_bf16 v[68:71], v[180:183], v[220:223], v[68:71]
	v_mfma_f32_16x16x32_bf16 v[64:67], v[188:191], v[220:223], v[64:67]
	v_mfma_f32_16x16x32_bf16 v[112:115], v[184:187], v[200:203], v[112:115]
	v_mfma_f32_16x16x32_bf16 v[104:107], v[192:195], v[200:203], v[104:107]
	v_mfma_f32_16x16x32_bf16 v[96:99], v[184:187], v[208:211], v[96:99]
	v_mfma_f32_16x16x32_bf16 v[88:91], v[192:195], v[208:211], v[88:91]
	v_mfma_f32_16x16x32_bf16 v[80:83], v[184:187], v[216:219], v[80:83]
	v_mfma_f32_16x16x32_bf16 v[72:75], v[192:195], v[216:219], v[72:75]
	v_mfma_f32_16x16x32_bf16 v[68:71], v[184:187], v[224:227], v[68:71]
	v_mfma_f32_16x16x32_bf16 v[64:67], v[192:195], v[224:227], v[64:67]
	s_barrier
	s_add_i32 s51, s40, s30
	v_lshl_add_u64 v[150:151], s[24:25], 0, v[134:135]
	s_mov_b32 m0, s51
	ds_read_b128 v[196:199], v158 offset:16384
	ds_read_b128 v[200:203], v158 offset:17408
	ds_read_b128 v[204:207], v158 offset:18432
	ds_read_b128 v[208:211], v158 offset:19456
	ds_read_b128 v[212:215], v158 offset:20480
	ds_read_b128 v[216:219], v158 offset:21504
	ds_read_b128 v[220:223], v158 offset:22528
	ds_read_b128 v[224:227], v158 offset:23552
	global_load_lds_dwordx4 v[150:151], off
	s_add_i32 m0, s51, 0x2000
	s_add_u32 s52, s24, 0x80000
	v_lshl_add_u64 v[228:229], s[24:25], 0, v[130:131]
	s_addc_u32 s53, s25, 0
	s_add_i32 s51, s41, s30
	global_load_lds_dwordx4 v[228:229], off
	v_lshl_add_u64 v[230:231], s[52:53], 0, v[134:135]
	s_mov_b32 m0, s51
	v_lshl_add_u64 v[232:233], s[26:27], 0, v[132:133]
	global_load_lds_dwordx4 v[230:231], off
	v_lshl_add_u64 v[230:231], s[52:53], 0, v[130:131]
	s_add_i32 m0, s51, 0x2000
	s_nop 0
	global_load_lds_dwordx4 v[230:231], off
	v_lshl_add_u64 v[230:231], s[26:27], 0, v[136:137]
	s_mov_b32 m0, s21
	s_nop 0
	global_load_lds_dwordx4 v[230:231], off
	s_mov_b32 m0, s33
	s_nop 0
	global_load_lds_dwordx4 v[232:233], off
	s_waitcnt vmcnt(8)
	s_waitcnt lgkmcnt(0)
	v_mfma_f32_16x16x32_bf16 v[60:63], v[146:149], v[196:199], v[60:63]
	v_mfma_f32_16x16x32_bf16 v[56:59], v[164:167], v[196:199], v[56:59]
	s_barrier
; #define PG8_STAGE(bufoff, gbase, voff) do { _Pragma("unroll") for (int _i = 0; _i < 2; ++_i) \
;         __builtin_amdgcn_global_load_lds((const unsigned*)((const char*)(gbase) + (voff)[_i]), (PG8_LAS unsigned*)(lds + (bufoff) + ldsw + _i * 8192), 16, 0, 0); } while (0)
; #define PG8_LDA(dst, b, h) do { _Pragma("unroll") for (int m = 0; m < 4; ++m) _Pragma("unroll") for (int k = 0; k < 2; ++k) dst[m][k] = *(const PG8_LAS bf16x8*)(lds + PG8_SA(b, h) + aoff + m * 2048 + k * 1024); } while (0)
; #define PG8_LDB(dst, b, h) do { _Pragma("unroll") for (int n = 0; n < 2; ++n) _Pragma("unroll") for (int k = 0; k < 2; ++k) dst[n][k] = *(const PG8_LAS bf16x8*)(lds + PG8_SB(b, h) + boff + n * 2048 + k * 1024); } while (0)
; #define PG8_MMA(ai, bj, At, Bt) do { __builtin_amdgcn_s_setprio(1); _Pragma("unroll") for (int m = 0; m < 4; ++m) _Pragma("unroll") for (int n = 0; n < 2; ++n) _Pragma("unroll") for (int k = 0; k < 2; ++k) \
;         acc[ai][bj][m][n] = __builtin_amdgcn_mfma_f32_16x16x32_bf16(Bt[n][k], At[m][k], acc[ai][bj][m][n], 0, 0, 0); __builtin_amdgcn_s_setprio(0); } while (0)
; #define PG8_WAIT_V(n) asm volatile("s_waitcnt vmcnt(" #n ")" ::: "memory")
; #define PG8_WAIT_L(n) asm volatile("s_waitcnt lgkmcnt(" #n ")" ::: "memory")
; #define PG8_BAR __builtin_amdgcn_s_barrier()
; #define PG8_SCHED __builtin_amdgcn_sched_barrier(0)
; template <class Epi, class Sched, bool ALIGN_EPI = false, bool SP2 = false>
; __device__ __forceinline__ void gemm_phase(PG8_LAS unsigned char* lds, const Gemm g, const Sched& S, const Epi& E) {
;     ...
;             PG8_WAIT_V(8); PG8_WAIT_L(0); PG8_BAR; PG8_MMA(1, 0, At, B0); PG8_MMA(1, 1, At, B1); PG8_BAR; PG8_SCHED;
;             PG8_LDB(B0, 1, 0); PG8_LDB(B1, 1, 1); PG8_SCHED; PG8_LDA(At, 1, 0); PG8_STAGE(PG8_SA(0, 1), a2 + hstep, voffA);
;             PG8_WAIT_V(8); PG8_WAIT_L(0); PG8_BAR; PG8_MMA(0, 0, At, B0); PG8_MMA(0, 1, At, B1); PG8_BAR; PG8_SCHED;
	s_waitcnt lgkmcnt(0)
	v_mfma_f32_16x16x32_bf16 v[52:55], v[146:149], v[204:207], v[52:55]
	v_mfma_f32_16x16x32_bf16 v[44:47], v[164:167], v[204:207], v[44:47]
	v_mfma_f32_16x16x32_bf16 v[36:39], v[146:149], v[212:215], v[36:39]
	v_mfma_f32_16x16x32_bf16 v[28:31], v[164:167], v[212:215], v[28:31]
	v_mfma_f32_16x16x32_bf16 v[20:23], v[146:149], v[220:223], v[20:23]
	v_mfma_f32_16x16x32_bf16 v[12:15], v[164:167], v[220:223], v[12:15]
	v_mfma_f32_16x16x32_bf16 v[60:63], v[160:163], v[200:203], v[60:63]
	v_mfma_f32_16x16x32_bf16 v[56:59], v[168:171], v[200:203], v[56:59]
	v_mfma_f32_16x16x32_bf16 v[52:55], v[160:163], v[208:211], v[52:55]
	v_mfma_f32_16x16x32_bf16 v[44:47], v[168:171], v[208:211], v[44:47]
	v_mfma_f32_16x16x32_bf16 v[36:39], v[160:163], v[216:219], v[36:39]
	v_mfma_f32_16x16x32_bf16 v[28:31], v[168:171], v[216:219], v[28:31]
	v_mfma_f32_16x16x32_bf16 v[20:23], v[160:163], v[224:227], v[20:23]
	v_mfma_f32_16x16x32_bf16 v[12:15], v[168:171], v[224:227], v[12:15]
	v_mfma_f32_16x16x32_bf16 v[48:51], v[180:183], v[196:199], v[48:51]
	v_mfma_f32_16x16x32_bf16 v[40:43], v[188:191], v[196:199], v[40:43]
	v_mfma_f32_16x16x32_bf16 v[32:35], v[180:183], v[204:207], v[32:35]
	v_mfma_f32_16x16x32_bf16 v[24:27], v[188:191], v[204:207], v[24:27]
	v_mfma_f32_16x16x32_bf16 v[16:19], v[180:183], v[212:215], v[16:19]
	v_mfma_f32_16x16x32_bf16 v[8:11], v[188:191], v[212:215], v[8:11]
	v_mfma_f32_16x16x32_bf16 v[4:7], v[180:183], v[220:223], v[4:7]
	v_mfma_f32_16x16x32_bf16 v[0:3], v[188:191], v[220:223], v[0:3]
	v_mfma_f32_16x16x32_bf16 v[48:51], v[184:187], v[200:203], v[48:51]
	v_mfma_f32_16x16x32_bf16 v[40:43], v[192:195], v[200:203], v[40:43]
	v_mfma_f32_16x16x32_bf16 v[32:35], v[184:187], v[208:211], v[32:35]
	v_mfma_f32_16x16x32_bf16 v[24:27], v[192:195], v[208:211], v[24:27]
	v_mfma_f32_16x16x32_bf16 v[16:19], v[184:187], v[216:219], v[16:19]
	v_mfma_f32_16x16x32_bf16 v[8:11], v[192:195], v[216:219], v[8:11]
	v_mfma_f32_16x16x32_bf16 v[4:7], v[184:187], v[224:227], v[4:7]
	v_mfma_f32_16x16x32_bf16 v[0:3], v[192:195], v[224:227], v[0:3]
	s_barrier
	s_add_i32 s51, 0, 0x18000
	v_add_u32_e32 v159, s51, v153
	s_add_i32 s52, 0, 0x1c000
	ds_read_b128 v[146:149], v159
	ds_read_b128 v[160:163], v159 offset:1024
	ds_read_b128 v[164:167], v159 offset:2048
	ds_read_b128 v[168:171], v159 offset:3072
	v_add_u32_e32 v159, s52, v153
	ds_read_b128 v[180:183], v159
	ds_read_b128 v[184:187], v159 offset:1024
	ds_read_b128 v[188:191], v159 offset:2048
	ds_read_b128 v[192:195], v159 offset:3072
	s_add_u32 s26, s26, 0x80000
	s_addc_u32 s27, s27, 0
	s_mov_b32 m0, s34
	v_lshl_add_u64 v[234:235], s[26:27], 0, v[136:137]
	ds_read_b128 v[196:199], v158 offset:32768
	ds_read_b128 v[200:203], v158 offset:33792
	ds_read_b128 v[204:207], v158 offset:34816
	ds_read_b128 v[208:211], v158 offset:35840
	ds_read_b128 v[212:215], v158 offset:36864
	ds_read_b128 v[216:219], v158 offset:37888
	ds_read_b128 v[220:223], v158 offset:38912
	ds_read_b128 v[224:227], v158 offset:39936
	global_load_lds_dwordx4 v[234:235], off
	v_lshl_add_u64 v[234:235], s[26:27], 0, v[132:133]
	s_mov_b32 m0, s35
	s_nop 0
	global_load_lds_dwordx4 v[234:235], off
	s_waitcnt vmcnt(8)
	s_waitcnt lgkmcnt(0)
	v_mfma_f32_16x16x32_bf16 v[124:127], v[146:149], v[196:199], v[124:127]
	v_mfma_f32_16x16x32_bf16 v[120:123], v[164:167], v[196:199], v[120:123]
	s_barrier
	s_waitcnt lgkmcnt(0)
	v_mfma_f32_16x16x32_bf16 v[116:119], v[146:149], v[204:207], v[116:119]
	v_mfma_f32_16x16x32_bf16 v[108:111], v[164:167], v[204:207], v[108:111]
	v_mfma_f32_16x16x32_bf16 v[100:103], v[146:149], v[212:215], v[100:103]
	v_mfma_f32_16x16x32_bf16 v[92:95], v[164:167], v[212:215], v[92:95]
	v_mfma_f32_16x16x32_bf16 v[84:87], v[146:149], v[220:223], v[84:87]
	v_mfma_f32_16x16x32_bf16 v[76:79], v[164:167], v[220:223], v[76:79]
	v_mfma_f32_16x16x32_bf16 v[124:127], v[160:163], v[200:203], v[124:127]
	v_mfma_f32_16x16x32_bf16 v[120:123], v[168:171], v[200:203], v[120:123]
	v_mfma_f32_16x16x32_bf16 v[116:119], v[160:163], v[208:211], v[116:119]
	v_mfma_f32_16x16x32_bf16 v[108:111], v[168:171], v[208:211], v[108:111]
	v_mfma_f32_16x16x32_bf16 v[100:103], v[160:163], v[216:219], v[100:103]
	v_mfma_f32_16x16x32_bf16 v[92:95], v[168:171], v[216:219], v[92:95]
	v_mfma_f32_16x16x32_bf16 v[84:87], v[160:163], v[224:227], v[84:87]
	v_mfma_f32_16x16x32_bf16 v[76:79], v[168:171], v[224:227], v[76:79]
	v_mfma_f32_16x16x32_bf16 v[112:115], v[180:183], v[196:199], v[112:115]
	v_mfma_f32_16x16x32_bf16 v[104:107], v[188:191], v[196:199], v[104:107]
	v_mfma_f32_16x16x32_bf16 v[96:99], v[180:183], v[204:207], v[96:99]
	v_mfma_f32_16x16x32_bf16 v[88:91], v[188:191], v[204:207], v[88:91]
	v_mfma_f32_16x16x32_bf16 v[80:83], v[180:183], v[212:215], v[80:83]
	v_mfma_f32_16x16x32_bf16 v[72:75], v[188:191], v[212:215], v[72:75]
	v_mfma_f32_16x16x32_bf16 v[68:71], v[180:183], v[220:223], v[68:71]
	v_mfma_f32_16x16x32_bf16 v[64:67], v[188:191], v[220:223], v[64:67]
	v_mfma_f32_16x16x32_bf16 v[112:115], v[184:187], v[200:203], v[112:115]
	v_mfma_f32_16x16x32_bf16 v[104:107], v[192:195], v[200:203], v[104:107]
	v_mfma_f32_16x16x32_bf16 v[96:99], v[184:187], v[208:211], v[96:99]
	v_mfma_f32_16x16x32_bf16 v[88:91], v[192:195], v[208:211], v[88:91]
	v_mfma_f32_16x16x32_bf16 v[80:83], v[184:187], v[216:219], v[80:83]
	v_mfma_f32_16x16x32_bf16 v[72:75], v[192:195], v[216:219], v[72:75]
	v_mfma_f32_16x16x32_bf16 v[68:71], v[184:187], v[224:227], v[68:71]
	v_mfma_f32_16x16x32_bf16 v[64:67], v[192:195], v[224:227], v[64:67]
	s_barrier
; #define PG8_STAGE(bufoff, gbase, voff) do { _Pragma("unroll") for (int _i = 0; _i < 2; ++_i) \
;         __builtin_amdgcn_global_load_lds((const unsigned*)((const char*)(gbase) + (voff)[_i]), (PG8_LAS unsigned*)(lds + (bufoff) + ldsw + _i * 8192), 16, 0, 0); } while (0)
; #define PG8_LDA(dst, b, h) do { _Pragma("unroll") for (int m = 0; m < 4; ++m) _Pragma("unroll") for (int k = 0; k < 2; ++k) dst[m][k] = *(const PG8_LAS bf16x8*)(lds + PG8_SA(b, h) + aoff + m * 2048 + k * 1024); } while (0)
; #define PG8_MMA(ai, bj, At, Bt) do { __builtin_amdgcn_s_setprio(1); _Pragma("unroll") for (int m = 0; m < 4; ++m) _Pragma("unroll") for (int n = 0; n < 2; ++n) _Pragma("unroll") for (int k = 0; k < 2; ++k) \
;         acc[ai][bj][m][n] = __builtin_amdgcn_mfma_f32_16x16x32_bf16(Bt[n][k], At[m][k], acc[ai][bj][m][n], 0, 0, 0); __builtin_amdgcn_s_setprio(0); } while (0)
; #define PG8_WAIT_V(n) asm volatile("s_waitcnt vmcnt(" #n ")" ::: "memory")
; #define PG8_WAIT_L(n) asm volatile("s_waitcnt lgkmcnt(" #n ")" ::: "memory")
; #define PG8_BAR __builtin_amdgcn_s_barrier()
; #define PG8_SCHED __builtin_amdgcn_sched_barrier(0)
; template <class Epi, class Sched, bool ALIGN_EPI = false, bool SP2 = false>
; __device__ __forceinline__ void gemm_phase(PG8_LAS unsigned char* lds, const Gemm g, const Sched& S, const Epi& E) {
;     ...
;             PG8_LDA(At, 1, 1); PG8_STAGE(PG8_SB(1, 0), b3, voffB); PG8_STAGE(PG8_SB(1, 1), b3 + hstep, voffB); PG8_STAGE(PG8_SA(1, 0), a3, voffA);
;             PG8_WAIT_V(8); PG8_WAIT_L(0); PG8_BAR; PG8_MMA(1, 0, At, B0); PG8_MMA(1, 1, At, B1); PG8_BAR; PG8_SCHED;
;     ...
;         if constexpr (ALIGN_EPI) { if (wr == 0) PG8_BAR; }
	s_add_i32 s26, s51, s30
	v_lshl_add_u64 v[150:151], v[150:151], 0, s[2:3]
	s_mov_b32 m0, s26
	ds_read_b128 v[196:199], v158 offset:49152
	ds_read_b128 v[200:203], v158 offset:50176
	ds_read_b128 v[204:207], v158 offset:51200
	ds_read_b128 v[208:211], v158 offset:52224
	ds_read_b128 v[212:215], v158 offset:53248
	ds_read_b128 v[216:219], v158 offset:54272
	ds_read_b128 v[220:223], v158 offset:55296
	ds_read_b128 v[224:227], v158 offset:56320
	global_load_lds_dwordx4 v[150:151], off
	s_add_i32 m0, s26, 0x2000
	s_add_u32 s24, s24, 0x80080
	v_lshl_add_u64 v[150:151], v[228:229], 0, s[2:3]
	s_addc_u32 s25, s25, 0
	s_add_i32 s26, s52, s30
	global_load_lds_dwordx4 v[150:151], off
	v_lshl_add_u64 v[150:151], s[24:25], 0, v[134:135]
	s_mov_b32 m0, s26
	s_nop 0
	global_load_lds_dwordx4 v[150:151], off
	v_lshl_add_u64 v[150:151], s[24:25], 0, v[130:131]
	s_add_i32 m0, s26, 0x2000
	s_nop 0
	global_load_lds_dwordx4 v[150:151], off
	v_lshl_add_u64 v[150:151], v[230:231], 0, s[2:3]
	s_mov_b32 m0, s36
	s_nop 0
	global_load_lds_dwordx4 v[150:151], off
	v_lshl_add_u64 v[150:151], v[232:233], 0, s[2:3]
	s_mov_b32 m0, s37
	s_nop 0
	global_load_lds_dwordx4 v[150:151], off
	s_waitcnt vmcnt(8)
	s_waitcnt lgkmcnt(0)
	v_mfma_f32_16x16x32_bf16 v[60:63], v[146:149], v[196:199], v[60:63]
	v_mfma_f32_16x16x32_bf16 v[56:59], v[164:167], v[196:199], v[56:59]
	s_barrier
	s_waitcnt lgkmcnt(0)
	v_mfma_f32_16x16x32_bf16 v[52:55], v[146:149], v[204:207], v[52:55]
	v_mfma_f32_16x16x32_bf16 v[44:47], v[164:167], v[204:207], v[44:47]
	v_mfma_f32_16x16x32_bf16 v[36:39], v[146:149], v[212:215], v[36:39]
	v_mfma_f32_16x16x32_bf16 v[28:31], v[164:167], v[212:215], v[28:31]
	v_mfma_f32_16x16x32_bf16 v[20:23], v[146:149], v[220:223], v[20:23]
	v_mfma_f32_16x16x32_bf16 v[12:15], v[164:167], v[220:223], v[12:15]
	v_mfma_f32_16x16x32_bf16 v[60:63], v[160:163], v[200:203], v[60:63]
	v_mfma_f32_16x16x32_bf16 v[56:59], v[168:171], v[200:203], v[56:59]
	v_mfma_f32_16x16x32_bf16 v[52:55], v[160:163], v[208:211], v[52:55]
	v_mfma_f32_16x16x32_bf16 v[44:47], v[168:171], v[208:211], v[44:47]
	v_mfma_f32_16x16x32_bf16 v[36:39], v[160:163], v[216:219], v[36:39]
	v_mfma_f32_16x16x32_bf16 v[28:31], v[168:171], v[216:219], v[28:31]
	v_mfma_f32_16x16x32_bf16 v[20:23], v[160:163], v[224:227], v[20:23]
	v_mfma_f32_16x16x32_bf16 v[12:15], v[168:171], v[224:227], v[12:15]
	v_mfma_f32_16x16x32_bf16 v[48:51], v[180:183], v[196:199], v[48:51]
	v_mfma_f32_16x16x32_bf16 v[40:43], v[188:191], v[196:199], v[40:43]
	v_mfma_f32_16x16x32_bf16 v[32:35], v[180:183], v[204:207], v[32:35]
	v_mfma_f32_16x16x32_bf16 v[24:27], v[188:191], v[204:207], v[24:27]
	v_mfma_f32_16x16x32_bf16 v[16:19], v[180:183], v[212:215], v[16:19]
	v_mfma_f32_16x16x32_bf16 v[8:11], v[188:191], v[212:215], v[8:11]
	v_mfma_f32_16x16x32_bf16 v[4:7], v[180:183], v[220:223], v[4:7]
	v_mfma_f32_16x16x32_bf16 v[0:3], v[188:191], v[220:223], v[0:3]
	v_mfma_f32_16x16x32_bf16 v[48:51], v[184:187], v[200:203], v[48:51]
	v_mfma_f32_16x16x32_bf16 v[40:43], v[192:195], v[200:203], v[40:43]
	v_mfma_f32_16x16x32_bf16 v[32:35], v[184:187], v[208:211], v[32:35]
	v_mfma_f32_16x16x32_bf16 v[24:27], v[192:195], v[208:211], v[24:27]
	v_mfma_f32_16x16x32_bf16 v[16:19], v[184:187], v[216:219], v[16:19]
	v_mfma_f32_16x16x32_bf16 v[8:11], v[192:195], v[216:219], v[8:11]
	v_mfma_f32_16x16x32_bf16 v[4:7], v[184:187], v[224:227], v[4:7]
	v_mfma_f32_16x16x32_bf16 v[0:3], v[192:195], v[224:227], v[0:3]
	s_barrier
	s_add_i32 s50, s50, 2
	s_add_u32 s22, s22, 0x100
	s_addc_u32 s23, s23, 0
	s_add_u32 s48, s48, 0x100
	s_addc_u32 s49, s49, 0
	s_cmp_gt_u32 s50, 29
	s_cbranch_scc0 .LBB0_289
	s_and_b64 vcc, exec, s[4:5]
	s_cbranch_vccz .LBB0_292
	s_barrier

; #define PG8_STAGE(bufoff, gbase, voff) do { _Pragma("unroll") for (int _i = 0; _i < 2; ++_i) \
;         __builtin_amdgcn_global_load_lds((const unsigned*)((const char*)(gbase) + (voff)[_i]), (PG8_LAS unsigned*)(lds + (bufoff) + ldsw + _i * 8192), 16, 0, 0); } while (0)
; #define PG8_LDA(dst, b, h) do { _Pragma("unroll") for (int m = 0; m < 4; ++m) _Pragma("unroll") for (int k = 0; k < 2; ++k) dst[m][k] = *(const PG8_LAS bf16x8*)(lds + PG8_SA(b, h) + aoff + m * 2048 + k * 1024); } while (0)
; #define PG8_LDB(dst, b, h) do { _Pragma("unroll") for (int n = 0; n < 2; ++n) _Pragma("unroll") for (int k = 0; k < 2; ++k) dst[n][k] = *(const PG8_LAS bf16x8*)(lds + PG8_SB(b, h) + boff + n * 2048 + k * 1024); } while (0)
; #define PG8_MMA(ai, bj, At, Bt) do { __builtin_amdgcn_s_setprio(1); _Pragma("unroll") for (int m = 0; m < 4; ++m) _Pragma("unroll") for (int n = 0; n < 2; ++n) _Pragma("unroll") for (int k = 0; k < 2; ++k) \
;         acc[ai][bj][m][n] = __builtin_amdgcn_mfma_f32_16x16x32_bf16(Bt[n][k], At[m][k], acc[ai][bj][m][n], 0, 0, 0); __builtin_amdgcn_s_setprio(0); } while (0)
; #define PG8_WAIT_V(n) asm volatile("s_waitcnt vmcnt(" #n ")" ::: "memory")
; #define PG8_WAIT_L(n) asm volatile("s_waitcnt lgkmcnt(" #n ")" ::: "memory")
; #define PG8_BAR __builtin_amdgcn_s_barrier()
; #define PG8_SCHED __builtin_amdgcn_sched_barrier(0)
; template <class Epi, class Sched, bool ALIGN_EPI = false, bool SP2 = false>
; __device__ __forceinline__ void gemm_phase(PG8_LAS unsigned char* lds, const Gemm g, const Sched& S, const Epi& E) {
;     ...
;             PG8_LDB(B0, 0, 0); PG8_LDB(B1, 0, 1); PG8_SCHED; PG8_LDA(At, 0, 0); PG8_STAGE(PG8_SA(1, 1), a1 + hstep, voffA);
;             PG8_WAIT_V(8); PG8_WAIT_L(0); PG8_BAR; PG8_MMA(0, 0, At, B0); PG8_MMA(0, 1, At, B1); PG8_BAR; PG8_SCHED;
;             PG8_LDA(At, 0, 1); PG8_STAGE(PG8_SB(0, 0), b2, voffB); PG8_STAGE(PG8_SB(0, 1), b2 + hstep, voffB); PG8_STAGE(PG8_SA(0, 0), a2, voffA);
;             PG8_WAIT_V(8); PG8_WAIT_L(0); PG8_BAR; PG8_MMA(1, 0, At, B0); PG8_MMA(1, 1, At, B1); PG8_BAR; PG8_SCHED;
.LBB0_585:
	ds_read_b128 v[142:145], v149
	ds_read_b128 v[152:155], v149 offset:1024
	ds_read_b128 v[156:159], v149 offset:2048
	ds_read_b128 v[160:163], v149 offset:3072
	ds_read_b128 v[164:167], v150
	ds_read_b128 v[168:171], v150 offset:1024
	ds_read_b128 v[180:183], v150 offset:2048
	ds_read_b128 v[184:187], v150 offset:3072
	s_add_u32 s26, s24, 0xfff80080
	s_addc_u32 s27, s25, -1
	s_cmp_eq_u32 s51, 28
	s_cselect_b32 s29, s17, s27
	s_cselect_b32 s28, s23, s26
	s_cselect_b32 s27, s13, s50
	s_cselect_b32 s26, s48, s49
	v_lshl_add_u64 v[220:221], s[24:25], 0, v[134:135]
	s_add_i32 m0, s34, 0xc000
	ds_read_b128 v[188:191], v151
	ds_read_b128 v[192:195], v151 offset:1024
	ds_read_b128 v[196:199], v151 offset:2048
	ds_read_b128 v[200:203], v151 offset:3072
	ds_read_b128 v[204:207], v151 offset:4096
	ds_read_b128 v[208:211], v151 offset:5120
	ds_read_b128 v[212:215], v151 offset:6144
	ds_read_b128 v[216:219], v151 offset:7168
	global_load_lds_dwordx4 v[220:221], off
	v_lshl_add_u64 v[220:221], s[24:25], 0, v[136:137]
	s_add_i32 m0, s34, 0xe000
	s_nop 0
	global_load_lds_dwordx4 v[220:221], off
	s_waitcnt vmcnt(8)
	s_waitcnt lgkmcnt(0)
	v_mfma_f32_16x16x32_bf16 v[124:127], v[142:145], v[188:191], v[124:127]
	v_mfma_f32_16x16x32_bf16 v[120:123], v[156:159], v[188:191], v[120:123]
	s_barrier
	s_waitcnt lgkmcnt(0)
	v_mfma_f32_16x16x32_bf16 v[108:111], v[142:145], v[196:199], v[108:111]
	v_mfma_f32_16x16x32_bf16 v[104:107], v[156:159], v[196:199], v[104:107]
	v_mfma_f32_16x16x32_bf16 v[92:95], v[142:145], v[204:207], v[92:95]
	v_mfma_f32_16x16x32_bf16 v[88:91], v[156:159], v[204:207], v[88:91]
	v_mfma_f32_16x16x32_bf16 v[76:79], v[142:145], v[212:215], v[76:79]
	v_mfma_f32_16x16x32_bf16 v[72:75], v[156:159], v[212:215], v[72:75]
	v_mfma_f32_16x16x32_bf16 v[124:127], v[152:155], v[192:195], v[124:127]
	v_mfma_f32_16x16x32_bf16 v[120:123], v[160:163], v[192:195], v[120:123]
	v_mfma_f32_16x16x32_bf16 v[108:111], v[152:155], v[200:203], v[108:111]
	v_mfma_f32_16x16x32_bf16 v[104:107], v[160:163], v[200:203], v[104:107]
	v_mfma_f32_16x16x32_bf16 v[92:95], v[152:155], v[208:211], v[92:95]
	v_mfma_f32_16x16x32_bf16 v[88:91], v[160:163], v[208:211], v[88:91]
	v_mfma_f32_16x16x32_bf16 v[76:79], v[152:155], v[216:219], v[76:79]
	v_mfma_f32_16x16x32_bf16 v[72:75], v[160:163], v[216:219], v[72:75]
	v_mfma_f32_16x16x32_bf16 v[116:119], v[164:167], v[188:191], v[116:119]
	v_mfma_f32_16x16x32_bf16 v[112:115], v[180:183], v[188:191], v[112:115]
	v_mfma_f32_16x16x32_bf16 v[100:103], v[164:167], v[196:199], v[100:103]
	v_mfma_f32_16x16x32_bf16 v[96:99], v[180:183], v[196:199], v[96:99]
	v_mfma_f32_16x16x32_bf16 v[84:87], v[164:167], v[204:207], v[84:87]
	v_mfma_f32_16x16x32_bf16 v[80:83], v[180:183], v[204:207], v[80:83]
	v_mfma_f32_16x16x32_bf16 v[68:71], v[164:167], v[212:215], v[68:71]
	v_mfma_f32_16x16x32_bf16 v[64:67], v[180:183], v[212:215], v[64:67]
	v_mfma_f32_16x16x32_bf16 v[116:119], v[168:171], v[192:195], v[116:119]
	v_mfma_f32_16x16x32_bf16 v[112:115], v[184:187], v[192:195], v[112:115]
	v_mfma_f32_16x16x32_bf16 v[100:103], v[168:171], v[200:203], v[100:103]
	v_mfma_f32_16x16x32_bf16 v[96:99], v[184:187], v[200:203], v[96:99]
	v_mfma_f32_16x16x32_bf16 v[84:87], v[168:171], v[208:211], v[84:87]
	v_mfma_f32_16x16x32_bf16 v[80:83], v[184:187], v[208:211], v[80:83]
	v_mfma_f32_16x16x32_bf16 v[68:71], v[168:171], v[216:219], v[68:71]
	v_mfma_f32_16x16x32_bf16 v[64:67], v[184:187], v[216:219], v[64:67]
	s_barrier
	s_add_i32 s52, s45, s33
	v_lshl_add_u64 v[220:221], s[26:27], 0, v[130:131]
	s_mov_b32 m0, s52
	ds_read_b128 v[188:191], v151 offset:16384
	ds_read_b128 v[192:195], v151 offset:17408
	ds_read_b128 v[196:199], v151 offset:18432
	ds_read_b128 v[200:203], v151 offset:19456
	ds_read_b128 v[204:207], v151 offset:20480
	ds_read_b128 v[208:211], v151 offset:21504
	ds_read_b128 v[212:215], v151 offset:22528
	ds_read_b128 v[216:219], v151 offset:23552
	global_load_lds_dwordx4 v[220:221], off
	s_add_i32 m0, s52, 0x2000
	s_add_u32 s52, s26, 0x80000
	v_lshl_add_u64 v[222:223], s[26:27], 0, v[132:133]
	s_addc_u32 s53, s27, 0
	s_add_i32 s54, s46, s33
	global_load_lds_dwordx4 v[222:223], off
	v_lshl_add_u64 v[224:225], s[52:53], 0, v[130:131]
	s_mov_b32 m0, s54
	v_lshl_add_u64 v[226:227], s[28:29], 0, v[132:133]
	global_load_lds_dwordx4 v[224:225], off
	v_lshl_add_u64 v[224:225], s[52:53], 0, v[132:133]
	s_add_i32 m0, s54, 0x2000
	s_nop 0
	global_load_lds_dwordx4 v[224:225], off
	v_lshl_add_u64 v[224:225], s[28:29], 0, v[130:131]
	s_mov_b32 m0, s34
	s_nop 0
	global_load_lds_dwordx4 v[224:225], off
	s_mov_b32 m0, s35
	s_nop 0
	global_load_lds_dwordx4 v[226:227], off
	s_waitcnt vmcnt(8)
	s_waitcnt lgkmcnt(0)
	v_mfma_f32_16x16x32_bf16 v[60:63], v[142:145], v[188:191], v[60:63]
	v_mfma_f32_16x16x32_bf16 v[56:59], v[156:159], v[188:191], v[56:59]
	s_barrier
; #define PG8_STAGE(bufoff, gbase, voff) do { _Pragma("unroll") for (int _i = 0; _i < 2; ++_i) \
;         __builtin_amdgcn_global_load_lds((const unsigned*)((const char*)(gbase) + (voff)[_i]), (PG8_LAS unsigned*)(lds + (bufoff) + ldsw + _i * 8192), 16, 0, 0); } while (0)
; #define PG8_LDA(dst, b, h) do { _Pragma("unroll") for (int m = 0; m < 4; ++m) _Pragma("unroll") for (int k = 0; k < 2; ++k) dst[m][k] = *(const PG8_LAS bf16x8*)(lds + PG8_SA(b, h) + aoff + m * 2048 + k * 1024); } while (0)
; #define PG8_LDB(dst, b, h) do { _Pragma("unroll") for (int n = 0; n < 2; ++n) _Pragma("unroll") for (int k = 0; k < 2; ++k) dst[n][k] = *(const PG8_LAS bf16x8*)(lds + PG8_SB(b, h) + boff + n * 2048 + k * 1024); } while (0)
; #define PG8_MMA(ai, bj, At, Bt) do { __builtin_amdgcn_s_setprio(1); _Pragma("unroll") for (int m = 0; m < 4; ++m) _Pragma("unroll") for (int n = 0; n < 2; ++n) _Pragma("unroll") for (int k = 0; k < 2; ++k) \
;         acc[ai][bj][m][n] = __builtin_amdgcn_mfma_f32_16x16x32_bf16(Bt[n][k], At[m][k], acc[ai][bj][m][n], 0, 0, 0); __builtin_amdgcn_s_setprio(0); } while (0)
; #define PG8_WAIT_V(n) asm volatile("s_waitcnt vmcnt(" #n ")" ::: "memory")
; #define PG8_WAIT_L(n) asm volatile("s_waitcnt lgkmcnt(" #n ")" ::: "memory")
; #define PG8_BAR __builtin_amdgcn_s_barrier()
; #define PG8_SCHED __builtin_amdgcn_sched_barrier(0)
; template <class Epi, class Sched, bool ALIGN_EPI = false, bool SP2 = false>
; __device__ __forceinline__ void gemm_phase(PG8_LAS unsigned char* lds, const Gemm g, const Sched& S, const Epi& E) {
;     ...
;             PG8_WAIT_V(8); PG8_WAIT_L(0); PG8_BAR; PG8_MMA(1, 0, At, B0); PG8_MMA(1, 1, At, B1); PG8_BAR; PG8_SCHED;
;             PG8_LDB(B0, 1, 0); PG8_LDB(B1, 1, 1); PG8_SCHED; PG8_LDA(At, 1, 0); PG8_STAGE(PG8_SA(0, 1), a2 + hstep, voffA);
;             PG8_WAIT_V(8); PG8_WAIT_L(0); PG8_BAR; PG8_MMA(0, 0, At, B0); PG8_MMA(0, 1, At, B1); PG8_BAR; PG8_SCHED;
	s_waitcnt lgkmcnt(0)
	v_mfma_f32_16x16x32_bf16 v[44:47], v[142:145], v[196:199], v[44:47]
	v_mfma_f32_16x16x32_bf16 v[40:43], v[156:159], v[196:199], v[40:43]
	v_mfma_f32_16x16x32_bf16 v[28:31], v[142:145], v[204:207], v[28:31]
	v_mfma_f32_16x16x32_bf16 v[24:27], v[156:159], v[204:207], v[24:27]
	v_mfma_f32_16x16x32_bf16 v[12:15], v[142:145], v[212:215], v[12:15]
	v_mfma_f32_16x16x32_bf16 v[8:11], v[156:159], v[212:215], v[8:11]
	v_mfma_f32_16x16x32_bf16 v[60:63], v[152:155], v[192:195], v[60:63]
	v_mfma_f32_16x16x32_bf16 v[56:59], v[160:163], v[192:195], v[56:59]
	v_mfma_f32_16x16x32_bf16 v[44:47], v[152:155], v[200:203], v[44:47]
	v_mfma_f32_16x16x32_bf16 v[40:43], v[160:163], v[200:203], v[40:43]
	v_mfma_f32_16x16x32_bf16 v[28:31], v[152:155], v[208:211], v[28:31]
	v_mfma_f32_16x16x32_bf16 v[24:27], v[160:163], v[208:211], v[24:27]
	v_mfma_f32_16x16x32_bf16 v[12:15], v[152:155], v[216:219], v[12:15]
	v_mfma_f32_16x16x32_bf16 v[8:11], v[160:163], v[216:219], v[8:11]
	v_mfma_f32_16x16x32_bf16 v[52:55], v[164:167], v[188:191], v[52:55]
	v_mfma_f32_16x16x32_bf16 v[48:51], v[180:183], v[188:191], v[48:51]
	v_mfma_f32_16x16x32_bf16 v[36:39], v[164:167], v[196:199], v[36:39]
	v_mfma_f32_16x16x32_bf16 v[32:35], v[180:183], v[196:199], v[32:35]
	v_mfma_f32_16x16x32_bf16 v[20:23], v[164:167], v[204:207], v[20:23]
	v_mfma_f32_16x16x32_bf16 v[16:19], v[180:183], v[204:207], v[16:19]
	v_mfma_f32_16x16x32_bf16 v[4:7], v[164:167], v[212:215], v[4:7]
	v_mfma_f32_16x16x32_bf16 v[0:3], v[180:183], v[212:215], v[0:3]
	v_mfma_f32_16x16x32_bf16 v[52:55], v[168:171], v[192:195], v[52:55]
	v_mfma_f32_16x16x32_bf16 v[48:51], v[184:187], v[192:195], v[48:51]
	v_mfma_f32_16x16x32_bf16 v[36:39], v[168:171], v[200:203], v[36:39]
	v_mfma_f32_16x16x32_bf16 v[32:35], v[184:187], v[200:203], v[32:35]
	v_mfma_f32_16x16x32_bf16 v[20:23], v[168:171], v[208:211], v[20:23]
	v_mfma_f32_16x16x32_bf16 v[16:19], v[184:187], v[208:211], v[16:19]
	v_mfma_f32_16x16x32_bf16 v[4:7], v[168:171], v[216:219], v[4:7]
	v_mfma_f32_16x16x32_bf16 v[0:3], v[184:187], v[216:219], v[0:3]
	s_barrier
	s_add_i32 s52, 0, 0x18000
	s_add_i32 s53, 0, 0x1c000
	v_add_u32_e32 v160, s52, v147
	v_add_u32_e32 v179, s53, v147
	ds_read_b128 v[142:145], v160
	ds_read_b128 v[152:155], v160 offset:1024
	ds_read_b128 v[156:159], v160 offset:2048
	ds_read_b128 v[160:163], v160 offset:3072
	ds_read_b128 v[164:167], v179
	ds_read_b128 v[168:171], v179 offset:1024
	ds_read_b128 v[180:183], v179 offset:2048
	ds_read_b128 v[184:187], v179 offset:3072
	s_add_u32 s28, s28, 0x80000
	s_addc_u32 s29, s29, 0
	s_mov_b32 m0, s36
	v_lshl_add_u64 v[228:229], s[28:29], 0, v[130:131]
	ds_read_b128 v[188:191], v151 offset:32768
	ds_read_b128 v[192:195], v151 offset:33792
	ds_read_b128 v[196:199], v151 offset:34816
	ds_read_b128 v[200:203], v151 offset:35840
	ds_read_b128 v[204:207], v151 offset:36864
	ds_read_b128 v[208:211], v151 offset:37888
	ds_read_b128 v[212:215], v151 offset:38912
	ds_read_b128 v[216:219], v151 offset:39936
	global_load_lds_dwordx4 v[228:229], off
	v_lshl_add_u64 v[228:229], s[28:29], 0, v[132:133]
	s_mov_b32 m0, s37
	s_nop 0
	global_load_lds_dwordx4 v[228:229], off
	s_waitcnt vmcnt(8)
	s_waitcnt lgkmcnt(0)
	v_mfma_f32_16x16x32_bf16 v[124:127], v[142:145], v[188:191], v[124:127]
	v_mfma_f32_16x16x32_bf16 v[120:123], v[156:159], v[188:191], v[120:123]
	s_barrier
	s_waitcnt lgkmcnt(0)
	v_mfma_f32_16x16x32_bf16 v[108:111], v[142:145], v[196:199], v[108:111]
	v_mfma_f32_16x16x32_bf16 v[104:107], v[156:159], v[196:199], v[104:107]
	v_mfma_f32_16x16x32_bf16 v[92:95], v[142:145], v[204:207], v[92:95]
	v_mfma_f32_16x16x32_bf16 v[88:91], v[156:159], v[204:207], v[88:91]
	v_mfma_f32_16x16x32_bf16 v[76:79], v[142:145], v[212:215], v[76:79]
	v_mfma_f32_16x16x32_bf16 v[72:75], v[156:159], v[212:215], v[72:75]
	v_mfma_f32_16x16x32_bf16 v[124:127], v[152:155], v[192:195], v[124:127]
	v_mfma_f32_16x16x32_bf16 v[120:123], v[160:163], v[192:195], v[120:123]
	v_mfma_f32_16x16x32_bf16 v[108:111], v[152:155], v[200:203], v[108:111]
	v_mfma_f32_16x16x32_bf16 v[104:107], v[160:163], v[200:203], v[104:107]
	v_mfma_f32_16x16x32_bf16 v[92:95], v[152:155], v[208:211], v[92:95]
	v_mfma_f32_16x16x32_bf16 v[88:91], v[160:163], v[208:211], v[88:91]
	v_mfma_f32_16x16x32_bf16 v[76:79], v[152:155], v[216:219], v[76:79]
	v_mfma_f32_16x16x32_bf16 v[72:75], v[160:163], v[216:219], v[72:75]
	v_mfma_f32_16x16x32_bf16 v[116:119], v[164:167], v[188:191], v[116:119]
	v_mfma_f32_16x16x32_bf16 v[112:115], v[180:183], v[188:191], v[112:115]
	v_mfma_f32_16x16x32_bf16 v[100:103], v[164:167], v[196:199], v[100:103]
	v_mfma_f32_16x16x32_bf16 v[96:99], v[180:183], v[196:199], v[96:99]
	v_mfma_f32_16x16x32_bf16 v[84:87], v[164:167], v[204:207], v[84:87]
	v_mfma_f32_16x16x32_bf16 v[80:83], v[180:183], v[204:207], v[80:83]
	v_mfma_f32_16x16x32_bf16 v[68:71], v[164:167], v[212:215], v[68:71]
	v_mfma_f32_16x16x32_bf16 v[64:67], v[180:183], v[212:215], v[64:67]
	v_mfma_f32_16x16x32_bf16 v[116:119], v[168:171], v[192:195], v[116:119]
	v_mfma_f32_16x16x32_bf16 v[112:115], v[184:187], v[192:195], v[112:115]
	v_mfma_f32_16x16x32_bf16 v[100:103], v[168:171], v[200:203], v[100:103]
	v_mfma_f32_16x16x32_bf16 v[96:99], v[184:187], v[200:203], v[96:99]
	v_mfma_f32_16x16x32_bf16 v[84:87], v[168:171], v[208:211], v[84:87]
	v_mfma_f32_16x16x32_bf16 v[80:83], v[184:187], v[208:211], v[80:83]
	v_mfma_f32_16x16x32_bf16 v[68:71], v[168:171], v[216:219], v[68:71]
	v_mfma_f32_16x16x32_bf16 v[64:67], v[184:187], v[216:219], v[64:67]
	s_barrier
; #define PG8_STAGE(bufoff, gbase, voff) do { _Pragma("unroll") for (int _i = 0; _i < 2; ++_i) \
;         __builtin_amdgcn_global_load_lds((const unsigned*)((const char*)(gbase) + (voff)[_i]), (PG8_LAS unsigned*)(lds + (bufoff) + ldsw + _i * 8192), 16, 0, 0); } while (0)
; #define PG8_LDA(dst, b, h) do { _Pragma("unroll") for (int m = 0; m < 4; ++m) _Pragma("unroll") for (int k = 0; k < 2; ++k) dst[m][k] = *(const PG8_LAS bf16x8*)(lds + PG8_SA(b, h) + aoff + m * 2048 + k * 1024); } while (0)
; #define PG8_MMA(ai, bj, At, Bt) do { __builtin_amdgcn_s_setprio(1); _Pragma("unroll") for (int m = 0; m < 4; ++m) _Pragma("unroll") for (int n = 0; n < 2; ++n) _Pragma("unroll") for (int k = 0; k < 2; ++k) \
;         acc[ai][bj][m][n] = __builtin_amdgcn_mfma_f32_16x16x32_bf16(Bt[n][k], At[m][k], acc[ai][bj][m][n], 0, 0, 0); __builtin_amdgcn_s_setprio(0); } while (0)
; #define PG8_WAIT_V(n) asm volatile("s_waitcnt vmcnt(" #n ")" ::: "memory")
; #define PG8_WAIT_L(n) asm volatile("s_waitcnt lgkmcnt(" #n ")" ::: "memory")
; #define PG8_BAR __builtin_amdgcn_s_barrier()
; #define PG8_SCHED __builtin_amdgcn_sched_barrier(0)
; template <class Epi, class Sched, bool ALIGN_EPI = false, bool SP2 = false>
; __device__ __forceinline__ void gemm_phase(PG8_LAS unsigned char* lds, const Gemm g, const Sched& S, const Epi& E) {
;     ...
;             PG8_LDA(At, 1, 1); PG8_STAGE(PG8_SB(1, 0), b3, voffB); PG8_STAGE(PG8_SB(1, 1), b3 + hstep, voffB); PG8_STAGE(PG8_SA(1, 0), a3, voffA);
;             PG8_WAIT_V(8); PG8_WAIT_L(0); PG8_BAR; PG8_MMA(1, 0, At, B0); PG8_MMA(1, 1, At, B1); PG8_BAR; PG8_SCHED;
;     ...
;         if constexpr (ALIGN_EPI) { if (wr == 0) PG8_BAR; }
	s_add_i32 s28, s52, s33
	v_lshl_add_u64 v[220:221], v[220:221], 0, s[4:5]
	s_mov_b32 m0, s28
	ds_read_b128 v[188:191], v151 offset:49152
	ds_read_b128 v[192:195], v151 offset:50176
	ds_read_b128 v[196:199], v151 offset:51200
	ds_read_b128 v[200:203], v151 offset:52224
	ds_read_b128 v[204:207], v151 offset:53248
	ds_read_b128 v[208:211], v151 offset:54272
	ds_read_b128 v[212:215], v151 offset:55296
	ds_read_b128 v[216:219], v151 offset:56320
	global_load_lds_dwordx4 v[220:221], off
	s_add_i32 m0, s28, 0x2000
	s_add_u32 s26, s26, 0x80080
	v_lshl_add_u64 v[220:221], v[222:223], 0, s[4:5]
	s_addc_u32 s27, s27, 0
	s_add_i32 s28, s53, s33
	global_load_lds_dwordx4 v[220:221], off
	v_lshl_add_u64 v[220:221], s[26:27], 0, v[130:131]
	s_mov_b32 m0, s28
	s_nop 0
	global_load_lds_dwordx4 v[220:221], off
	v_lshl_add_u64 v[220:221], s[26:27], 0, v[132:133]
	s_add_i32 m0, s28, 0x2000
	s_nop 0
	global_load_lds_dwordx4 v[220:221], off
	v_lshl_add_u64 v[220:221], v[224:225], 0, s[4:5]
	s_mov_b32 m0, s41
	s_nop 0
	global_load_lds_dwordx4 v[220:221], off
	v_lshl_add_u64 v[220:221], v[226:227], 0, s[4:5]
	s_mov_b32 m0, s44
	s_nop 0
	global_load_lds_dwordx4 v[220:221], off
	s_waitcnt vmcnt(8)
	s_waitcnt lgkmcnt(0)
	v_mfma_f32_16x16x32_bf16 v[60:63], v[142:145], v[188:191], v[60:63]
	v_mfma_f32_16x16x32_bf16 v[56:59], v[156:159], v[188:191], v[56:59]
	s_barrier
	s_waitcnt lgkmcnt(0)
	v_mfma_f32_16x16x32_bf16 v[44:47], v[142:145], v[196:199], v[44:47]
	v_mfma_f32_16x16x32_bf16 v[40:43], v[156:159], v[196:199], v[40:43]
	v_mfma_f32_16x16x32_bf16 v[28:31], v[142:145], v[204:207], v[28:31]
	v_mfma_f32_16x16x32_bf16 v[24:27], v[156:159], v[204:207], v[24:27]
	v_mfma_f32_16x16x32_bf16 v[12:15], v[142:145], v[212:215], v[12:15]
	v_mfma_f32_16x16x32_bf16 v[8:11], v[156:159], v[212:215], v[8:11]
	v_mfma_f32_16x16x32_bf16 v[60:63], v[152:155], v[192:195], v[60:63]
	v_mfma_f32_16x16x32_bf16 v[56:59], v[160:163], v[192:195], v[56:59]
	v_mfma_f32_16x16x32_bf16 v[44:47], v[152:155], v[200:203], v[44:47]
	v_mfma_f32_16x16x32_bf16 v[40:43], v[160:163], v[200:203], v[40:43]
	v_mfma_f32_16x16x32_bf16 v[28:31], v[152:155], v[208:211], v[28:31]
	v_mfma_f32_16x16x32_bf16 v[24:27], v[160:163], v[208:211], v[24:27]
	v_mfma_f32_16x16x32_bf16 v[12:15], v[152:155], v[216:219], v[12:15]
	v_mfma_f32_16x16x32_bf16 v[8:11], v[160:163], v[216:219], v[8:11]
	v_mfma_f32_16x16x32_bf16 v[52:55], v[164:167], v[188:191], v[52:55]
	v_mfma_f32_16x16x32_bf16 v[48:51], v[180:183], v[188:191], v[48:51]
	v_mfma_f32_16x16x32_bf16 v[36:39], v[164:167], v[196:199], v[36:39]
	v_mfma_f32_16x16x32_bf16 v[32:35], v[180:183], v[196:199], v[32:35]
	v_mfma_f32_16x16x32_bf16 v[20:23], v[164:167], v[204:207], v[20:23]
	v_mfma_f32_16x16x32_bf16 v[16:19], v[180:183], v[204:207], v[16:19]
	v_mfma_f32_16x16x32_bf16 v[4:7], v[164:167], v[212:215], v[4:7]
	v_mfma_f32_16x16x32_bf16 v[0:3], v[180:183], v[212:215], v[0:3]
	v_mfma_f32_16x16x32_bf16 v[52:55], v[168:171], v[192:195], v[52:55]
	v_mfma_f32_16x16x32_bf16 v[48:51], v[184:187], v[192:195], v[48:51]
	v_mfma_f32_16x16x32_bf16 v[36:39], v[168:171], v[200:203], v[36:39]
	v_mfma_f32_16x16x32_bf16 v[32:35], v[184:187], v[200:203], v[32:35]
	v_mfma_f32_16x16x32_bf16 v[20:23], v[168:171], v[208:211], v[20:23]
	v_mfma_f32_16x16x32_bf16 v[16:19], v[184:187], v[208:211], v[16:19]
	v_mfma_f32_16x16x32_bf16 v[4:7], v[168:171], v[216:219], v[4:7]
	v_mfma_f32_16x16x32_bf16 v[0:3], v[184:187], v[216:219], v[0:3]
	s_barrier
	s_add_i32 s51, s51, 2
	s_add_u32 s24, s24, 0x100
	s_addc_u32 s25, s25, 0
	s_add_u32 s49, s49, 0x100
	s_addc_u32 s50, s50, 0
	s_cmp_gt_u32 s51, 29
	s_cbranch_scc0 .LBB0_585
	s_and_b64 vcc, exec, s[6:7]
	s_cbranch_vccz .LBB0_588
	s_barrier

; #define PG8_STAGE(bufoff, gbase, voff) do { _Pragma("unroll") for (int _i = 0; _i < 2; ++_i) \
;         __builtin_amdgcn_global_load_lds((const unsigned*)((const char*)(gbase) + (voff)[_i]), (PG8_LAS unsigned*)(lds + (bufoff) + ldsw + _i * 8192), 16, 0, 0); } while (0)
; #define PG8_LDA(dst, b, h) do { _Pragma("unroll") for (int m = 0; m < 4; ++m) _Pragma("unroll") for (int k = 0; k < 2; ++k) dst[m][k] = *(const PG8_LAS bf16x8*)(lds + PG8_SA(b, h) + aoff + m * 2048 + k * 1024); } while (0)
; #define PG8_LDB(dst, b, h) do { _Pragma("unroll") for (int n = 0; n < 2; ++n) _Pragma("unroll") for (int k = 0; k < 2; ++k) dst[n][k] = *(const PG8_LAS bf16x8*)(lds + PG8_SB(b, h) + boff + n * 2048 + k * 1024); } while (0)
; #define PG8_MMA(ai, bj, At, Bt) do { __builtin_amdgcn_s_setprio(1); _Pragma("unroll") for (int m = 0; m < 4; ++m) _Pragma("unroll") for (int n = 0; n < 2; ++n) _Pragma("unroll") for (int k = 0; k < 2; ++k) \
;         acc[ai][bj][m][n] = __builtin_amdgcn_mfma_f32_16x16x32_bf16(Bt[n][k], At[m][k], acc[ai][bj][m][n], 0, 0, 0); __builtin_amdgcn_s_setprio(0); } while (0)
; #define PG8_WAIT_V(n) asm volatile("s_waitcnt vmcnt(" #n ")" ::: "memory")
; #define PG8_WAIT_L(n) asm volatile("s_waitcnt lgkmcnt(" #n ")" ::: "memory")
; #define PG8_BAR __builtin_amdgcn_s_barrier()
; #define PG8_SCHED __builtin_amdgcn_sched_barrier(0)
; template <class Epi, class Sched, bool ALIGN_EPI = false, bool SP2 = false>
; __device__ __forceinline__ void gemm_phase(PG8_LAS unsigned char* lds, const Gemm g, const Sched& S, const Epi& E) {
;     ...
;             PG8_LDB(B0, 0, 0); PG8_LDB(B1, 0, 1); PG8_SCHED; PG8_LDA(At, 0, 0); PG8_STAGE(PG8_SA(1, 1), a1 + hstep, voffA);
;             PG8_WAIT_V(8); PG8_WAIT_L(0); PG8_BAR; PG8_MMA(0, 0, At, B0); PG8_MMA(0, 1, At, B1); PG8_BAR; PG8_SCHED;
;             PG8_LDA(At, 0, 1); PG8_STAGE(PG8_SB(0, 0), b2, voffB); PG8_STAGE(PG8_SB(0, 1), b2 + hstep, voffB); PG8_STAGE(PG8_SA(0, 0), a2, voffA);
;             PG8_WAIT_V(8); PG8_WAIT_L(0); PG8_BAR; PG8_MMA(1, 0, At, B0); PG8_MMA(1, 1, At, B1); PG8_BAR; PG8_SCHED;
.LBB0_837:
	ds_read_b128 v[146:149], v158
	ds_read_b128 v[150:153], v158 offset:1024
	ds_read_b128 v[162:165], v158 offset:2048
	ds_read_b128 v[166:169], v158 offset:3072
	ds_read_b128 v[180:183], v159
	ds_read_b128 v[184:187], v159 offset:1024
	ds_read_b128 v[188:191], v159 offset:2048
	ds_read_b128 v[192:195], v159 offset:3072
	s_add_u32 s22, s20, 0xfff80080
	s_addc_u32 s23, s21, -1
	s_cmp_eq_u32 s50, 28
	s_cselect_b32 s25, s11, s23
	s_cselect_b32 s24, s46, s22
	s_cselect_b32 s23, s7, s49
	s_cselect_b32 s22, s47, s48
	v_lshl_add_u64 v[170:171], s[20:21], 0, v[138:139]
	s_add_i32 m0, s30, 0xc000
	ds_read_b128 v[196:199], v160
	ds_read_b128 v[200:203], v160 offset:1024
	ds_read_b128 v[204:207], v160 offset:2048
	ds_read_b128 v[208:211], v160 offset:3072
	ds_read_b128 v[212:215], v160 offset:4096
	ds_read_b128 v[216:219], v160 offset:5120
	ds_read_b128 v[220:223], v160 offset:6144
	ds_read_b128 v[224:227], v160 offset:7168
	global_load_lds_dwordx4 v[170:171], off
	v_lshl_add_u64 v[170:171], s[20:21], 0, v[140:141]
	s_add_i32 m0, s30, 0xe000
	s_nop 0
	global_load_lds_dwordx4 v[170:171], off
	s_waitcnt vmcnt(8)
	s_waitcnt lgkmcnt(0)
	v_mfma_f32_16x16x32_bf16 v[124:127], v[146:149], v[196:199], v[124:127]
	v_mfma_f32_16x16x32_bf16 v[116:119], v[162:165], v[196:199], v[116:119]
	s_barrier
	s_waitcnt lgkmcnt(0)
	v_mfma_f32_16x16x32_bf16 v[108:111], v[146:149], v[204:207], v[108:111]
	v_mfma_f32_16x16x32_bf16 v[100:103], v[162:165], v[204:207], v[100:103]
	v_mfma_f32_16x16x32_bf16 v[92:95], v[146:149], v[212:215], v[92:95]
	v_mfma_f32_16x16x32_bf16 v[84:87], v[162:165], v[212:215], v[84:87]
	v_mfma_f32_16x16x32_bf16 v[76:79], v[146:149], v[220:223], v[76:79]
	v_mfma_f32_16x16x32_bf16 v[68:71], v[162:165], v[220:223], v[68:71]
	v_mfma_f32_16x16x32_bf16 v[124:127], v[150:153], v[200:203], v[124:127]
	v_mfma_f32_16x16x32_bf16 v[116:119], v[166:169], v[200:203], v[116:119]
	v_mfma_f32_16x16x32_bf16 v[108:111], v[150:153], v[208:211], v[108:111]
	v_mfma_f32_16x16x32_bf16 v[100:103], v[166:169], v[208:211], v[100:103]
	v_mfma_f32_16x16x32_bf16 v[92:95], v[150:153], v[216:219], v[92:95]
	v_mfma_f32_16x16x32_bf16 v[84:87], v[166:169], v[216:219], v[84:87]
	v_mfma_f32_16x16x32_bf16 v[76:79], v[150:153], v[224:227], v[76:79]
	v_mfma_f32_16x16x32_bf16 v[68:71], v[166:169], v[224:227], v[68:71]
	v_mfma_f32_16x16x32_bf16 v[120:123], v[180:183], v[196:199], v[120:123]
	v_mfma_f32_16x16x32_bf16 v[112:115], v[188:191], v[196:199], v[112:115]
	v_mfma_f32_16x16x32_bf16 v[104:107], v[180:183], v[204:207], v[104:107]
	v_mfma_f32_16x16x32_bf16 v[96:99], v[188:191], v[204:207], v[96:99]
	v_mfma_f32_16x16x32_bf16 v[88:91], v[180:183], v[212:215], v[88:91]
	v_mfma_f32_16x16x32_bf16 v[80:83], v[188:191], v[212:215], v[80:83]
	v_mfma_f32_16x16x32_bf16 v[72:75], v[180:183], v[220:223], v[72:75]
	v_mfma_f32_16x16x32_bf16 v[64:67], v[188:191], v[220:223], v[64:67]
	v_mfma_f32_16x16x32_bf16 v[120:123], v[184:187], v[200:203], v[120:123]
	v_mfma_f32_16x16x32_bf16 v[112:115], v[192:195], v[200:203], v[112:115]
	v_mfma_f32_16x16x32_bf16 v[104:107], v[184:187], v[208:211], v[104:107]
	v_mfma_f32_16x16x32_bf16 v[96:99], v[192:195], v[208:211], v[96:99]
	v_mfma_f32_16x16x32_bf16 v[88:91], v[184:187], v[216:219], v[88:91]
	v_mfma_f32_16x16x32_bf16 v[80:83], v[192:195], v[216:219], v[80:83]
	v_mfma_f32_16x16x32_bf16 v[72:75], v[184:187], v[224:227], v[72:75]
	v_mfma_f32_16x16x32_bf16 v[64:67], v[192:195], v[224:227], v[64:67]
	s_barrier
	s_add_i32 s51, s37, s26
	v_lshl_add_u64 v[170:171], s[22:23], 0, v[134:135]
	s_mov_b32 m0, s51
	ds_read_b128 v[196:199], v160 offset:16384
	ds_read_b128 v[200:203], v160 offset:17408
	ds_read_b128 v[204:207], v160 offset:18432
	ds_read_b128 v[208:211], v160 offset:19456
	ds_read_b128 v[212:215], v160 offset:20480
	ds_read_b128 v[216:219], v160 offset:21504
	ds_read_b128 v[220:223], v160 offset:22528
	ds_read_b128 v[224:227], v160 offset:23552
	global_load_lds_dwordx4 v[170:171], off
	s_add_i32 m0, s51, 0x2000
	s_add_u32 s52, s22, 0x80000
	v_lshl_add_u64 v[228:229], s[22:23], 0, v[130:131]
	s_addc_u32 s53, s23, 0
	s_add_i32 s51, s40, s26
	global_load_lds_dwordx4 v[228:229], off
	v_lshl_add_u64 v[230:231], s[52:53], 0, v[134:135]
	s_mov_b32 m0, s51
	v_lshl_add_u64 v[232:233], s[24:25], 0, v[132:133]
	global_load_lds_dwordx4 v[230:231], off
	v_lshl_add_u64 v[230:231], s[52:53], 0, v[130:131]
	s_add_i32 m0, s51, 0x2000
	s_nop 0
	global_load_lds_dwordx4 v[230:231], off
	v_lshl_add_u64 v[230:231], s[24:25], 0, v[136:137]
	s_mov_b32 m0, s30
	s_nop 0
	global_load_lds_dwordx4 v[230:231], off
	s_mov_b32 m0, s31
	s_nop 0
	global_load_lds_dwordx4 v[232:233], off
	s_waitcnt vmcnt(8)
	s_waitcnt lgkmcnt(0)
	v_mfma_f32_16x16x32_bf16 v[60:63], v[146:149], v[196:199], v[60:63]
	v_mfma_f32_16x16x32_bf16 v[52:55], v[162:165], v[196:199], v[52:55]
	s_barrier
; #define PG8_STAGE(bufoff, gbase, voff) do { _Pragma("unroll") for (int _i = 0; _i < 2; ++_i) \
;         __builtin_amdgcn_global_load_lds((const unsigned*)((const char*)(gbase) + (voff)[_i]), (PG8_LAS unsigned*)(lds + (bufoff) + ldsw + _i * 8192), 16, 0, 0); } while (0)
; #define PG8_LDA(dst, b, h) do { _Pragma("unroll") for (int m = 0; m < 4; ++m) _Pragma("unroll") for (int k = 0; k < 2; ++k) dst[m][k] = *(const PG8_LAS bf16x8*)(lds + PG8_SA(b, h) + aoff + m * 2048 + k * 1024); } while (0)
; #define PG8_LDB(dst, b, h) do { _Pragma("unroll") for (int n = 0; n < 2; ++n) _Pragma("unroll") for (int k = 0; k < 2; ++k) dst[n][k] = *(const PG8_LAS bf16x8*)(lds + PG8_SB(b, h) + boff + n * 2048 + k * 1024); } while (0)
; #define PG8_MMA(ai, bj, At, Bt) do { __builtin_amdgcn_s_setprio(1); _Pragma("unroll") for (int m = 0; m < 4; ++m) _Pragma("unroll") for (int n = 0; n < 2; ++n) _Pragma("unroll") for (int k = 0; k < 2; ++k) \
;         acc[ai][bj][m][n] = __builtin_amdgcn_mfma_f32_16x16x32_bf16(Bt[n][k], At[m][k], acc[ai][bj][m][n], 0, 0, 0); __builtin_amdgcn_s_setprio(0); } while (0)
; #define PG8_WAIT_V(n) asm volatile("s_waitcnt vmcnt(" #n ")" ::: "memory")
; #define PG8_WAIT_L(n) asm volatile("s_waitcnt lgkmcnt(" #n ")" ::: "memory")
; #define PG8_BAR __builtin_amdgcn_s_barrier()
; #define PG8_SCHED __builtin_amdgcn_sched_barrier(0)
; template <class Epi, class Sched, bool ALIGN_EPI = false, bool SP2 = false>
; __device__ __forceinline__ void gemm_phase(PG8_LAS unsigned char* lds, const Gemm g, const Sched& S, const Epi& E) {
;     ...
;             PG8_WAIT_V(8); PG8_WAIT_L(0); PG8_BAR; PG8_MMA(1, 0, At, B0); PG8_MMA(1, 1, At, B1); PG8_BAR; PG8_SCHED;
;             PG8_LDB(B0, 1, 0); PG8_LDB(B1, 1, 1); PG8_SCHED; PG8_LDA(At, 1, 0); PG8_STAGE(PG8_SA(0, 1), a2 + hstep, voffA);
;             PG8_WAIT_V(8); PG8_WAIT_L(0); PG8_BAR; PG8_MMA(0, 0, At, B0); PG8_MMA(0, 1, At, B1); PG8_BAR; PG8_SCHED;
	s_waitcnt lgkmcnt(0)
	v_mfma_f32_16x16x32_bf16 v[44:47], v[146:149], v[204:207], v[44:47]
	v_mfma_f32_16x16x32_bf16 v[36:39], v[162:165], v[204:207], v[36:39]
	v_mfma_f32_16x16x32_bf16 v[28:31], v[146:149], v[212:215], v[28:31]
	v_mfma_f32_16x16x32_bf16 v[20:23], v[162:165], v[212:215], v[20:23]
	v_mfma_f32_16x16x32_bf16 v[12:15], v[146:149], v[220:223], v[12:15]
	v_mfma_f32_16x16x32_bf16 v[4:7], v[162:165], v[220:223], v[4:7]
	v_mfma_f32_16x16x32_bf16 v[60:63], v[150:153], v[200:203], v[60:63]
	v_mfma_f32_16x16x32_bf16 v[52:55], v[166:169], v[200:203], v[52:55]
	v_mfma_f32_16x16x32_bf16 v[44:47], v[150:153], v[208:211], v[44:47]
	v_mfma_f32_16x16x32_bf16 v[36:39], v[166:169], v[208:211], v[36:39]
	v_mfma_f32_16x16x32_bf16 v[28:31], v[150:153], v[216:219], v[28:31]
	v_mfma_f32_16x16x32_bf16 v[20:23], v[166:169], v[216:219], v[20:23]
	v_mfma_f32_16x16x32_bf16 v[12:15], v[150:153], v[224:227], v[12:15]
	v_mfma_f32_16x16x32_bf16 v[4:7], v[166:169], v[224:227], v[4:7]
	v_mfma_f32_16x16x32_bf16 v[56:59], v[180:183], v[196:199], v[56:59]
	v_mfma_f32_16x16x32_bf16 v[48:51], v[188:191], v[196:199], v[48:51]
	v_mfma_f32_16x16x32_bf16 v[40:43], v[180:183], v[204:207], v[40:43]
	v_mfma_f32_16x16x32_bf16 v[32:35], v[188:191], v[204:207], v[32:35]
	v_mfma_f32_16x16x32_bf16 v[24:27], v[180:183], v[212:215], v[24:27]
	v_mfma_f32_16x16x32_bf16 v[16:19], v[188:191], v[212:215], v[16:19]
	v_mfma_f32_16x16x32_bf16 v[8:11], v[180:183], v[220:223], v[8:11]
	v_mfma_f32_16x16x32_bf16 v[0:3], v[188:191], v[220:223], v[0:3]
	v_mfma_f32_16x16x32_bf16 v[56:59], v[184:187], v[200:203], v[56:59]
	v_mfma_f32_16x16x32_bf16 v[48:51], v[192:195], v[200:203], v[48:51]
	v_mfma_f32_16x16x32_bf16 v[40:43], v[184:187], v[208:211], v[40:43]
	v_mfma_f32_16x16x32_bf16 v[32:35], v[192:195], v[208:211], v[32:35]
	v_mfma_f32_16x16x32_bf16 v[24:27], v[184:187], v[216:219], v[24:27]
	v_mfma_f32_16x16x32_bf16 v[16:19], v[192:195], v[216:219], v[16:19]
	v_mfma_f32_16x16x32_bf16 v[8:11], v[184:187], v[224:227], v[8:11]
	v_mfma_f32_16x16x32_bf16 v[0:3], v[192:195], v[224:227], v[0:3]
	s_barrier
	s_add_i32 s51, 0, 0x18000
	v_add_u32_e32 v161, s51, v155
	s_add_i32 s52, 0, 0x1c000
	ds_read_b128 v[146:149], v161
	ds_read_b128 v[150:153], v161 offset:1024
	ds_read_b128 v[162:165], v161 offset:2048
	ds_read_b128 v[166:169], v161 offset:3072
	v_add_u32_e32 v161, s52, v155
	ds_read_b128 v[180:183], v161
	ds_read_b128 v[184:187], v161 offset:1024
	ds_read_b128 v[188:191], v161 offset:2048
	ds_read_b128 v[192:195], v161 offset:3072
	s_add_u32 s24, s24, 0x80000
	s_addc_u32 s25, s25, 0
	s_mov_b32 m0, s33
	v_lshl_add_u64 v[234:235], s[24:25], 0, v[136:137]
	ds_read_b128 v[196:199], v160 offset:32768
	ds_read_b128 v[200:203], v160 offset:33792
	ds_read_b128 v[204:207], v160 offset:34816
	ds_read_b128 v[208:211], v160 offset:35840
	ds_read_b128 v[212:215], v160 offset:36864
	ds_read_b128 v[216:219], v160 offset:37888
	ds_read_b128 v[220:223], v160 offset:38912
	ds_read_b128 v[224:227], v160 offset:39936
	global_load_lds_dwordx4 v[234:235], off
	v_lshl_add_u64 v[234:235], s[24:25], 0, v[132:133]
	s_mov_b32 m0, s34
	s_nop 0
	global_load_lds_dwordx4 v[234:235], off
	s_waitcnt vmcnt(8)
	s_waitcnt lgkmcnt(0)
	v_mfma_f32_16x16x32_bf16 v[124:127], v[146:149], v[196:199], v[124:127]
	v_mfma_f32_16x16x32_bf16 v[116:119], v[162:165], v[196:199], v[116:119]
	s_barrier
	s_waitcnt lgkmcnt(0)
	v_mfma_f32_16x16x32_bf16 v[108:111], v[146:149], v[204:207], v[108:111]
	v_mfma_f32_16x16x32_bf16 v[100:103], v[162:165], v[204:207], v[100:103]
	v_mfma_f32_16x16x32_bf16 v[92:95], v[146:149], v[212:215], v[92:95]
	v_mfma_f32_16x16x32_bf16 v[84:87], v[162:165], v[212:215], v[84:87]
	v_mfma_f32_16x16x32_bf16 v[76:79], v[146:149], v[220:223], v[76:79]
	v_mfma_f32_16x16x32_bf16 v[68:71], v[162:165], v[220:223], v[68:71]
	v_mfma_f32_16x16x32_bf16 v[124:127], v[150:153], v[200:203], v[124:127]
	v_mfma_f32_16x16x32_bf16 v[116:119], v[166:169], v[200:203], v[116:119]
	v_mfma_f32_16x16x32_bf16 v[108:111], v[150:153], v[208:211], v[108:111]
	v_mfma_f32_16x16x32_bf16 v[100:103], v[166:169], v[208:211], v[100:103]
	v_mfma_f32_16x16x32_bf16 v[92:95], v[150:153], v[216:219], v[92:95]
	v_mfma_f32_16x16x32_bf16 v[84:87], v[166:169], v[216:219], v[84:87]
	v_mfma_f32_16x16x32_bf16 v[76:79], v[150:153], v[224:227], v[76:79]
	v_mfma_f32_16x16x32_bf16 v[68:71], v[166:169], v[224:227], v[68:71]
	v_mfma_f32_16x16x32_bf16 v[120:123], v[180:183], v[196:199], v[120:123]
	v_mfma_f32_16x16x32_bf16 v[112:115], v[188:191], v[196:199], v[112:115]
	v_mfma_f32_16x16x32_bf16 v[104:107], v[180:183], v[204:207], v[104:107]
	v_mfma_f32_16x16x32_bf16 v[96:99], v[188:191], v[204:207], v[96:99]
	v_mfma_f32_16x16x32_bf16 v[88:91], v[180:183], v[212:215], v[88:91]
	v_mfma_f32_16x16x32_bf16 v[80:83], v[188:191], v[212:215], v[80:83]
	v_mfma_f32_16x16x32_bf16 v[72:75], v[180:183], v[220:223], v[72:75]
	v_mfma_f32_16x16x32_bf16 v[64:67], v[188:191], v[220:223], v[64:67]
	v_mfma_f32_16x16x32_bf16 v[120:123], v[184:187], v[200:203], v[120:123]
	v_mfma_f32_16x16x32_bf16 v[112:115], v[192:195], v[200:203], v[112:115]
	v_mfma_f32_16x16x32_bf16 v[104:107], v[184:187], v[208:211], v[104:107]
	v_mfma_f32_16x16x32_bf16 v[96:99], v[192:195], v[208:211], v[96:99]
	v_mfma_f32_16x16x32_bf16 v[88:91], v[184:187], v[216:219], v[88:91]
	v_mfma_f32_16x16x32_bf16 v[80:83], v[192:195], v[216:219], v[80:83]
	v_mfma_f32_16x16x32_bf16 v[72:75], v[184:187], v[224:227], v[72:75]
	v_mfma_f32_16x16x32_bf16 v[64:67], v[192:195], v[224:227], v[64:67]
	s_barrier
; #define PG8_STAGE(bufoff, gbase, voff) do { _Pragma("unroll") for (int _i = 0; _i < 2; ++_i) \
;         __builtin_amdgcn_global_load_lds((const unsigned*)((const char*)(gbase) + (voff)[_i]), (PG8_LAS unsigned*)(lds + (bufoff) + ldsw + _i * 8192), 16, 0, 0); } while (0)
; #define PG8_LDA(dst, b, h) do { _Pragma("unroll") for (int m = 0; m < 4; ++m) _Pragma("unroll") for (int k = 0; k < 2; ++k) dst[m][k] = *(const PG8_LAS bf16x8*)(lds + PG8_SA(b, h) + aoff + m * 2048 + k * 1024); } while (0)
; #define PG8_MMA(ai, bj, At, Bt) do { __builtin_amdgcn_s_setprio(1); _Pragma("unroll") for (int m = 0; m < 4; ++m) _Pragma("unroll") for (int n = 0; n < 2; ++n) _Pragma("unroll") for (int k = 0; k < 2; ++k) \
;         acc[ai][bj][m][n] = __builtin_amdgcn_mfma_f32_16x16x32_bf16(Bt[n][k], At[m][k], acc[ai][bj][m][n], 0, 0, 0); __builtin_amdgcn_s_setprio(0); } while (0)
; #define PG8_WAIT_V(n) asm volatile("s_waitcnt vmcnt(" #n ")" ::: "memory")
; #define PG8_WAIT_L(n) asm volatile("s_waitcnt lgkmcnt(" #n ")" ::: "memory")
; #define PG8_BAR __builtin_amdgcn_s_barrier()
; #define PG8_SCHED __builtin_amdgcn_sched_barrier(0)
; template <class Epi, class Sched, bool ALIGN_EPI = false, bool SP2 = false>
; __device__ __forceinline__ void gemm_phase(PG8_LAS unsigned char* lds, const Gemm g, const Sched& S, const Epi& E) {
;     ...
;             PG8_LDA(At, 1, 1); PG8_STAGE(PG8_SB(1, 0), b3, voffB); PG8_STAGE(PG8_SB(1, 1), b3 + hstep, voffB); PG8_STAGE(PG8_SA(1, 0), a3, voffA);
;             PG8_WAIT_V(8); PG8_WAIT_L(0); PG8_BAR; PG8_MMA(1, 0, At, B0); PG8_MMA(1, 1, At, B1); PG8_BAR; PG8_SCHED;
;     ...
;         if constexpr (ALIGN_EPI) { if (wr == 0) PG8_BAR; }
	s_add_i32 s24, s51, s26
	v_lshl_add_u64 v[170:171], v[170:171], 0, s[2:3]
	s_mov_b32 m0, s24
	ds_read_b128 v[196:199], v160 offset:49152
	ds_read_b128 v[200:203], v160 offset:50176
	ds_read_b128 v[204:207], v160 offset:51200
	ds_read_b128 v[208:211], v160 offset:52224
	ds_read_b128 v[212:215], v160 offset:53248
	ds_read_b128 v[216:219], v160 offset:54272
	ds_read_b128 v[220:223], v160 offset:55296
	ds_read_b128 v[224:227], v160 offset:56320
	global_load_lds_dwordx4 v[170:171], off
	s_add_i32 m0, s24, 0x2000
	s_add_u32 s22, s22, 0x80080
	v_lshl_add_u64 v[170:171], v[228:229], 0, s[2:3]
	s_addc_u32 s23, s23, 0
	s_add_i32 s24, s52, s26
	global_load_lds_dwordx4 v[170:171], off
	v_lshl_add_u64 v[170:171], s[22:23], 0, v[134:135]
	s_mov_b32 m0, s24
	s_nop 0
	global_load_lds_dwordx4 v[170:171], off
	v_lshl_add_u64 v[170:171], s[22:23], 0, v[130:131]
	s_add_i32 m0, s24, 0x2000
	s_nop 0
	global_load_lds_dwordx4 v[170:171], off
	v_lshl_add_u64 v[170:171], v[230:231], 0, s[2:3]
	s_mov_b32 m0, s35
	s_nop 0
	global_load_lds_dwordx4 v[170:171], off
	v_lshl_add_u64 v[170:171], v[232:233], 0, s[2:3]
	s_mov_b32 m0, s36
	s_nop 0
	global_load_lds_dwordx4 v[170:171], off
	s_waitcnt vmcnt(8)
	s_waitcnt lgkmcnt(0)
	v_mfma_f32_16x16x32_bf16 v[60:63], v[146:149], v[196:199], v[60:63]
	v_mfma_f32_16x16x32_bf16 v[52:55], v[162:165], v[196:199], v[52:55]
	s_barrier
	s_waitcnt lgkmcnt(0)
	v_mfma_f32_16x16x32_bf16 v[44:47], v[146:149], v[204:207], v[44:47]
	v_mfma_f32_16x16x32_bf16 v[36:39], v[162:165], v[204:207], v[36:39]
	v_mfma_f32_16x16x32_bf16 v[28:31], v[146:149], v[212:215], v[28:31]
	v_mfma_f32_16x16x32_bf16 v[20:23], v[162:165], v[212:215], v[20:23]
	v_mfma_f32_16x16x32_bf16 v[12:15], v[146:149], v[220:223], v[12:15]
	v_mfma_f32_16x16x32_bf16 v[4:7], v[162:165], v[220:223], v[4:7]
	v_mfma_f32_16x16x32_bf16 v[60:63], v[150:153], v[200:203], v[60:63]
	v_mfma_f32_16x16x32_bf16 v[52:55], v[166:169], v[200:203], v[52:55]
	v_mfma_f32_16x16x32_bf16 v[44:47], v[150:153], v[208:211], v[44:47]
	v_mfma_f32_16x16x32_bf16 v[36:39], v[166:169], v[208:211], v[36:39]
	v_mfma_f32_16x16x32_bf16 v[28:31], v[150:153], v[216:219], v[28:31]
	v_mfma_f32_16x16x32_bf16 v[20:23], v[166:169], v[216:219], v[20:23]
	v_mfma_f32_16x16x32_bf16 v[12:15], v[150:153], v[224:227], v[12:15]
	v_mfma_f32_16x16x32_bf16 v[4:7], v[166:169], v[224:227], v[4:7]
	v_mfma_f32_16x16x32_bf16 v[56:59], v[180:183], v[196:199], v[56:59]
	v_mfma_f32_16x16x32_bf16 v[48:51], v[188:191], v[196:199], v[48:51]
	v_mfma_f32_16x16x32_bf16 v[40:43], v[180:183], v[204:207], v[40:43]
	v_mfma_f32_16x16x32_bf16 v[32:35], v[188:191], v[204:207], v[32:35]
	v_mfma_f32_16x16x32_bf16 v[24:27], v[180:183], v[212:215], v[24:27]
	v_mfma_f32_16x16x32_bf16 v[16:19], v[188:191], v[212:215], v[16:19]
	v_mfma_f32_16x16x32_bf16 v[8:11], v[180:183], v[220:223], v[8:11]
	v_mfma_f32_16x16x32_bf16 v[0:3], v[188:191], v[220:223], v[0:3]
	v_mfma_f32_16x16x32_bf16 v[56:59], v[184:187], v[200:203], v[56:59]
	v_mfma_f32_16x16x32_bf16 v[48:51], v[192:195], v[200:203], v[48:51]
	v_mfma_f32_16x16x32_bf16 v[40:43], v[184:187], v[208:211], v[40:43]
	v_mfma_f32_16x16x32_bf16 v[32:35], v[192:195], v[208:211], v[32:35]
	v_mfma_f32_16x16x32_bf16 v[24:27], v[184:187], v[216:219], v[24:27]
	v_mfma_f32_16x16x32_bf16 v[16:19], v[192:195], v[216:219], v[16:19]
	v_mfma_f32_16x16x32_bf16 v[8:11], v[184:187], v[224:227], v[8:11]
	v_mfma_f32_16x16x32_bf16 v[0:3], v[192:195], v[224:227], v[0:3]
	s_barrier
	s_add_i32 s50, s50, 2
	s_add_u32 s20, s20, 0x100
	s_addc_u32 s21, s21, 0
	s_add_u32 s48, s48, 0x100
	s_addc_u32 s49, s49, 0
	s_cmp_gt_u32 s50, 29
	s_cbranch_scc0 .LBB0_837
	s_and_b64 vcc, exec, s[4:5]
	s_cbranch_vccz .LBB0_840
	s_barrier

; #define PG8_STAGE(bufoff, gbase, voff) do { _Pragma("unroll") for (int _i = 0; _i < 2; ++_i) \
;         __builtin_amdgcn_global_load_lds((const unsigned*)((const char*)(gbase) + (voff)[_i]), (PG8_LAS unsigned*)(lds + (bufoff) + ldsw + _i * 8192), 16, 0, 0); } while (0)
; #define PG8_LDA(dst, b, h) do { _Pragma("unroll") for (int m = 0; m < 4; ++m) _Pragma("unroll") for (int k = 0; k < 2; ++k) dst[m][k] = *(const PG8_LAS bf16x8*)(lds + PG8_SA(b, h) + aoff + m * 2048 + k * 1024); } while (0)
; #define PG8_LDB(dst, b, h) do { _Pragma("unroll") for (int n = 0; n < 2; ++n) _Pragma("unroll") for (int k = 0; k < 2; ++k) dst[n][k] = *(const PG8_LAS bf16x8*)(lds + PG8_SB(b, h) + boff + n * 2048 + k * 1024); } while (0)
; #define PG8_MMA(ai, bj, At, Bt) do { __builtin_amdgcn_s_setprio(1); _Pragma("unroll") for (int m = 0; m < 4; ++m) _Pragma("unroll") for (int n = 0; n < 2; ++n) _Pragma("unroll") for (int k = 0; k < 2; ++k) \
;         acc[ai][bj][m][n] = __builtin_amdgcn_mfma_f32_16x16x32_bf16(Bt[n][k], At[m][k], acc[ai][bj][m][n], 0, 0, 0); __builtin_amdgcn_s_setprio(0); } while (0)
; #define PG8_WAIT_V(n) asm volatile("s_waitcnt vmcnt(" #n ")" ::: "memory")
; #define PG8_WAIT_L(n) asm volatile("s_waitcnt lgkmcnt(" #n ")" ::: "memory")
; #define PG8_BAR __builtin_amdgcn_s_barrier()
; #define PG8_SCHED __builtin_amdgcn_sched_barrier(0)
; template <class Epi, class Sched, bool ALIGN_EPI = false, bool SP2 = false>
; __device__ __forceinline__ void gemm_phase(PG8_LAS unsigned char* lds, const Gemm g, const Sched& S, const Epi& E) {
;     ...
;             PG8_LDB(B0, 0, 0); PG8_LDB(B1, 0, 1); PG8_SCHED; PG8_LDA(At, 0, 0); PG8_STAGE(PG8_SA(1, 1), a1 + hstep, voffA);
;             PG8_WAIT_V(8); PG8_WAIT_L(0); PG8_BAR; PG8_MMA(0, 0, At, B0); PG8_MMA(0, 1, At, B1); PG8_BAR; PG8_SCHED;
;             PG8_LDA(At, 0, 1); PG8_STAGE(PG8_SB(0, 0), b2, voffB); PG8_STAGE(PG8_SB(0, 1), b2 + hstep, voffB); PG8_STAGE(PG8_SA(0, 0), a2, voffA);
;             PG8_WAIT_V(8); PG8_WAIT_L(0); PG8_BAR; PG8_MMA(1, 0, At, B0); PG8_MMA(1, 1, At, B1); PG8_BAR; PG8_SCHED;
.LBB0_1080:
	ds_read_b128 v[142:145], v151
	ds_read_b128 v[154:157], v151 offset:1024
	ds_read_b128 v[158:161], v151 offset:2048
	ds_read_b128 v[162:165], v151 offset:3072
	ds_read_b128 v[166:169], v152
	ds_read_b128 v[180:183], v152 offset:1024
	ds_read_b128 v[184:187], v152 offset:2048
	ds_read_b128 v[188:191], v152 offset:3072
	s_add_u32 s20, s18, 0x100
	s_addc_u32 s21, s19, 0
	s_cmpk_eq_i32 s49, 0x54
	s_cselect_b32 s25, s13, s21
	s_cselect_b32 s24, s12, s20
	s_cselect_b32 s23, s17, s48
	s_cselect_b32 s22, s16, s47
	v_lshl_add_u64 v[146:147], s[18:19], 0, v[134:135]
	s_add_i32 m0, s29, 0xc000
	ds_read_b128 v[192:195], v153
	ds_read_b128 v[196:199], v153 offset:1024
	ds_read_b128 v[200:203], v153 offset:2048
	ds_read_b128 v[204:207], v153 offset:3072
	ds_read_b128 v[208:211], v153 offset:4096
	ds_read_b128 v[212:215], v153 offset:5120
	ds_read_b128 v[216:219], v153 offset:6144
	ds_read_b128 v[220:223], v153 offset:7168
	global_load_lds_dwordx4 v[146:147], off
	v_lshl_add_u64 v[146:147], s[18:19], 0, v[136:137]
	s_add_i32 m0, s29, 0xe000
	s_nop 0
	global_load_lds_dwordx4 v[146:147], off
	s_waitcnt vmcnt(8)
	s_waitcnt lgkmcnt(0)
	v_mfma_f32_16x16x32_bf16 v[124:127], v[142:145], v[192:195], v[124:127]
	v_mfma_f32_16x16x32_bf16 v[120:123], v[158:161], v[192:195], v[120:123]
	s_barrier
	s_waitcnt lgkmcnt(0)
	v_mfma_f32_16x16x32_bf16 v[108:111], v[142:145], v[200:203], v[108:111]
	v_mfma_f32_16x16x32_bf16 v[104:107], v[158:161], v[200:203], v[104:107]
	v_mfma_f32_16x16x32_bf16 v[92:95], v[142:145], v[208:211], v[92:95]
	v_mfma_f32_16x16x32_bf16 v[88:91], v[158:161], v[208:211], v[88:91]
	v_mfma_f32_16x16x32_bf16 v[76:79], v[142:145], v[216:219], v[76:79]
	v_mfma_f32_16x16x32_bf16 v[72:75], v[158:161], v[216:219], v[72:75]
	v_mfma_f32_16x16x32_bf16 v[124:127], v[154:157], v[196:199], v[124:127]
	v_mfma_f32_16x16x32_bf16 v[120:123], v[162:165], v[196:199], v[120:123]
	v_mfma_f32_16x16x32_bf16 v[108:111], v[154:157], v[204:207], v[108:111]
	v_mfma_f32_16x16x32_bf16 v[104:107], v[162:165], v[204:207], v[104:107]
	v_mfma_f32_16x16x32_bf16 v[92:95], v[154:157], v[212:215], v[92:95]
	v_mfma_f32_16x16x32_bf16 v[88:91], v[162:165], v[212:215], v[88:91]
	v_mfma_f32_16x16x32_bf16 v[76:79], v[154:157], v[220:223], v[76:79]
	v_mfma_f32_16x16x32_bf16 v[72:75], v[162:165], v[220:223], v[72:75]
	v_mfma_f32_16x16x32_bf16 v[116:119], v[166:169], v[192:195], v[116:119]
	v_mfma_f32_16x16x32_bf16 v[112:115], v[184:187], v[192:195], v[112:115]
	v_mfma_f32_16x16x32_bf16 v[100:103], v[166:169], v[200:203], v[100:103]
	v_mfma_f32_16x16x32_bf16 v[96:99], v[184:187], v[200:203], v[96:99]
	v_mfma_f32_16x16x32_bf16 v[84:87], v[166:169], v[208:211], v[84:87]
	v_mfma_f32_16x16x32_bf16 v[80:83], v[184:187], v[208:211], v[80:83]
	v_mfma_f32_16x16x32_bf16 v[68:71], v[166:169], v[216:219], v[68:71]
	v_mfma_f32_16x16x32_bf16 v[64:67], v[184:187], v[216:219], v[64:67]
	v_mfma_f32_16x16x32_bf16 v[116:119], v[180:183], v[196:199], v[116:119]
	v_mfma_f32_16x16x32_bf16 v[112:115], v[188:191], v[196:199], v[112:115]
	v_mfma_f32_16x16x32_bf16 v[100:103], v[180:183], v[204:207], v[100:103]
	v_mfma_f32_16x16x32_bf16 v[96:99], v[188:191], v[204:207], v[96:99]
	v_mfma_f32_16x16x32_bf16 v[84:87], v[180:183], v[212:215], v[84:87]
	v_mfma_f32_16x16x32_bf16 v[80:83], v[188:191], v[212:215], v[80:83]
	v_mfma_f32_16x16x32_bf16 v[68:71], v[180:183], v[220:223], v[68:71]
	v_mfma_f32_16x16x32_bf16 v[64:67], v[188:191], v[220:223], v[64:67]
	s_barrier
	s_add_i32 s18, s37, s28
	v_lshl_add_u64 v[146:147], s[22:23], 0, v[130:131]
	s_mov_b32 m0, s18
	ds_read_b128 v[192:195], v153 offset:16384
	ds_read_b128 v[196:199], v153 offset:17408
	ds_read_b128 v[200:203], v153 offset:18432
	ds_read_b128 v[204:207], v153 offset:19456
	ds_read_b128 v[208:211], v153 offset:20480
	ds_read_b128 v[212:215], v153 offset:21504
	ds_read_b128 v[216:219], v153 offset:22528
	ds_read_b128 v[220:223], v153 offset:23552
	global_load_lds_dwordx4 v[146:147], off
	s_add_i32 m0, s18, 0x2000
	s_add_u32 s18, s22, 0x160000
	v_lshl_add_u64 v[170:171], s[22:23], 0, v[132:133]
	s_addc_u32 s19, s23, 0
	s_add_i32 s50, s40, s28
	global_load_lds_dwordx4 v[170:171], off
	v_lshl_add_u64 v[224:225], s[18:19], 0, v[130:131]
	s_mov_b32 m0, s50
	v_lshl_add_u64 v[226:227], s[24:25], 0, v[132:133]
	global_load_lds_dwordx4 v[224:225], off
	v_lshl_add_u64 v[224:225], s[18:19], 0, v[132:133]
	s_add_i32 m0, s50, 0x2000
	s_nop 0
	global_load_lds_dwordx4 v[224:225], off
	v_lshl_add_u64 v[224:225], s[24:25], 0, v[130:131]
	s_mov_b32 m0, s29
	s_nop 0
	global_load_lds_dwordx4 v[224:225], off
	s_mov_b32 m0, s30
	s_nop 0
	global_load_lds_dwordx4 v[226:227], off
	s_waitcnt vmcnt(8)
	s_waitcnt lgkmcnt(0)
	v_mfma_f32_16x16x32_bf16 v[60:63], v[142:145], v[192:195], v[60:63]
	v_mfma_f32_16x16x32_bf16 v[56:59], v[158:161], v[192:195], v[56:59]
	s_barrier
; #define PG8_STAGE(bufoff, gbase, voff) do { _Pragma("unroll") for (int _i = 0; _i < 2; ++_i) \
;         __builtin_amdgcn_global_load_lds((const unsigned*)((const char*)(gbase) + (voff)[_i]), (PG8_LAS unsigned*)(lds + (bufoff) + ldsw + _i * 8192), 16, 0, 0); } while (0)
; #define PG8_LDA(dst, b, h) do { _Pragma("unroll") for (int m = 0; m < 4; ++m) _Pragma("unroll") for (int k = 0; k < 2; ++k) dst[m][k] = *(const PG8_LAS bf16x8*)(lds + PG8_SA(b, h) + aoff + m * 2048 + k * 1024); } while (0)
; #define PG8_LDB(dst, b, h) do { _Pragma("unroll") for (int n = 0; n < 2; ++n) _Pragma("unroll") for (int k = 0; k < 2; ++k) dst[n][k] = *(const PG8_LAS bf16x8*)(lds + PG8_SB(b, h) + boff + n * 2048 + k * 1024); } while (0)
; #define PG8_MMA(ai, bj, At, Bt) do { __builtin_amdgcn_s_setprio(1); _Pragma("unroll") for (int m = 0; m < 4; ++m) _Pragma("unroll") for (int n = 0; n < 2; ++n) _Pragma("unroll") for (int k = 0; k < 2; ++k) \
;         acc[ai][bj][m][n] = __builtin_amdgcn_mfma_f32_16x16x32_bf16(Bt[n][k], At[m][k], acc[ai][bj][m][n], 0, 0, 0); __builtin_amdgcn_s_setprio(0); } while (0)
; #define PG8_WAIT_V(n) asm volatile("s_waitcnt vmcnt(" #n ")" ::: "memory")
; #define PG8_WAIT_L(n) asm volatile("s_waitcnt lgkmcnt(" #n ")" ::: "memory")
; #define PG8_BAR __builtin_amdgcn_s_barrier()
; #define PG8_SCHED __builtin_amdgcn_sched_barrier(0)
; template <class Epi, class Sched, bool ALIGN_EPI = false, bool SP2 = false>
; __device__ __forceinline__ void gemm_phase(PG8_LAS unsigned char* lds, const Gemm g, const Sched& S, const Epi& E) {
;     ...
;             PG8_WAIT_V(8); PG8_WAIT_L(0); PG8_BAR; PG8_MMA(1, 0, At, B0); PG8_MMA(1, 1, At, B1); PG8_BAR; PG8_SCHED;
;             PG8_LDB(B0, 1, 0); PG8_LDB(B1, 1, 1); PG8_SCHED; PG8_LDA(At, 1, 0); PG8_STAGE(PG8_SA(0, 1), a2 + hstep, voffA);
;             PG8_WAIT_V(8); PG8_WAIT_L(0); PG8_BAR; PG8_MMA(0, 0, At, B0); PG8_MMA(0, 1, At, B1); PG8_BAR; PG8_SCHED;
	s_waitcnt lgkmcnt(0)
	v_mfma_f32_16x16x32_bf16 v[44:47], v[142:145], v[200:203], v[44:47]
	v_mfma_f32_16x16x32_bf16 v[40:43], v[158:161], v[200:203], v[40:43]
	v_mfma_f32_16x16x32_bf16 v[28:31], v[142:145], v[208:211], v[28:31]
	v_mfma_f32_16x16x32_bf16 v[24:27], v[158:161], v[208:211], v[24:27]
	v_mfma_f32_16x16x32_bf16 v[12:15], v[142:145], v[216:219], v[12:15]
	v_mfma_f32_16x16x32_bf16 v[8:11], v[158:161], v[216:219], v[8:11]
	v_mfma_f32_16x16x32_bf16 v[60:63], v[154:157], v[196:199], v[60:63]
	v_mfma_f32_16x16x32_bf16 v[56:59], v[162:165], v[196:199], v[56:59]
	v_mfma_f32_16x16x32_bf16 v[44:47], v[154:157], v[204:207], v[44:47]
	v_mfma_f32_16x16x32_bf16 v[40:43], v[162:165], v[204:207], v[40:43]
	v_mfma_f32_16x16x32_bf16 v[28:31], v[154:157], v[212:215], v[28:31]
	v_mfma_f32_16x16x32_bf16 v[24:27], v[162:165], v[212:215], v[24:27]
	v_mfma_f32_16x16x32_bf16 v[12:15], v[154:157], v[220:223], v[12:15]
	v_mfma_f32_16x16x32_bf16 v[8:11], v[162:165], v[220:223], v[8:11]
	v_mfma_f32_16x16x32_bf16 v[52:55], v[166:169], v[192:195], v[52:55]
	v_mfma_f32_16x16x32_bf16 v[48:51], v[184:187], v[192:195], v[48:51]
	v_mfma_f32_16x16x32_bf16 v[36:39], v[166:169], v[200:203], v[36:39]
	v_mfma_f32_16x16x32_bf16 v[32:35], v[184:187], v[200:203], v[32:35]
	v_mfma_f32_16x16x32_bf16 v[20:23], v[166:169], v[208:211], v[20:23]
	v_mfma_f32_16x16x32_bf16 v[16:19], v[184:187], v[208:211], v[16:19]
	v_mfma_f32_16x16x32_bf16 v[4:7], v[166:169], v[216:219], v[4:7]
	v_mfma_f32_16x16x32_bf16 v[0:3], v[184:187], v[216:219], v[0:3]
	v_mfma_f32_16x16x32_bf16 v[52:55], v[180:183], v[196:199], v[52:55]
	v_mfma_f32_16x16x32_bf16 v[48:51], v[188:191], v[196:199], v[48:51]
	v_mfma_f32_16x16x32_bf16 v[36:39], v[180:183], v[204:207], v[36:39]
	v_mfma_f32_16x16x32_bf16 v[32:35], v[188:191], v[204:207], v[32:35]
	v_mfma_f32_16x16x32_bf16 v[20:23], v[180:183], v[212:215], v[20:23]
	v_mfma_f32_16x16x32_bf16 v[16:19], v[188:191], v[212:215], v[16:19]
	v_mfma_f32_16x16x32_bf16 v[4:7], v[180:183], v[220:223], v[4:7]
	v_mfma_f32_16x16x32_bf16 v[0:3], v[188:191], v[220:223], v[0:3]
	s_barrier
	s_add_i32 s50, 0, 0x18000
	s_add_i32 s51, 0, 0x1c000
	v_add_u32_e32 v162, s50, v149
	v_add_u32_e32 v179, s51, v149
	ds_read_b128 v[142:145], v162
	ds_read_b128 v[154:157], v162 offset:1024
	ds_read_b128 v[158:161], v162 offset:2048
	ds_read_b128 v[162:165], v162 offset:3072
	ds_read_b128 v[166:169], v179
	ds_read_b128 v[180:183], v179 offset:1024
	ds_read_b128 v[184:187], v179 offset:2048
	ds_read_b128 v[188:191], v179 offset:3072
	s_add_u32 s18, s24, 0x160000
	s_addc_u32 s19, s25, 0
	s_mov_b32 m0, s31
	v_lshl_add_u64 v[228:229], s[18:19], 0, v[130:131]
	ds_read_b128 v[192:195], v153 offset:32768
	ds_read_b128 v[196:199], v153 offset:33792
	ds_read_b128 v[200:203], v153 offset:34816
	ds_read_b128 v[204:207], v153 offset:35840
	ds_read_b128 v[208:211], v153 offset:36864
	ds_read_b128 v[212:215], v153 offset:37888
	ds_read_b128 v[216:219], v153 offset:38912
	ds_read_b128 v[220:223], v153 offset:39936
	global_load_lds_dwordx4 v[228:229], off
	v_lshl_add_u64 v[228:229], s[18:19], 0, v[132:133]
	s_mov_b32 m0, s33
	s_nop 0
	global_load_lds_dwordx4 v[228:229], off
	s_waitcnt vmcnt(8)
	s_waitcnt lgkmcnt(0)
	v_mfma_f32_16x16x32_bf16 v[124:127], v[142:145], v[192:195], v[124:127]
	v_mfma_f32_16x16x32_bf16 v[120:123], v[158:161], v[192:195], v[120:123]
	s_barrier
	s_waitcnt lgkmcnt(0)
	v_mfma_f32_16x16x32_bf16 v[108:111], v[142:145], v[200:203], v[108:111]
	v_mfma_f32_16x16x32_bf16 v[104:107], v[158:161], v[200:203], v[104:107]
	v_mfma_f32_16x16x32_bf16 v[92:95], v[142:145], v[208:211], v[92:95]
	v_mfma_f32_16x16x32_bf16 v[88:91], v[158:161], v[208:211], v[88:91]
	v_mfma_f32_16x16x32_bf16 v[76:79], v[142:145], v[216:219], v[76:79]
	v_mfma_f32_16x16x32_bf16 v[72:75], v[158:161], v[216:219], v[72:75]
	v_mfma_f32_16x16x32_bf16 v[124:127], v[154:157], v[196:199], v[124:127]
	v_mfma_f32_16x16x32_bf16 v[120:123], v[162:165], v[196:199], v[120:123]
	v_mfma_f32_16x16x32_bf16 v[108:111], v[154:157], v[204:207], v[108:111]
	v_mfma_f32_16x16x32_bf16 v[104:107], v[162:165], v[204:207], v[104:107]
	v_mfma_f32_16x16x32_bf16 v[92:95], v[154:157], v[212:215], v[92:95]
	v_mfma_f32_16x16x32_bf16 v[88:91], v[162:165], v[212:215], v[88:91]
	v_mfma_f32_16x16x32_bf16 v[76:79], v[154:157], v[220:223], v[76:79]
	v_mfma_f32_16x16x32_bf16 v[72:75], v[162:165], v[220:223], v[72:75]
	v_mfma_f32_16x16x32_bf16 v[116:119], v[166:169], v[192:195], v[116:119]
	v_mfma_f32_16x16x32_bf16 v[112:115], v[184:187], v[192:195], v[112:115]
	v_mfma_f32_16x16x32_bf16 v[100:103], v[166:169], v[200:203], v[100:103]
	v_mfma_f32_16x16x32_bf16 v[96:99], v[184:187], v[200:203], v[96:99]
	v_mfma_f32_16x16x32_bf16 v[84:87], v[166:169], v[208:211], v[84:87]
	v_mfma_f32_16x16x32_bf16 v[80:83], v[184:187], v[208:211], v[80:83]
	v_mfma_f32_16x16x32_bf16 v[68:71], v[166:169], v[216:219], v[68:71]
	v_mfma_f32_16x16x32_bf16 v[64:67], v[184:187], v[216:219], v[64:67]
	v_mfma_f32_16x16x32_bf16 v[116:119], v[180:183], v[196:199], v[116:119]
	v_mfma_f32_16x16x32_bf16 v[112:115], v[188:191], v[196:199], v[112:115]
	v_mfma_f32_16x16x32_bf16 v[100:103], v[180:183], v[204:207], v[100:103]
	v_mfma_f32_16x16x32_bf16 v[96:99], v[188:191], v[204:207], v[96:99]
	v_mfma_f32_16x16x32_bf16 v[84:87], v[180:183], v[212:215], v[84:87]
	v_mfma_f32_16x16x32_bf16 v[80:83], v[188:191], v[212:215], v[80:83]
	v_mfma_f32_16x16x32_bf16 v[68:71], v[180:183], v[220:223], v[68:71]
	v_mfma_f32_16x16x32_bf16 v[64:67], v[188:191], v[220:223], v[64:67]
	s_barrier
; #define PG8_STAGE(bufoff, gbase, voff) do { _Pragma("unroll") for (int _i = 0; _i < 2; ++_i) \
;         __builtin_amdgcn_global_load_lds((const unsigned*)((const char*)(gbase) + (voff)[_i]), (PG8_LAS unsigned*)(lds + (bufoff) + ldsw + _i * 8192), 16, 0, 0); } while (0)
; #define PG8_LDA(dst, b, h) do { _Pragma("unroll") for (int m = 0; m < 4; ++m) _Pragma("unroll") for (int k = 0; k < 2; ++k) dst[m][k] = *(const PG8_LAS bf16x8*)(lds + PG8_SA(b, h) + aoff + m * 2048 + k * 1024); } while (0)
; #define PG8_MMA(ai, bj, At, Bt) do { __builtin_amdgcn_s_setprio(1); _Pragma("unroll") for (int m = 0; m < 4; ++m) _Pragma("unroll") for (int n = 0; n < 2; ++n) _Pragma("unroll") for (int k = 0; k < 2; ++k) \
;         acc[ai][bj][m][n] = __builtin_amdgcn_mfma_f32_16x16x32_bf16(Bt[n][k], At[m][k], acc[ai][bj][m][n], 0, 0, 0); __builtin_amdgcn_s_setprio(0); } while (0)
; #define PG8_WAIT_V(n) asm volatile("s_waitcnt vmcnt(" #n ")" ::: "memory")
; #define PG8_WAIT_L(n) asm volatile("s_waitcnt lgkmcnt(" #n ")" ::: "memory")
; #define PG8_BAR __builtin_amdgcn_s_barrier()
; #define PG8_SCHED __builtin_amdgcn_sched_barrier(0)
; template <class Epi, class Sched, bool ALIGN_EPI = false, bool SP2 = false>
; __device__ __forceinline__ void gemm_phase(PG8_LAS unsigned char* lds, const Gemm g, const Sched& S, const Epi& E) {
;     ...
;             PG8_LDA(At, 1, 1); PG8_STAGE(PG8_SB(1, 0), b3, voffB); PG8_STAGE(PG8_SB(1, 1), b3 + hstep, voffB); PG8_STAGE(PG8_SA(1, 0), a3, voffA);
;             PG8_WAIT_V(8); PG8_WAIT_L(0); PG8_BAR; PG8_MMA(1, 0, At, B0); PG8_MMA(1, 1, At, B1); PG8_BAR; PG8_SCHED;
;     ...
;         if constexpr (ALIGN_EPI) { if (wr == 0) PG8_BAR; }
	s_add_i32 s18, s50, s28
	v_lshl_add_u64 v[146:147], v[146:147], 0, s[4:5]
	s_mov_b32 m0, s18
	ds_read_b128 v[192:195], v153 offset:49152
	ds_read_b128 v[196:199], v153 offset:50176
	ds_read_b128 v[200:203], v153 offset:51200
	ds_read_b128 v[204:207], v153 offset:52224
	ds_read_b128 v[208:211], v153 offset:53248
	ds_read_b128 v[212:215], v153 offset:54272
	ds_read_b128 v[216:219], v153 offset:55296
	ds_read_b128 v[220:223], v153 offset:56320
	global_load_lds_dwordx4 v[146:147], off
	s_add_i32 m0, s18, 0x2000
	s_add_u32 s18, s22, 0x160080
	v_lshl_add_u64 v[146:147], v[170:171], 0, s[4:5]
	s_addc_u32 s19, s23, 0
	s_add_i32 s22, s51, s28
	global_load_lds_dwordx4 v[146:147], off
	v_lshl_add_u64 v[146:147], s[18:19], 0, v[130:131]
	s_mov_b32 m0, s22
	s_nop 0
	global_load_lds_dwordx4 v[146:147], off
	v_lshl_add_u64 v[146:147], s[18:19], 0, v[132:133]
	s_add_i32 m0, s22, 0x2000
	s_nop 0
	global_load_lds_dwordx4 v[146:147], off
	v_lshl_add_u64 v[146:147], v[224:225], 0, s[4:5]
	s_mov_b32 m0, s35
	s_nop 0
	global_load_lds_dwordx4 v[146:147], off
	v_lshl_add_u64 v[146:147], v[226:227], 0, s[4:5]
	s_mov_b32 m0, s36
	s_nop 0
	global_load_lds_dwordx4 v[146:147], off
	s_waitcnt vmcnt(8)
	s_waitcnt lgkmcnt(0)
	v_mfma_f32_16x16x32_bf16 v[60:63], v[142:145], v[192:195], v[60:63]
	v_mfma_f32_16x16x32_bf16 v[56:59], v[158:161], v[192:195], v[56:59]
	s_barrier
	s_waitcnt lgkmcnt(0)
	v_mfma_f32_16x16x32_bf16 v[44:47], v[142:145], v[200:203], v[44:47]
	v_mfma_f32_16x16x32_bf16 v[40:43], v[158:161], v[200:203], v[40:43]
	v_mfma_f32_16x16x32_bf16 v[28:31], v[142:145], v[208:211], v[28:31]
	v_mfma_f32_16x16x32_bf16 v[24:27], v[158:161], v[208:211], v[24:27]
	v_mfma_f32_16x16x32_bf16 v[12:15], v[142:145], v[216:219], v[12:15]
	v_mfma_f32_16x16x32_bf16 v[8:11], v[158:161], v[216:219], v[8:11]
	v_mfma_f32_16x16x32_bf16 v[60:63], v[154:157], v[196:199], v[60:63]
	v_mfma_f32_16x16x32_bf16 v[56:59], v[162:165], v[196:199], v[56:59]
	v_mfma_f32_16x16x32_bf16 v[44:47], v[154:157], v[204:207], v[44:47]
	v_mfma_f32_16x16x32_bf16 v[40:43], v[162:165], v[204:207], v[40:43]
	v_mfma_f32_16x16x32_bf16 v[28:31], v[154:157], v[212:215], v[28:31]
	v_mfma_f32_16x16x32_bf16 v[24:27], v[162:165], v[212:215], v[24:27]
	v_mfma_f32_16x16x32_bf16 v[12:15], v[154:157], v[220:223], v[12:15]
	v_mfma_f32_16x16x32_bf16 v[8:11], v[162:165], v[220:223], v[8:11]
	v_mfma_f32_16x16x32_bf16 v[52:55], v[166:169], v[192:195], v[52:55]
	v_mfma_f32_16x16x32_bf16 v[48:51], v[184:187], v[192:195], v[48:51]
	v_mfma_f32_16x16x32_bf16 v[36:39], v[166:169], v[200:203], v[36:39]
	v_mfma_f32_16x16x32_bf16 v[32:35], v[184:187], v[200:203], v[32:35]
	v_mfma_f32_16x16x32_bf16 v[20:23], v[166:169], v[208:211], v[20:23]
	v_mfma_f32_16x16x32_bf16 v[16:19], v[184:187], v[208:211], v[16:19]
	v_mfma_f32_16x16x32_bf16 v[4:7], v[166:169], v[216:219], v[4:7]
	v_mfma_f32_16x16x32_bf16 v[0:3], v[184:187], v[216:219], v[0:3]
	v_mfma_f32_16x16x32_bf16 v[52:55], v[180:183], v[196:199], v[52:55]
	v_mfma_f32_16x16x32_bf16 v[48:51], v[188:191], v[196:199], v[48:51]
	v_mfma_f32_16x16x32_bf16 v[36:39], v[180:183], v[204:207], v[36:39]
	v_mfma_f32_16x16x32_bf16 v[32:35], v[188:191], v[204:207], v[32:35]
	v_mfma_f32_16x16x32_bf16 v[20:23], v[180:183], v[212:215], v[20:23]
	v_mfma_f32_16x16x32_bf16 v[16:19], v[188:191], v[212:215], v[16:19]
	v_mfma_f32_16x16x32_bf16 v[4:7], v[180:183], v[220:223], v[4:7]
	v_mfma_f32_16x16x32_bf16 v[0:3], v[188:191], v[220:223], v[0:3]
	s_barrier
	s_add_i32 s49, s49, 2
	s_add_u32 s47, s47, 0x100
	s_addc_u32 s48, s48, 0
	s_cmpk_gt_u32 s49, 0x55
	s_mov_b64 s[18:19], s[20:21]
	s_cbranch_scc0 .LBB0_1080
	s_and_b64 vcc, exec, s[6:7]
	s_cbranch_vccz .LBB0_1083
	s_barrier

; #define PG8_STAGE(bufoff, gbase, voff) do { _Pragma("unroll") for (int _i = 0; _i < 2; ++_i) \
;         __builtin_amdgcn_global_load_lds((const unsigned*)((const char*)(gbase) + (voff)[_i]), (PG8_LAS unsigned*)(lds + (bufoff) + ldsw + _i * 8192), 16, 0, 0); } while (0)
; #define PG8_LDA(dst, b, h) do { _Pragma("unroll") for (int m = 0; m < 4; ++m) _Pragma("unroll") for (int k = 0; k < 2; ++k) dst[m][k] = *(const PG8_LAS bf16x8*)(lds + PG8_SA(b, h) + aoff + m * 2048 + k * 1024); } while (0)
; #define PG8_LDB(dst, b, h) do { _Pragma("unroll") for (int n = 0; n < 2; ++n) _Pragma("unroll") for (int k = 0; k < 2; ++k) dst[n][k] = *(const PG8_LAS bf16x8*)(lds + PG8_SB(b, h) + boff + n * 2048 + k * 1024); } while (0)
; #define PG8_MMA(ai, bj, At, Bt) do { __builtin_amdgcn_s_setprio(1); _Pragma("unroll") for (int m = 0; m < 4; ++m) _Pragma("unroll") for (int n = 0; n < 2; ++n) _Pragma("unroll") for (int k = 0; k < 2; ++k) \
;         acc[ai][bj][m][n] = __builtin_amdgcn_mfma_f32_16x16x32_bf16(Bt[n][k], At[m][k], acc[ai][bj][m][n], 0, 0, 0); __builtin_amdgcn_s_setprio(0); } while (0)
; #define PG8_WAIT_V(n) asm volatile("s_waitcnt vmcnt(" #n ")" ::: "memory")
; #define PG8_WAIT_L(n) asm volatile("s_waitcnt lgkmcnt(" #n ")" ::: "memory")
; #define PG8_BAR __builtin_amdgcn_s_barrier()
; #define PG8_SCHED __builtin_amdgcn_sched_barrier(0)
; template <class Epi, class Sched, bool ALIGN_EPI = false, bool SP2 = false>
; __device__ __forceinline__ void gemm_phase(PG8_LAS unsigned char* lds, const Gemm g, const Sched& S, const Epi& E) {
;     ...
;             PG8_LDB(B0, 0, 0); PG8_LDB(B1, 0, 1); PG8_SCHED; PG8_LDA(At, 0, 0); PG8_STAGE(PG8_SA(1, 1), a1 + hstep, voffA);
;             PG8_WAIT_V(8); PG8_WAIT_L(0); PG8_BAR; PG8_MMA(0, 0, At, B0); PG8_MMA(0, 1, At, B1); PG8_BAR; PG8_SCHED;
;             PG8_LDA(At, 0, 1); PG8_STAGE(PG8_SB(0, 0), b2, voffB); PG8_STAGE(PG8_SB(0, 1), b2 + hstep, voffB); PG8_STAGE(PG8_SA(0, 0), a2, voffA);
;             PG8_WAIT_V(8); PG8_WAIT_L(0); PG8_BAR; PG8_MMA(1, 0, At, B0); PG8_MMA(1, 1, At, B1); PG8_BAR; PG8_SCHED;
.LBB0_1181:
	ds_read_b128 v[146:149], v154
	ds_read_b128 v[158:161], v154 offset:1024
	ds_read_b128 v[162:165], v154 offset:2048
	ds_read_b128 v[166:169], v154 offset:3072
	ds_read_b128 v[180:183], v155
	ds_read_b128 v[184:187], v155 offset:1024
	ds_read_b128 v[188:191], v155 offset:2048
	ds_read_b128 v[192:195], v155 offset:3072
	s_add_u32 s22, s20, 0xfff80080
	s_addc_u32 s23, s21, -1
	s_cmp_eq_u32 s48, 28
	s_cselect_b32 s25, s11, s23
	s_cselect_b32 s24, s44, s22
	s_cselect_b32 s23, s7, s47
	s_cselect_b32 s22, s45, s46
	v_lshl_add_u64 v[170:171], s[20:21], 0, v[138:139]
	s_add_i32 m0, s17, 0xc000
	ds_read_b128 v[196:199], v156
	ds_read_b128 v[200:203], v156 offset:1024
	ds_read_b128 v[204:207], v156 offset:2048
	ds_read_b128 v[208:211], v156 offset:3072
	ds_read_b128 v[212:215], v156 offset:4096
	ds_read_b128 v[216:219], v156 offset:5120
	ds_read_b128 v[220:223], v156 offset:6144
	ds_read_b128 v[224:227], v156 offset:7168
	global_load_lds_dwordx4 v[170:171], off
	v_lshl_add_u64 v[170:171], s[20:21], 0, v[140:141]
	s_add_i32 m0, s17, 0xe000
	s_nop 0
	global_load_lds_dwordx4 v[170:171], off
	s_waitcnt vmcnt(8)
	s_waitcnt lgkmcnt(0)
	v_mfma_f32_16x16x32_bf16 v[124:127], v[146:149], v[196:199], v[124:127]
	v_mfma_f32_16x16x32_bf16 v[120:123], v[162:165], v[196:199], v[120:123]
	s_barrier
	s_waitcnt lgkmcnt(0)
	v_mfma_f32_16x16x32_bf16 v[112:115], v[146:149], v[204:207], v[112:115]
	v_mfma_f32_16x16x32_bf16 v[104:107], v[162:165], v[204:207], v[104:107]
	v_mfma_f32_16x16x32_bf16 v[96:99], v[146:149], v[212:215], v[96:99]
	v_mfma_f32_16x16x32_bf16 v[88:91], v[162:165], v[212:215], v[88:91]
	v_mfma_f32_16x16x32_bf16 v[80:83], v[146:149], v[220:223], v[80:83]
	v_mfma_f32_16x16x32_bf16 v[72:75], v[162:165], v[220:223], v[72:75]
	v_mfma_f32_16x16x32_bf16 v[124:127], v[158:161], v[200:203], v[124:127]
	v_mfma_f32_16x16x32_bf16 v[120:123], v[166:169], v[200:203], v[120:123]
	v_mfma_f32_16x16x32_bf16 v[112:115], v[158:161], v[208:211], v[112:115]
	v_mfma_f32_16x16x32_bf16 v[104:107], v[166:169], v[208:211], v[104:107]
	v_mfma_f32_16x16x32_bf16 v[96:99], v[158:161], v[216:219], v[96:99]
	v_mfma_f32_16x16x32_bf16 v[88:91], v[166:169], v[216:219], v[88:91]
	v_mfma_f32_16x16x32_bf16 v[80:83], v[158:161], v[224:227], v[80:83]
	v_mfma_f32_16x16x32_bf16 v[72:75], v[166:169], v[224:227], v[72:75]
	v_mfma_f32_16x16x32_bf16 v[116:119], v[180:183], v[196:199], v[116:119]
	v_mfma_f32_16x16x32_bf16 v[108:111], v[188:191], v[196:199], v[108:111]
	v_mfma_f32_16x16x32_bf16 v[100:103], v[180:183], v[204:207], v[100:103]
	v_mfma_f32_16x16x32_bf16 v[92:95], v[188:191], v[204:207], v[92:95]
	v_mfma_f32_16x16x32_bf16 v[84:87], v[180:183], v[212:215], v[84:87]
	v_mfma_f32_16x16x32_bf16 v[76:79], v[188:191], v[212:215], v[76:79]
	v_mfma_f32_16x16x32_bf16 v[68:71], v[180:183], v[220:223], v[68:71]
	v_mfma_f32_16x16x32_bf16 v[64:67], v[188:191], v[220:223], v[64:67]
	v_mfma_f32_16x16x32_bf16 v[116:119], v[184:187], v[200:203], v[116:119]
	v_mfma_f32_16x16x32_bf16 v[108:111], v[192:195], v[200:203], v[108:111]
	v_mfma_f32_16x16x32_bf16 v[100:103], v[184:187], v[208:211], v[100:103]
	v_mfma_f32_16x16x32_bf16 v[92:95], v[192:195], v[208:211], v[92:95]
	v_mfma_f32_16x16x32_bf16 v[84:87], v[184:187], v[216:219], v[84:87]
	v_mfma_f32_16x16x32_bf16 v[76:79], v[192:195], v[216:219], v[76:79]
	v_mfma_f32_16x16x32_bf16 v[68:71], v[184:187], v[224:227], v[68:71]
	v_mfma_f32_16x16x32_bf16 v[64:67], v[192:195], v[224:227], v[64:67]
	s_barrier
	s_add_i32 s49, s35, s28
	v_lshl_add_u64 v[170:171], s[22:23], 0, v[132:133]
	s_mov_b32 m0, s49
	ds_read_b128 v[196:199], v156 offset:16384
	ds_read_b128 v[200:203], v156 offset:17408
	ds_read_b128 v[204:207], v156 offset:18432
	ds_read_b128 v[208:211], v156 offset:19456
	ds_read_b128 v[212:215], v156 offset:20480
	ds_read_b128 v[216:219], v156 offset:21504
	ds_read_b128 v[220:223], v156 offset:22528
	ds_read_b128 v[224:227], v156 offset:23552
	global_load_lds_dwordx4 v[170:171], off
	s_add_i32 m0, s49, 0x2000
	s_add_u32 s50, s22, 0x80000
	v_lshl_add_u64 v[228:229], s[22:23], 0, v[136:137]
	s_addc_u32 s51, s23, 0
	s_add_i32 s49, s36, s28
	global_load_lds_dwordx4 v[228:229], off
	v_lshl_add_u64 v[230:231], s[50:51], 0, v[132:133]
	s_mov_b32 m0, s49
	v_lshl_add_u64 v[232:233], s[24:25], 0, v[134:135]
	global_load_lds_dwordx4 v[230:231], off
	v_lshl_add_u64 v[230:231], s[50:51], 0, v[136:137]
	s_add_i32 m0, s49, 0x2000
	s_nop 0
	global_load_lds_dwordx4 v[230:231], off
	v_lshl_add_u64 v[230:231], s[24:25], 0, v[130:131]
	s_mov_b32 m0, s17
	s_nop 0
	global_load_lds_dwordx4 v[230:231], off
	s_mov_b32 m0, s29
	s_nop 0
	global_load_lds_dwordx4 v[232:233], off
	s_waitcnt vmcnt(8)
	s_waitcnt lgkmcnt(0)
	v_mfma_f32_16x16x32_bf16 v[60:63], v[146:149], v[196:199], v[60:63]
	v_mfma_f32_16x16x32_bf16 v[56:59], v[162:165], v[196:199], v[56:59]
	s_barrier
; #define PG8_STAGE(bufoff, gbase, voff) do { _Pragma("unroll") for (int _i = 0; _i < 2; ++_i) \
;         __builtin_amdgcn_global_load_lds((const unsigned*)((const char*)(gbase) + (voff)[_i]), (PG8_LAS unsigned*)(lds + (bufoff) + ldsw + _i * 8192), 16, 0, 0); } while (0)
; #define PG8_LDA(dst, b, h) do { _Pragma("unroll") for (int m = 0; m < 4; ++m) _Pragma("unroll") for (int k = 0; k < 2; ++k) dst[m][k] = *(const PG8_LAS bf16x8*)(lds + PG8_SA(b, h) + aoff + m * 2048 + k * 1024); } while (0)
; #define PG8_LDB(dst, b, h) do { _Pragma("unroll") for (int n = 0; n < 2; ++n) _Pragma("unroll") for (int k = 0; k < 2; ++k) dst[n][k] = *(const PG8_LAS bf16x8*)(lds + PG8_SB(b, h) + boff + n * 2048 + k * 1024); } while (0)
; #define PG8_MMA(ai, bj, At, Bt) do { __builtin_amdgcn_s_setprio(1); _Pragma("unroll") for (int m = 0; m < 4; ++m) _Pragma("unroll") for (int n = 0; n < 2; ++n) _Pragma("unroll") for (int k = 0; k < 2; ++k) \
;         acc[ai][bj][m][n] = __builtin_amdgcn_mfma_f32_16x16x32_bf16(Bt[n][k], At[m][k], acc[ai][bj][m][n], 0, 0, 0); __builtin_amdgcn_s_setprio(0); } while (0)
; #define PG8_WAIT_V(n) asm volatile("s_waitcnt vmcnt(" #n ")" ::: "memory")
; #define PG8_WAIT_L(n) asm volatile("s_waitcnt lgkmcnt(" #n ")" ::: "memory")
; #define PG8_BAR __builtin_amdgcn_s_barrier()
; #define PG8_SCHED __builtin_amdgcn_sched_barrier(0)
; template <class Epi, class Sched, bool ALIGN_EPI = false, bool SP2 = false>
; __device__ __forceinline__ void gemm_phase(PG8_LAS unsigned char* lds, const Gemm g, const Sched& S, const Epi& E) {
;     ...
;             PG8_WAIT_V(8); PG8_WAIT_L(0); PG8_BAR; PG8_MMA(1, 0, At, B0); PG8_MMA(1, 1, At, B1); PG8_BAR; PG8_SCHED;
;             PG8_LDB(B0, 1, 0); PG8_LDB(B1, 1, 1); PG8_SCHED; PG8_LDA(At, 1, 0); PG8_STAGE(PG8_SA(0, 1), a2 + hstep, voffA);
;             PG8_WAIT_V(8); PG8_WAIT_L(0); PG8_BAR; PG8_MMA(0, 0, At, B0); PG8_MMA(0, 1, At, B1); PG8_BAR; PG8_SCHED;
	s_waitcnt lgkmcnt(0)
	v_mfma_f32_16x16x32_bf16 v[52:55], v[146:149], v[204:207], v[52:55]
	v_mfma_f32_16x16x32_bf16 v[44:47], v[162:165], v[204:207], v[44:47]
	v_mfma_f32_16x16x32_bf16 v[36:39], v[146:149], v[212:215], v[36:39]
	v_mfma_f32_16x16x32_bf16 v[28:31], v[162:165], v[212:215], v[28:31]
	v_mfma_f32_16x16x32_bf16 v[20:23], v[146:149], v[220:223], v[20:23]
	v_mfma_f32_16x16x32_bf16 v[12:15], v[162:165], v[220:223], v[12:15]
	v_mfma_f32_16x16x32_bf16 v[60:63], v[158:161], v[200:203], v[60:63]
	v_mfma_f32_16x16x32_bf16 v[56:59], v[166:169], v[200:203], v[56:59]
	v_mfma_f32_16x16x32_bf16 v[52:55], v[158:161], v[208:211], v[52:55]
	v_mfma_f32_16x16x32_bf16 v[44:47], v[166:169], v[208:211], v[44:47]
	v_mfma_f32_16x16x32_bf16 v[36:39], v[158:161], v[216:219], v[36:39]
	v_mfma_f32_16x16x32_bf16 v[28:31], v[166:169], v[216:219], v[28:31]
	v_mfma_f32_16x16x32_bf16 v[20:23], v[158:161], v[224:227], v[20:23]
	v_mfma_f32_16x16x32_bf16 v[12:15], v[166:169], v[224:227], v[12:15]
	v_mfma_f32_16x16x32_bf16 v[48:51], v[180:183], v[196:199], v[48:51]
	v_mfma_f32_16x16x32_bf16 v[40:43], v[188:191], v[196:199], v[40:43]
	v_mfma_f32_16x16x32_bf16 v[32:35], v[180:183], v[204:207], v[32:35]
	v_mfma_f32_16x16x32_bf16 v[24:27], v[188:191], v[204:207], v[24:27]
	v_mfma_f32_16x16x32_bf16 v[16:19], v[180:183], v[212:215], v[16:19]
	v_mfma_f32_16x16x32_bf16 v[8:11], v[188:191], v[212:215], v[8:11]
	v_mfma_f32_16x16x32_bf16 v[4:7], v[180:183], v[220:223], v[4:7]
	v_mfma_f32_16x16x32_bf16 v[0:3], v[188:191], v[220:223], v[0:3]
	v_mfma_f32_16x16x32_bf16 v[48:51], v[184:187], v[200:203], v[48:51]
	v_mfma_f32_16x16x32_bf16 v[40:43], v[192:195], v[200:203], v[40:43]
	v_mfma_f32_16x16x32_bf16 v[32:35], v[184:187], v[208:211], v[32:35]
	v_mfma_f32_16x16x32_bf16 v[24:27], v[192:195], v[208:211], v[24:27]
	v_mfma_f32_16x16x32_bf16 v[16:19], v[184:187], v[216:219], v[16:19]
	v_mfma_f32_16x16x32_bf16 v[8:11], v[192:195], v[216:219], v[8:11]
	v_mfma_f32_16x16x32_bf16 v[4:7], v[184:187], v[224:227], v[4:7]
	v_mfma_f32_16x16x32_bf16 v[0:3], v[192:195], v[224:227], v[0:3]
	s_barrier
	s_add_i32 s49, 0, 0x18000
	v_add_u32_e32 v157, s49, v151
	s_add_i32 s50, 0, 0x1c000
	ds_read_b128 v[146:149], v157
	ds_read_b128 v[158:161], v157 offset:1024
	ds_read_b128 v[162:165], v157 offset:2048
	ds_read_b128 v[166:169], v157 offset:3072
	v_add_u32_e32 v157, s50, v151
	ds_read_b128 v[180:183], v157
	ds_read_b128 v[184:187], v157 offset:1024
	ds_read_b128 v[188:191], v157 offset:2048
	ds_read_b128 v[192:195], v157 offset:3072
	s_add_u32 s24, s24, 0x80000
	s_addc_u32 s25, s25, 0
	s_mov_b32 m0, s30
	v_lshl_add_u64 v[234:235], s[24:25], 0, v[130:131]
	ds_read_b128 v[196:199], v156 offset:32768
	ds_read_b128 v[200:203], v156 offset:33792
	ds_read_b128 v[204:207], v156 offset:34816
	ds_read_b128 v[208:211], v156 offset:35840
	ds_read_b128 v[212:215], v156 offset:36864
	ds_read_b128 v[216:219], v156 offset:37888
	ds_read_b128 v[220:223], v156 offset:38912
	ds_read_b128 v[224:227], v156 offset:39936
	global_load_lds_dwordx4 v[234:235], off
	v_lshl_add_u64 v[234:235], s[24:25], 0, v[134:135]
	s_mov_b32 m0, s31
	s_nop 0
	global_load_lds_dwordx4 v[234:235], off
	s_waitcnt vmcnt(8)
	s_waitcnt lgkmcnt(0)
	v_mfma_f32_16x16x32_bf16 v[124:127], v[146:149], v[196:199], v[124:127]
	v_mfma_f32_16x16x32_bf16 v[120:123], v[162:165], v[196:199], v[120:123]
	s_barrier
	s_waitcnt lgkmcnt(0)
	v_mfma_f32_16x16x32_bf16 v[112:115], v[146:149], v[204:207], v[112:115]
	v_mfma_f32_16x16x32_bf16 v[104:107], v[162:165], v[204:207], v[104:107]
	v_mfma_f32_16x16x32_bf16 v[96:99], v[146:149], v[212:215], v[96:99]
	v_mfma_f32_16x16x32_bf16 v[88:91], v[162:165], v[212:215], v[88:91]
	v_mfma_f32_16x16x32_bf16 v[80:83], v[146:149], v[220:223], v[80:83]
	v_mfma_f32_16x16x32_bf16 v[72:75], v[162:165], v[220:223], v[72:75]
	v_mfma_f32_16x16x32_bf16 v[124:127], v[158:161], v[200:203], v[124:127]
	v_mfma_f32_16x16x32_bf16 v[120:123], v[166:169], v[200:203], v[120:123]
	v_mfma_f32_16x16x32_bf16 v[112:115], v[158:161], v[208:211], v[112:115]
	v_mfma_f32_16x16x32_bf16 v[104:107], v[166:169], v[208:211], v[104:107]
	v_mfma_f32_16x16x32_bf16 v[96:99], v[158:161], v[216:219], v[96:99]
	v_mfma_f32_16x16x32_bf16 v[88:91], v[166:169], v[216:219], v[88:91]
	v_mfma_f32_16x16x32_bf16 v[80:83], v[158:161], v[224:227], v[80:83]
	v_mfma_f32_16x16x32_bf16 v[72:75], v[166:169], v[224:227], v[72:75]
	v_mfma_f32_16x16x32_bf16 v[116:119], v[180:183], v[196:199], v[116:119]
	v_mfma_f32_16x16x32_bf16 v[108:111], v[188:191], v[196:199], v[108:111]
	v_mfma_f32_16x16x32_bf16 v[100:103], v[180:183], v[204:207], v[100:103]
	v_mfma_f32_16x16x32_bf16 v[92:95], v[188:191], v[204:207], v[92:95]
	v_mfma_f32_16x16x32_bf16 v[84:87], v[180:183], v[212:215], v[84:87]
	v_mfma_f32_16x16x32_bf16 v[76:79], v[188:191], v[212:215], v[76:79]
	v_mfma_f32_16x16x32_bf16 v[68:71], v[180:183], v[220:223], v[68:71]
	v_mfma_f32_16x16x32_bf16 v[64:67], v[188:191], v[220:223], v[64:67]
	v_mfma_f32_16x16x32_bf16 v[116:119], v[184:187], v[200:203], v[116:119]
	v_mfma_f32_16x16x32_bf16 v[108:111], v[192:195], v[200:203], v[108:111]
	v_mfma_f32_16x16x32_bf16 v[100:103], v[184:187], v[208:211], v[100:103]
	v_mfma_f32_16x16x32_bf16 v[92:95], v[192:195], v[208:211], v[92:95]
	v_mfma_f32_16x16x32_bf16 v[84:87], v[184:187], v[216:219], v[84:87]
	v_mfma_f32_16x16x32_bf16 v[76:79], v[192:195], v[216:219], v[76:79]
	v_mfma_f32_16x16x32_bf16 v[68:71], v[184:187], v[224:227], v[68:71]
	v_mfma_f32_16x16x32_bf16 v[64:67], v[192:195], v[224:227], v[64:67]
	s_barrier
; #define PG8_STAGE(bufoff, gbase, voff) do { _Pragma("unroll") for (int _i = 0; _i < 2; ++_i) \
;         __builtin_amdgcn_global_load_lds((const unsigned*)((const char*)(gbase) + (voff)[_i]), (PG8_LAS unsigned*)(lds + (bufoff) + ldsw + _i * 8192), 16, 0, 0); } while (0)
; #define PG8_LDA(dst, b, h) do { _Pragma("unroll") for (int m = 0; m < 4; ++m) _Pragma("unroll") for (int k = 0; k < 2; ++k) dst[m][k] = *(const PG8_LAS bf16x8*)(lds + PG8_SA(b, h) + aoff + m * 2048 + k * 1024); } while (0)
; #define PG8_MMA(ai, bj, At, Bt) do { __builtin_amdgcn_s_setprio(1); _Pragma("unroll") for (int m = 0; m < 4; ++m) _Pragma("unroll") for (int n = 0; n < 2; ++n) _Pragma("unroll") for (int k = 0; k < 2; ++k) \
;         acc[ai][bj][m][n] = __builtin_amdgcn_mfma_f32_16x16x32_bf16(Bt[n][k], At[m][k], acc[ai][bj][m][n], 0, 0, 0); __builtin_amdgcn_s_setprio(0); } while (0)
; #define PG8_WAIT_V(n) asm volatile("s_waitcnt vmcnt(" #n ")" ::: "memory")
; #define PG8_WAIT_L(n) asm volatile("s_waitcnt lgkmcnt(" #n ")" ::: "memory")
; #define PG8_BAR __builtin_amdgcn_s_barrier()
; #define PG8_SCHED __builtin_amdgcn_sched_barrier(0)
; template <class Epi, class Sched, bool ALIGN_EPI = false, bool SP2 = false>
; __device__ __forceinline__ void gemm_phase(PG8_LAS unsigned char* lds, const Gemm g, const Sched& S, const Epi& E) {
;     ...
;             PG8_LDA(At, 1, 1); PG8_STAGE(PG8_SB(1, 0), b3, voffB); PG8_STAGE(PG8_SB(1, 1), b3 + hstep, voffB); PG8_STAGE(PG8_SA(1, 0), a3, voffA);
;             PG8_WAIT_V(8); PG8_WAIT_L(0); PG8_BAR; PG8_MMA(1, 0, At, B0); PG8_MMA(1, 1, At, B1); PG8_BAR; PG8_SCHED;
;     ...
;         if constexpr (ALIGN_EPI) { if (wr == 0) PG8_BAR; }
	s_add_i32 s24, s49, s28
	v_lshl_add_u64 v[170:171], v[170:171], 0, s[2:3]
	s_mov_b32 m0, s24
	ds_read_b128 v[196:199], v156 offset:49152
	ds_read_b128 v[200:203], v156 offset:50176
	ds_read_b128 v[204:207], v156 offset:51200
	ds_read_b128 v[208:211], v156 offset:52224
	ds_read_b128 v[212:215], v156 offset:53248
	ds_read_b128 v[216:219], v156 offset:54272
	ds_read_b128 v[220:223], v156 offset:55296
	ds_read_b128 v[224:227], v156 offset:56320
	global_load_lds_dwordx4 v[170:171], off
	s_add_i32 m0, s24, 0x2000
	s_add_u32 s22, s22, 0x80080
	v_lshl_add_u64 v[170:171], v[228:229], 0, s[2:3]
	s_addc_u32 s23, s23, 0
	s_add_i32 s24, s50, s28
	global_load_lds_dwordx4 v[170:171], off
	v_lshl_add_u64 v[170:171], s[22:23], 0, v[132:133]
	s_mov_b32 m0, s24
	s_nop 0
	global_load_lds_dwordx4 v[170:171], off
	v_lshl_add_u64 v[170:171], s[22:23], 0, v[136:137]
	s_add_i32 m0, s24, 0x2000
	s_nop 0
	global_load_lds_dwordx4 v[170:171], off
	v_lshl_add_u64 v[170:171], v[230:231], 0, s[2:3]
	s_mov_b32 m0, s33
	s_nop 0
	global_load_lds_dwordx4 v[170:171], off
	v_lshl_add_u64 v[170:171], v[232:233], 0, s[2:3]
	s_mov_b32 m0, s34
	s_nop 0
	global_load_lds_dwordx4 v[170:171], off
	s_waitcnt vmcnt(8)
	s_waitcnt lgkmcnt(0)
	v_mfma_f32_16x16x32_bf16 v[60:63], v[146:149], v[196:199], v[60:63]
	v_mfma_f32_16x16x32_bf16 v[56:59], v[162:165], v[196:199], v[56:59]
	s_barrier
	s_waitcnt lgkmcnt(0)
	v_mfma_f32_16x16x32_bf16 v[52:55], v[146:149], v[204:207], v[52:55]
	v_mfma_f32_16x16x32_bf16 v[44:47], v[162:165], v[204:207], v[44:47]
	v_mfma_f32_16x16x32_bf16 v[36:39], v[146:149], v[212:215], v[36:39]
	v_mfma_f32_16x16x32_bf16 v[28:31], v[162:165], v[212:215], v[28:31]
	v_mfma_f32_16x16x32_bf16 v[20:23], v[146:149], v[220:223], v[20:23]
	v_mfma_f32_16x16x32_bf16 v[12:15], v[162:165], v[220:223], v[12:15]
	v_mfma_f32_16x16x32_bf16 v[60:63], v[158:161], v[200:203], v[60:63]
	v_mfma_f32_16x16x32_bf16 v[56:59], v[166:169], v[200:203], v[56:59]
	v_mfma_f32_16x16x32_bf16 v[52:55], v[158:161], v[208:211], v[52:55]
	v_mfma_f32_16x16x32_bf16 v[44:47], v[166:169], v[208:211], v[44:47]
	v_mfma_f32_16x16x32_bf16 v[36:39], v[158:161], v[216:219], v[36:39]
	v_mfma_f32_16x16x32_bf16 v[28:31], v[166:169], v[216:219], v[28:31]
	v_mfma_f32_16x16x32_bf16 v[20:23], v[158:161], v[224:227], v[20:23]
	v_mfma_f32_16x16x32_bf16 v[12:15], v[166:169], v[224:227], v[12:15]
	v_mfma_f32_16x16x32_bf16 v[48:51], v[180:183], v[196:199], v[48:51]
	v_mfma_f32_16x16x32_bf16 v[40:43], v[188:191], v[196:199], v[40:43]
	v_mfma_f32_16x16x32_bf16 v[32:35], v[180:183], v[204:207], v[32:35]
	v_mfma_f32_16x16x32_bf16 v[24:27], v[188:191], v[204:207], v[24:27]
	v_mfma_f32_16x16x32_bf16 v[16:19], v[180:183], v[212:215], v[16:19]
	v_mfma_f32_16x16x32_bf16 v[8:11], v[188:191], v[212:215], v[8:11]
	v_mfma_f32_16x16x32_bf16 v[4:7], v[180:183], v[220:223], v[4:7]
	v_mfma_f32_16x16x32_bf16 v[0:3], v[188:191], v[220:223], v[0:3]
	v_mfma_f32_16x16x32_bf16 v[48:51], v[184:187], v[200:203], v[48:51]
	v_mfma_f32_16x16x32_bf16 v[40:43], v[192:195], v[200:203], v[40:43]
	v_mfma_f32_16x16x32_bf16 v[32:35], v[184:187], v[208:211], v[32:35]
	v_mfma_f32_16x16x32_bf16 v[24:27], v[192:195], v[208:211], v[24:27]
	v_mfma_f32_16x16x32_bf16 v[16:19], v[184:187], v[216:219], v[16:19]
	v_mfma_f32_16x16x32_bf16 v[8:11], v[192:195], v[216:219], v[8:11]
	v_mfma_f32_16x16x32_bf16 v[4:7], v[184:187], v[224:227], v[4:7]
	v_mfma_f32_16x16x32_bf16 v[0:3], v[192:195], v[224:227], v[0:3]
	s_barrier
	s_add_i32 s48, s48, 2
	s_add_u32 s20, s20, 0x100
	s_addc_u32 s21, s21, 0
	s_add_u32 s46, s46, 0x100
	s_addc_u32 s47, s47, 0
	s_cmp_gt_u32 s48, 29
	s_cbranch_scc0 .LBB0_1181
	s_and_b64 vcc, exec, s[4:5]
	s_cbranch_vccz .LBB0_1184
	s_barrier

; #define PG8_STAGE(bufoff, gbase, voff) do { _Pragma("unroll") for (int _i = 0; _i < 2; ++_i) \
;         __builtin_amdgcn_global_load_lds((const unsigned*)((const char*)(gbase) + (voff)[_i]), (PG8_LAS unsigned*)(lds + (bufoff) + ldsw + _i * 8192), 16, 0, 0); } while (0)
; #define PG8_LDA(dst, b, h) do { _Pragma("unroll") for (int m = 0; m < 4; ++m) _Pragma("unroll") for (int k = 0; k < 2; ++k) dst[m][k] = *(const PG8_LAS bf16x8*)(lds + PG8_SA(b, h) + aoff + m * 2048 + k * 1024); } while (0)
; #define PG8_LDB(dst, b, h) do { _Pragma("unroll") for (int n = 0; n < 2; ++n) _Pragma("unroll") for (int k = 0; k < 2; ++k) dst[n][k] = *(const PG8_LAS bf16x8*)(lds + PG8_SB(b, h) + boff + n * 2048 + k * 1024); } while (0)
; #define PG8_MMA(ai, bj, At, Bt) do { __builtin_amdgcn_s_setprio(1); _Pragma("unroll") for (int m = 0; m < 4; ++m) _Pragma("unroll") for (int n = 0; n < 2; ++n) _Pragma("unroll") for (int k = 0; k < 2; ++k) \
;         acc[ai][bj][m][n] = __builtin_amdgcn_mfma_f32_16x16x32_bf16(Bt[n][k], At[m][k], acc[ai][bj][m][n], 0, 0, 0); __builtin_amdgcn_s_setprio(0); } while (0)
; #define PG8_WAIT_V(n) asm volatile("s_waitcnt vmcnt(" #n ")" ::: "memory")
; #define PG8_WAIT_L(n) asm volatile("s_waitcnt lgkmcnt(" #n ")" ::: "memory")
; #define PG8_BAR __builtin_amdgcn_s_barrier()
; #define PG8_SCHED __builtin_amdgcn_sched_barrier(0)
; template <class Epi, class Sched, bool ALIGN_EPI = false, bool SP2 = false>
; __device__ __forceinline__ void gemm_phase(PG8_LAS unsigned char* lds, const Gemm g, const Sched& S, const Epi& E) {
;     ...
;             PG8_LDB(B0, 0, 0); PG8_LDB(B1, 0, 1); PG8_SCHED; PG8_LDA(At, 0, 0); PG8_STAGE(PG8_SA(1, 1), a1 + hstep, voffA);
;             PG8_WAIT_V(8); PG8_WAIT_L(0); PG8_BAR; PG8_MMA(0, 0, At, B0); PG8_MMA(0, 1, At, B1); PG8_BAR; PG8_SCHED;
;             PG8_LDA(At, 0, 1); PG8_STAGE(PG8_SB(0, 0), b2, voffB); PG8_STAGE(PG8_SB(0, 1), b2 + hstep, voffB); PG8_STAGE(PG8_SA(0, 0), a2, voffA);
;             PG8_WAIT_V(8); PG8_WAIT_L(0); PG8_BAR; PG8_MMA(1, 0, At, B0); PG8_MMA(1, 1, At, B1); PG8_BAR; PG8_SCHED;
.LBB0_1457:
	ds_read_b128 v[142:145], v151
	ds_read_b128 v[154:157], v151 offset:1024
	ds_read_b128 v[158:161], v151 offset:2048
	ds_read_b128 v[162:165], v151 offset:3072
	ds_read_b128 v[166:169], v152
	ds_read_b128 v[178:181], v152 offset:1024
	ds_read_b128 v[182:185], v152 offset:2048
	ds_read_b128 v[186:189], v152 offset:3072
	s_add_u32 s24, s22, 0x100
	s_addc_u32 s25, s23, 0
	s_cmp_eq_u32 s47, 28
	s_cselect_b32 s29, s15, s25
	s_cselect_b32 s28, s21, s24
	s_cselect_b32 s27, s13, s46
	s_cselect_b32 s26, s44, s45
	v_lshl_add_u64 v[146:147], s[22:23], 0, v[134:135]
	s_add_i32 m0, s34, 0xc000
	ds_read_b128 v[190:193], v153
	ds_read_b128 v[194:197], v153 offset:1024
	ds_read_b128 v[198:201], v153 offset:2048
	ds_read_b128 v[202:205], v153 offset:3072
	ds_read_b128 v[206:209], v153 offset:4096
	ds_read_b128 v[210:213], v153 offset:5120
	ds_read_b128 v[214:217], v153 offset:6144
	ds_read_b128 v[218:221], v153 offset:7168
	global_load_lds_dwordx4 v[146:147], off
	v_lshl_add_u64 v[146:147], s[22:23], 0, v[136:137]
	s_add_i32 m0, s34, 0xe000
	s_nop 0
	global_load_lds_dwordx4 v[146:147], off
	s_waitcnt vmcnt(8)
	s_waitcnt lgkmcnt(0)
	v_mfma_f32_16x16x32_bf16 v[124:127], v[142:145], v[190:193], v[124:127]
	v_mfma_f32_16x16x32_bf16 v[120:123], v[158:161], v[190:193], v[120:123]
	s_barrier
	s_waitcnt lgkmcnt(0)
	v_mfma_f32_16x16x32_bf16 v[108:111], v[142:145], v[198:201], v[108:111]
	v_mfma_f32_16x16x32_bf16 v[104:107], v[158:161], v[198:201], v[104:107]
	v_mfma_f32_16x16x32_bf16 v[92:95], v[142:145], v[206:209], v[92:95]
	v_mfma_f32_16x16x32_bf16 v[88:91], v[158:161], v[206:209], v[88:91]
	v_mfma_f32_16x16x32_bf16 v[76:79], v[142:145], v[214:217], v[76:79]
	v_mfma_f32_16x16x32_bf16 v[72:75], v[158:161], v[214:217], v[72:75]
	v_mfma_f32_16x16x32_bf16 v[124:127], v[154:157], v[194:197], v[124:127]
	v_mfma_f32_16x16x32_bf16 v[120:123], v[162:165], v[194:197], v[120:123]
	v_mfma_f32_16x16x32_bf16 v[108:111], v[154:157], v[202:205], v[108:111]
	v_mfma_f32_16x16x32_bf16 v[104:107], v[162:165], v[202:205], v[104:107]
	v_mfma_f32_16x16x32_bf16 v[92:95], v[154:157], v[210:213], v[92:95]
	v_mfma_f32_16x16x32_bf16 v[88:91], v[162:165], v[210:213], v[88:91]
	v_mfma_f32_16x16x32_bf16 v[76:79], v[154:157], v[218:221], v[76:79]
	v_mfma_f32_16x16x32_bf16 v[72:75], v[162:165], v[218:221], v[72:75]
	v_mfma_f32_16x16x32_bf16 v[116:119], v[166:169], v[190:193], v[116:119]
	v_mfma_f32_16x16x32_bf16 v[112:115], v[182:185], v[190:193], v[112:115]
	v_mfma_f32_16x16x32_bf16 v[100:103], v[166:169], v[198:201], v[100:103]
	v_mfma_f32_16x16x32_bf16 v[96:99], v[182:185], v[198:201], v[96:99]
	v_mfma_f32_16x16x32_bf16 v[84:87], v[166:169], v[206:209], v[84:87]
	v_mfma_f32_16x16x32_bf16 v[80:83], v[182:185], v[206:209], v[80:83]
	v_mfma_f32_16x16x32_bf16 v[68:71], v[166:169], v[214:217], v[68:71]
	v_mfma_f32_16x16x32_bf16 v[64:67], v[182:185], v[214:217], v[64:67]
	v_mfma_f32_16x16x32_bf16 v[116:119], v[178:181], v[194:197], v[116:119]
	v_mfma_f32_16x16x32_bf16 v[112:115], v[186:189], v[194:197], v[112:115]
	v_mfma_f32_16x16x32_bf16 v[100:103], v[178:181], v[202:205], v[100:103]
	v_mfma_f32_16x16x32_bf16 v[96:99], v[186:189], v[202:205], v[96:99]
	v_mfma_f32_16x16x32_bf16 v[84:87], v[178:181], v[210:213], v[84:87]
	v_mfma_f32_16x16x32_bf16 v[80:83], v[186:189], v[210:213], v[80:83]
	v_mfma_f32_16x16x32_bf16 v[68:71], v[178:181], v[218:221], v[68:71]
	v_mfma_f32_16x16x32_bf16 v[64:67], v[186:189], v[218:221], v[64:67]
	s_barrier
	s_add_i32 s22, s41, s33
	v_lshl_add_u64 v[146:147], s[26:27], 0, v[130:131]
	s_mov_b32 m0, s22
	ds_read_b128 v[190:193], v153 offset:16384
	ds_read_b128 v[194:197], v153 offset:17408
	ds_read_b128 v[198:201], v153 offset:18432
	ds_read_b128 v[202:205], v153 offset:19456
	ds_read_b128 v[206:209], v153 offset:20480
	ds_read_b128 v[210:213], v153 offset:21504
	ds_read_b128 v[214:217], v153 offset:22528
	ds_read_b128 v[218:221], v153 offset:23552
	global_load_lds_dwordx4 v[146:147], off
	s_add_i32 m0, s22, 0x2000
	s_add_u32 s22, s26, 0x80000
	v_lshl_add_u64 v[170:171], s[26:27], 0, v[132:133]
	s_addc_u32 s23, s27, 0
	s_add_i32 s48, s42, s33
	global_load_lds_dwordx4 v[170:171], off
	v_lshl_add_u64 v[222:223], s[22:23], 0, v[130:131]
	s_mov_b32 m0, s48
	v_lshl_add_u64 v[224:225], s[28:29], 0, v[132:133]
	global_load_lds_dwordx4 v[222:223], off
	v_lshl_add_u64 v[222:223], s[22:23], 0, v[132:133]
	s_add_i32 m0, s48, 0x2000
	s_nop 0
	global_load_lds_dwordx4 v[222:223], off
	v_lshl_add_u64 v[222:223], s[28:29], 0, v[130:131]
	s_mov_b32 m0, s34
	s_nop 0
	global_load_lds_dwordx4 v[222:223], off
	s_mov_b32 m0, s35
	s_nop 0
	global_load_lds_dwordx4 v[224:225], off
	s_waitcnt vmcnt(8)
	s_waitcnt lgkmcnt(0)
	v_mfma_f32_16x16x32_bf16 v[60:63], v[142:145], v[190:193], v[60:63]
	v_mfma_f32_16x16x32_bf16 v[56:59], v[158:161], v[190:193], v[56:59]
	s_barrier
; #define PG8_STAGE(bufoff, gbase, voff) do { _Pragma("unroll") for (int _i = 0; _i < 2; ++_i) \
;         __builtin_amdgcn_global_load_lds((const unsigned*)((const char*)(gbase) + (voff)[_i]), (PG8_LAS unsigned*)(lds + (bufoff) + ldsw + _i * 8192), 16, 0, 0); } while (0)
; #define PG8_LDA(dst, b, h) do { _Pragma("unroll") for (int m = 0; m < 4; ++m) _Pragma("unroll") for (int k = 0; k < 2; ++k) dst[m][k] = *(const PG8_LAS bf16x8*)(lds + PG8_SA(b, h) + aoff + m * 2048 + k * 1024); } while (0)
; #define PG8_LDB(dst, b, h) do { _Pragma("unroll") for (int n = 0; n < 2; ++n) _Pragma("unroll") for (int k = 0; k < 2; ++k) dst[n][k] = *(const PG8_LAS bf16x8*)(lds + PG8_SB(b, h) + boff + n * 2048 + k * 1024); } while (0)
; #define PG8_MMA(ai, bj, At, Bt) do { __builtin_amdgcn_s_setprio(1); _Pragma("unroll") for (int m = 0; m < 4; ++m) _Pragma("unroll") for (int n = 0; n < 2; ++n) _Pragma("unroll") for (int k = 0; k < 2; ++k) \
;         acc[ai][bj][m][n] = __builtin_amdgcn_mfma_f32_16x16x32_bf16(Bt[n][k], At[m][k], acc[ai][bj][m][n], 0, 0, 0); __builtin_amdgcn_s_setprio(0); } while (0)
; #define PG8_WAIT_V(n) asm volatile("s_waitcnt vmcnt(" #n ")" ::: "memory")
; #define PG8_WAIT_L(n) asm volatile("s_waitcnt lgkmcnt(" #n ")" ::: "memory")
; #define PG8_BAR __builtin_amdgcn_s_barrier()
; #define PG8_SCHED __builtin_amdgcn_sched_barrier(0)
; template <class Epi, class Sched, bool ALIGN_EPI = false, bool SP2 = false>
; __device__ __forceinline__ void gemm_phase(PG8_LAS unsigned char* lds, const Gemm g, const Sched& S, const Epi& E) {
;     ...
;             PG8_WAIT_V(8); PG8_WAIT_L(0); PG8_BAR; PG8_MMA(1, 0, At, B0); PG8_MMA(1, 1, At, B1); PG8_BAR; PG8_SCHED;
;             PG8_LDB(B0, 1, 0); PG8_LDB(B1, 1, 1); PG8_SCHED; PG8_LDA(At, 1, 0); PG8_STAGE(PG8_SA(0, 1), a2 + hstep, voffA);
;             PG8_WAIT_V(8); PG8_WAIT_L(0); PG8_BAR; PG8_MMA(0, 0, At, B0); PG8_MMA(0, 1, At, B1); PG8_BAR; PG8_SCHED;
	s_waitcnt lgkmcnt(0)
	v_mfma_f32_16x16x32_bf16 v[44:47], v[142:145], v[198:201], v[44:47]
	v_mfma_f32_16x16x32_bf16 v[40:43], v[158:161], v[198:201], v[40:43]
	v_mfma_f32_16x16x32_bf16 v[28:31], v[142:145], v[206:209], v[28:31]
	v_mfma_f32_16x16x32_bf16 v[24:27], v[158:161], v[206:209], v[24:27]
	v_mfma_f32_16x16x32_bf16 v[12:15], v[142:145], v[214:217], v[12:15]
	v_mfma_f32_16x16x32_bf16 v[8:11], v[158:161], v[214:217], v[8:11]
	v_mfma_f32_16x16x32_bf16 v[60:63], v[154:157], v[194:197], v[60:63]
	v_mfma_f32_16x16x32_bf16 v[56:59], v[162:165], v[194:197], v[56:59]
	v_mfma_f32_16x16x32_bf16 v[44:47], v[154:157], v[202:205], v[44:47]
	v_mfma_f32_16x16x32_bf16 v[40:43], v[162:165], v[202:205], v[40:43]
	v_mfma_f32_16x16x32_bf16 v[28:31], v[154:157], v[210:213], v[28:31]
	v_mfma_f32_16x16x32_bf16 v[24:27], v[162:165], v[210:213], v[24:27]
	v_mfma_f32_16x16x32_bf16 v[12:15], v[154:157], v[218:221], v[12:15]
	v_mfma_f32_16x16x32_bf16 v[8:11], v[162:165], v[218:221], v[8:11]
	v_mfma_f32_16x16x32_bf16 v[52:55], v[166:169], v[190:193], v[52:55]
	v_mfma_f32_16x16x32_bf16 v[48:51], v[182:185], v[190:193], v[48:51]
	v_mfma_f32_16x16x32_bf16 v[36:39], v[166:169], v[198:201], v[36:39]
	v_mfma_f32_16x16x32_bf16 v[32:35], v[182:185], v[198:201], v[32:35]
	v_mfma_f32_16x16x32_bf16 v[20:23], v[166:169], v[206:209], v[20:23]
	v_mfma_f32_16x16x32_bf16 v[16:19], v[182:185], v[206:209], v[16:19]
	v_mfma_f32_16x16x32_bf16 v[4:7], v[166:169], v[214:217], v[4:7]
	v_mfma_f32_16x16x32_bf16 v[0:3], v[182:185], v[214:217], v[0:3]
	v_mfma_f32_16x16x32_bf16 v[52:55], v[178:181], v[194:197], v[52:55]
	v_mfma_f32_16x16x32_bf16 v[48:51], v[186:189], v[194:197], v[48:51]
	v_mfma_f32_16x16x32_bf16 v[36:39], v[178:181], v[202:205], v[36:39]
	v_mfma_f32_16x16x32_bf16 v[32:35], v[186:189], v[202:205], v[32:35]
	v_mfma_f32_16x16x32_bf16 v[20:23], v[178:181], v[210:213], v[20:23]
	v_mfma_f32_16x16x32_bf16 v[16:19], v[186:189], v[210:213], v[16:19]
	v_mfma_f32_16x16x32_bf16 v[4:7], v[178:181], v[218:221], v[4:7]
	v_mfma_f32_16x16x32_bf16 v[0:3], v[186:189], v[218:221], v[0:3]
	s_barrier
	s_add_i32 s48, 0, 0x18000
	s_add_i32 s49, 0, 0x1c000
	v_add_u32_e32 v162, s48, v149
	v_add_u32_e32 v186, s49, v149
	ds_read_b128 v[142:145], v162
	ds_read_b128 v[154:157], v162 offset:1024
	ds_read_b128 v[158:161], v162 offset:2048
	ds_read_b128 v[162:165], v162 offset:3072
	ds_read_b128 v[166:169], v186
	ds_read_b128 v[178:181], v186 offset:1024
	ds_read_b128 v[182:185], v186 offset:2048
	ds_read_b128 v[186:189], v186 offset:3072
	s_add_u32 s22, s28, 0x80000
	s_addc_u32 s23, s29, 0
	s_mov_b32 m0, s36
	v_lshl_add_u64 v[226:227], s[22:23], 0, v[130:131]
	ds_read_b128 v[190:193], v153 offset:32768
	ds_read_b128 v[194:197], v153 offset:33792
	ds_read_b128 v[198:201], v153 offset:34816
	ds_read_b128 v[202:205], v153 offset:35840
	ds_read_b128 v[206:209], v153 offset:36864
	ds_read_b128 v[210:213], v153 offset:37888
	ds_read_b128 v[214:217], v153 offset:38912
	ds_read_b128 v[218:221], v153 offset:39936
	global_load_lds_dwordx4 v[226:227], off
	v_lshl_add_u64 v[226:227], s[22:23], 0, v[132:133]
	s_mov_b32 m0, s37
	s_nop 0
	global_load_lds_dwordx4 v[226:227], off
	s_waitcnt vmcnt(8)
	s_waitcnt lgkmcnt(0)
	v_mfma_f32_16x16x32_bf16 v[124:127], v[142:145], v[190:193], v[124:127]
	v_mfma_f32_16x16x32_bf16 v[120:123], v[158:161], v[190:193], v[120:123]
	s_barrier
	s_waitcnt lgkmcnt(0)
	v_mfma_f32_16x16x32_bf16 v[108:111], v[142:145], v[198:201], v[108:111]
	v_mfma_f32_16x16x32_bf16 v[104:107], v[158:161], v[198:201], v[104:107]
	v_mfma_f32_16x16x32_bf16 v[92:95], v[142:145], v[206:209], v[92:95]
	v_mfma_f32_16x16x32_bf16 v[88:91], v[158:161], v[206:209], v[88:91]
	v_mfma_f32_16x16x32_bf16 v[76:79], v[142:145], v[214:217], v[76:79]
	v_mfma_f32_16x16x32_bf16 v[72:75], v[158:161], v[214:217], v[72:75]
	v_mfma_f32_16x16x32_bf16 v[124:127], v[154:157], v[194:197], v[124:127]
	v_mfma_f32_16x16x32_bf16 v[120:123], v[162:165], v[194:197], v[120:123]
	v_mfma_f32_16x16x32_bf16 v[108:111], v[154:157], v[202:205], v[108:111]
	v_mfma_f32_16x16x32_bf16 v[104:107], v[162:165], v[202:205], v[104:107]
	v_mfma_f32_16x16x32_bf16 v[92:95], v[154:157], v[210:213], v[92:95]
	v_mfma_f32_16x16x32_bf16 v[88:91], v[162:165], v[210:213], v[88:91]
	v_mfma_f32_16x16x32_bf16 v[76:79], v[154:157], v[218:221], v[76:79]
	v_mfma_f32_16x16x32_bf16 v[72:75], v[162:165], v[218:221], v[72:75]
	v_mfma_f32_16x16x32_bf16 v[116:119], v[166:169], v[190:193], v[116:119]
	v_mfma_f32_16x16x32_bf16 v[112:115], v[182:185], v[190:193], v[112:115]
	v_mfma_f32_16x16x32_bf16 v[100:103], v[166:169], v[198:201], v[100:103]
	v_mfma_f32_16x16x32_bf16 v[96:99], v[182:185], v[198:201], v[96:99]
	v_mfma_f32_16x16x32_bf16 v[84:87], v[166:169], v[206:209], v[84:87]
	v_mfma_f32_16x16x32_bf16 v[80:83], v[182:185], v[206:209], v[80:83]
	v_mfma_f32_16x16x32_bf16 v[68:71], v[166:169], v[214:217], v[68:71]
	v_mfma_f32_16x16x32_bf16 v[64:67], v[182:185], v[214:217], v[64:67]
	v_mfma_f32_16x16x32_bf16 v[116:119], v[178:181], v[194:197], v[116:119]
	v_mfma_f32_16x16x32_bf16 v[112:115], v[186:189], v[194:197], v[112:115]
	v_mfma_f32_16x16x32_bf16 v[100:103], v[178:181], v[202:205], v[100:103]
	v_mfma_f32_16x16x32_bf16 v[96:99], v[186:189], v[202:205], v[96:99]
	v_mfma_f32_16x16x32_bf16 v[84:87], v[178:181], v[210:213], v[84:87]
	v_mfma_f32_16x16x32_bf16 v[80:83], v[186:189], v[210:213], v[80:83]
	v_mfma_f32_16x16x32_bf16 v[68:71], v[178:181], v[218:221], v[68:71]
	v_mfma_f32_16x16x32_bf16 v[64:67], v[186:189], v[218:221], v[64:67]
	s_barrier
; #define PG8_STAGE(bufoff, gbase, voff) do { _Pragma("unroll") for (int _i = 0; _i < 2; ++_i) \
;         __builtin_amdgcn_global_load_lds((const unsigned*)((const char*)(gbase) + (voff)[_i]), (PG8_LAS unsigned*)(lds + (bufoff) + ldsw + _i * 8192), 16, 0, 0); } while (0)
; #define PG8_LDA(dst, b, h) do { _Pragma("unroll") for (int m = 0; m < 4; ++m) _Pragma("unroll") for (int k = 0; k < 2; ++k) dst[m][k] = *(const PG8_LAS bf16x8*)(lds + PG8_SA(b, h) + aoff + m * 2048 + k * 1024); } while (0)
; #define PG8_MMA(ai, bj, At, Bt) do { __builtin_amdgcn_s_setprio(1); _Pragma("unroll") for (int m = 0; m < 4; ++m) _Pragma("unroll") for (int n = 0; n < 2; ++n) _Pragma("unroll") for (int k = 0; k < 2; ++k) \
;         acc[ai][bj][m][n] = __builtin_amdgcn_mfma_f32_16x16x32_bf16(Bt[n][k], At[m][k], acc[ai][bj][m][n], 0, 0, 0); __builtin_amdgcn_s_setprio(0); } while (0)
; #define PG8_WAIT_V(n) asm volatile("s_waitcnt vmcnt(" #n ")" ::: "memory")
; #define PG8_WAIT_L(n) asm volatile("s_waitcnt lgkmcnt(" #n ")" ::: "memory")
; #define PG8_BAR __builtin_amdgcn_s_barrier()
; #define PG8_SCHED __builtin_amdgcn_sched_barrier(0)
; template <class Epi, class Sched, bool ALIGN_EPI = false, bool SP2 = false>
; __device__ __forceinline__ void gemm_phase(PG8_LAS unsigned char* lds, const Gemm g, const Sched& S, const Epi& E) {
;     ...
;             PG8_LDA(At, 1, 1); PG8_STAGE(PG8_SB(1, 0), b3, voffB); PG8_STAGE(PG8_SB(1, 1), b3 + hstep, voffB); PG8_STAGE(PG8_SA(1, 0), a3, voffA);
;             PG8_WAIT_V(8); PG8_WAIT_L(0); PG8_BAR; PG8_MMA(1, 0, At, B0); PG8_MMA(1, 1, At, B1); PG8_BAR; PG8_SCHED;
;     ...
;         if constexpr (ALIGN_EPI) { if (wr == 0) PG8_BAR; }
	s_add_i32 s22, s48, s33
	v_lshl_add_u64 v[146:147], v[146:147], 0, s[4:5]
	s_mov_b32 m0, s22
	ds_read_b128 v[190:193], v153 offset:49152
	ds_read_b128 v[194:197], v153 offset:50176
	ds_read_b128 v[198:201], v153 offset:51200
	ds_read_b128 v[202:205], v153 offset:52224
	ds_read_b128 v[206:209], v153 offset:53248
	ds_read_b128 v[210:213], v153 offset:54272
	ds_read_b128 v[214:217], v153 offset:55296
	ds_read_b128 v[218:221], v153 offset:56320
	global_load_lds_dwordx4 v[146:147], off
	s_add_i32 m0, s22, 0x2000
	s_add_u32 s22, s26, 0x80080
	v_lshl_add_u64 v[146:147], v[170:171], 0, s[4:5]
	s_addc_u32 s23, s27, 0
	s_add_i32 s26, s49, s33
	global_load_lds_dwordx4 v[146:147], off
	v_lshl_add_u64 v[146:147], s[22:23], 0, v[130:131]
	s_mov_b32 m0, s26
	s_nop 0
	global_load_lds_dwordx4 v[146:147], off
	v_lshl_add_u64 v[146:147], s[22:23], 0, v[132:133]
	s_add_i32 m0, s26, 0x2000
	s_nop 0
	global_load_lds_dwordx4 v[146:147], off
	v_lshl_add_u64 v[146:147], v[222:223], 0, s[4:5]
	s_mov_b32 m0, s39
	s_nop 0
	global_load_lds_dwordx4 v[146:147], off
	v_lshl_add_u64 v[146:147], v[224:225], 0, s[4:5]
	s_mov_b32 m0, s40
	s_nop 0
	global_load_lds_dwordx4 v[146:147], off
	s_waitcnt vmcnt(8)
	s_waitcnt lgkmcnt(0)
	v_mfma_f32_16x16x32_bf16 v[60:63], v[142:145], v[190:193], v[60:63]
	v_mfma_f32_16x16x32_bf16 v[56:59], v[158:161], v[190:193], v[56:59]
	s_barrier
	s_waitcnt lgkmcnt(0)
	v_mfma_f32_16x16x32_bf16 v[44:47], v[142:145], v[198:201], v[44:47]
	v_mfma_f32_16x16x32_bf16 v[40:43], v[158:161], v[198:201], v[40:43]
	v_mfma_f32_16x16x32_bf16 v[28:31], v[142:145], v[206:209], v[28:31]
	v_mfma_f32_16x16x32_bf16 v[24:27], v[158:161], v[206:209], v[24:27]
	v_mfma_f32_16x16x32_bf16 v[12:15], v[142:145], v[214:217], v[12:15]
	v_mfma_f32_16x16x32_bf16 v[8:11], v[158:161], v[214:217], v[8:11]
	v_mfma_f32_16x16x32_bf16 v[60:63], v[154:157], v[194:197], v[60:63]
	v_mfma_f32_16x16x32_bf16 v[56:59], v[162:165], v[194:197], v[56:59]
	v_mfma_f32_16x16x32_bf16 v[44:47], v[154:157], v[202:205], v[44:47]
	v_mfma_f32_16x16x32_bf16 v[40:43], v[162:165], v[202:205], v[40:43]
	v_mfma_f32_16x16x32_bf16 v[28:31], v[154:157], v[210:213], v[28:31]
	v_mfma_f32_16x16x32_bf16 v[24:27], v[162:165], v[210:213], v[24:27]
	v_mfma_f32_16x16x32_bf16 v[12:15], v[154:157], v[218:221], v[12:15]
	v_mfma_f32_16x16x32_bf16 v[8:11], v[162:165], v[218:221], v[8:11]
	v_mfma_f32_16x16x32_bf16 v[52:55], v[166:169], v[190:193], v[52:55]
	v_mfma_f32_16x16x32_bf16 v[48:51], v[182:185], v[190:193], v[48:51]
	v_mfma_f32_16x16x32_bf16 v[36:39], v[166:169], v[198:201], v[36:39]
	v_mfma_f32_16x16x32_bf16 v[32:35], v[182:185], v[198:201], v[32:35]
	v_mfma_f32_16x16x32_bf16 v[20:23], v[166:169], v[206:209], v[20:23]
	v_mfma_f32_16x16x32_bf16 v[16:19], v[182:185], v[206:209], v[16:19]
	v_mfma_f32_16x16x32_bf16 v[4:7], v[166:169], v[214:217], v[4:7]
	v_mfma_f32_16x16x32_bf16 v[0:3], v[182:185], v[214:217], v[0:3]
	v_mfma_f32_16x16x32_bf16 v[52:55], v[178:181], v[194:197], v[52:55]
	v_mfma_f32_16x16x32_bf16 v[48:51], v[186:189], v[194:197], v[48:51]
	v_mfma_f32_16x16x32_bf16 v[36:39], v[178:181], v[202:205], v[36:39]
	v_mfma_f32_16x16x32_bf16 v[32:35], v[186:189], v[202:205], v[32:35]
	v_mfma_f32_16x16x32_bf16 v[20:23], v[178:181], v[210:213], v[20:23]
	v_mfma_f32_16x16x32_bf16 v[16:19], v[186:189], v[210:213], v[16:19]
	v_mfma_f32_16x16x32_bf16 v[4:7], v[178:181], v[218:221], v[4:7]
	v_mfma_f32_16x16x32_bf16 v[0:3], v[186:189], v[218:221], v[0:3]
	s_barrier
	s_add_i32 s47, s47, 2
	s_add_u32 s45, s45, 0x100
	s_addc_u32 s46, s46, 0
	s_cmp_gt_u32 s47, 29
	s_mov_b64 s[22:23], s[24:25]
	s_cbranch_scc0 .LBB0_1457
	s_and_b64 vcc, exec, s[6:7]
	s_cbranch_vccz .LBB0_1460
	s_barrier

; #define PG8_STAGE(bufoff, gbase, voff) do { _Pragma("unroll") for (int _i = 0; _i < 2; ++_i) \
;         __builtin_amdgcn_global_load_lds((const unsigned*)((const char*)(gbase) + (voff)[_i]), (PG8_LAS unsigned*)(lds + (bufoff) + ldsw + _i * 8192), 16, 0, 0); } while (0)
; #define PG8_LDA(dst, b, h) do { _Pragma("unroll") for (int m = 0; m < 4; ++m) _Pragma("unroll") for (int k = 0; k < 2; ++k) dst[m][k] = *(const PG8_LAS bf16x8*)(lds + PG8_SA(b, h) + aoff + m * 2048 + k * 1024); } while (0)
; #define PG8_LDB(dst, b, h) do { _Pragma("unroll") for (int n = 0; n < 2; ++n) _Pragma("unroll") for (int k = 0; k < 2; ++k) dst[n][k] = *(const PG8_LAS bf16x8*)(lds + PG8_SB(b, h) + boff + n * 2048 + k * 1024); } while (0)
; #define PG8_MMA(ai, bj, At, Bt) do { __builtin_amdgcn_s_setprio(1); _Pragma("unroll") for (int m = 0; m < 4; ++m) _Pragma("unroll") for (int n = 0; n < 2; ++n) _Pragma("unroll") for (int k = 0; k < 2; ++k) \
;         acc[ai][bj][m][n] = __builtin_amdgcn_mfma_f32_16x16x32_bf16(Bt[n][k], At[m][k], acc[ai][bj][m][n], 0, 0, 0); __builtin_amdgcn_s_setprio(0); } while (0)
; #define PG8_WAIT_V(n) asm volatile("s_waitcnt vmcnt(" #n ")" ::: "memory")
; #define PG8_WAIT_L(n) asm volatile("s_waitcnt lgkmcnt(" #n ")" ::: "memory")
; #define PG8_BAR __builtin_amdgcn_s_barrier()
; #define PG8_SCHED __builtin_amdgcn_sched_barrier(0)
; template <class Epi, class Sched, bool ALIGN_EPI = false, bool SP2 = false>
; __device__ __forceinline__ void gemm_phase(PG8_LAS unsigned char* lds, const Gemm g, const Sched& S, const Epi& E) {
;     ...
;             PG8_LDB(B0, 0, 0); PG8_LDB(B1, 0, 1); PG8_SCHED; PG8_LDA(At, 0, 0); PG8_STAGE(PG8_SA(1, 1), a1 + hstep, voffA);
;             PG8_WAIT_V(8); PG8_WAIT_L(0); PG8_BAR; PG8_MMA(0, 0, At, B0); PG8_MMA(0, 1, At, B1); PG8_BAR; PG8_SCHED;
;             PG8_LDA(At, 0, 1); PG8_STAGE(PG8_SB(0, 0), b2, voffB); PG8_STAGE(PG8_SB(0, 1), b2 + hstep, voffB); PG8_STAGE(PG8_SA(0, 0), a2, voffA);
;             PG8_WAIT_V(8); PG8_WAIT_L(0); PG8_BAR; PG8_MMA(1, 0, At, B0); PG8_MMA(1, 1, At, B1); PG8_BAR; PG8_SCHED;
.LBB0_1712:
	ds_read_b128 v[144:147], v156
	ds_read_b128 v[148:151], v156 offset:1024
	ds_read_b128 v[160:163], v156 offset:2048
	ds_read_b128 v[164:167], v156 offset:3072
	ds_read_b128 v[168:171], v157
	ds_read_b128 v[174:177], v157 offset:1024
	ds_read_b128 v[178:181], v157 offset:2048
	ds_read_b128 v[182:185], v157 offset:3072
	s_add_u32 s20, s18, 0xfff80080
	s_addc_u32 s21, s19, -1
	s_cmp_eq_u32 s44, 28
	s_cselect_b32 s23, s11, s21
	s_cselect_b32 s22, s40, s20
	s_cselect_b32 s21, s9, s43
	s_cselect_b32 s20, s41, s42
	v_lshl_add_u64 v[218:219], s[18:19], 0, v[136:137]
	s_add_i32 m0, s17, 0xc000
	ds_read_b128 v[186:189], v158
	ds_read_b128 v[190:193], v158 offset:1024
	ds_read_b128 v[194:197], v158 offset:2048
	ds_read_b128 v[198:201], v158 offset:3072
	ds_read_b128 v[202:205], v158 offset:4096
	ds_read_b128 v[206:209], v158 offset:5120
	ds_read_b128 v[210:213], v158 offset:6144
	ds_read_b128 v[214:217], v158 offset:7168
	global_load_lds_dwordx4 v[218:219], off
	v_lshl_add_u64 v[218:219], s[18:19], 0, v[138:139]
	s_add_i32 m0, s17, 0xe000
	s_nop 0
	global_load_lds_dwordx4 v[218:219], off
	s_waitcnt vmcnt(8)
	s_waitcnt lgkmcnt(0)
	v_mfma_f32_16x16x32_bf16 v[124:127], v[144:147], v[186:189], v[124:127]
	v_mfma_f32_16x16x32_bf16 v[120:123], v[160:163], v[186:189], v[120:123]
	s_barrier
	s_waitcnt lgkmcnt(0)
	v_mfma_f32_16x16x32_bf16 v[108:111], v[144:147], v[194:197], v[108:111]
	v_mfma_f32_16x16x32_bf16 v[104:107], v[160:163], v[194:197], v[104:107]
	v_mfma_f32_16x16x32_bf16 v[92:95], v[144:147], v[202:205], v[92:95]
	v_mfma_f32_16x16x32_bf16 v[88:91], v[160:163], v[202:205], v[88:91]
	v_mfma_f32_16x16x32_bf16 v[76:79], v[144:147], v[210:213], v[76:79]
	v_mfma_f32_16x16x32_bf16 v[72:75], v[160:163], v[210:213], v[72:75]
	v_mfma_f32_16x16x32_bf16 v[124:127], v[148:151], v[190:193], v[124:127]
	v_mfma_f32_16x16x32_bf16 v[120:123], v[164:167], v[190:193], v[120:123]
	v_mfma_f32_16x16x32_bf16 v[108:111], v[148:151], v[198:201], v[108:111]
	v_mfma_f32_16x16x32_bf16 v[104:107], v[164:167], v[198:201], v[104:107]
	v_mfma_f32_16x16x32_bf16 v[92:95], v[148:151], v[206:209], v[92:95]
	v_mfma_f32_16x16x32_bf16 v[88:91], v[164:167], v[206:209], v[88:91]
	v_mfma_f32_16x16x32_bf16 v[76:79], v[148:151], v[214:217], v[76:79]
	v_mfma_f32_16x16x32_bf16 v[72:75], v[164:167], v[214:217], v[72:75]
	v_mfma_f32_16x16x32_bf16 v[116:119], v[168:171], v[186:189], v[116:119]
	v_mfma_f32_16x16x32_bf16 v[112:115], v[178:181], v[186:189], v[112:115]
	v_mfma_f32_16x16x32_bf16 v[100:103], v[168:171], v[194:197], v[100:103]
	v_mfma_f32_16x16x32_bf16 v[96:99], v[178:181], v[194:197], v[96:99]
	v_mfma_f32_16x16x32_bf16 v[84:87], v[168:171], v[202:205], v[84:87]
	v_mfma_f32_16x16x32_bf16 v[80:83], v[178:181], v[202:205], v[80:83]
	v_mfma_f32_16x16x32_bf16 v[68:71], v[168:171], v[210:213], v[68:71]
	v_mfma_f32_16x16x32_bf16 v[64:67], v[178:181], v[210:213], v[64:67]
	v_mfma_f32_16x16x32_bf16 v[116:119], v[174:177], v[190:193], v[116:119]
	v_mfma_f32_16x16x32_bf16 v[112:115], v[182:185], v[190:193], v[112:115]
	v_mfma_f32_16x16x32_bf16 v[100:103], v[174:177], v[198:201], v[100:103]
	v_mfma_f32_16x16x32_bf16 v[96:99], v[182:185], v[198:201], v[96:99]
	v_mfma_f32_16x16x32_bf16 v[84:87], v[174:177], v[206:209], v[84:87]
	v_mfma_f32_16x16x32_bf16 v[80:83], v[182:185], v[206:209], v[80:83]
	v_mfma_f32_16x16x32_bf16 v[68:71], v[174:177], v[214:217], v[68:71]
	v_mfma_f32_16x16x32_bf16 v[64:67], v[182:185], v[214:217], v[64:67]
	s_barrier
	s_add_i32 s45, s34, s26
	v_lshl_add_u64 v[218:219], s[20:21], 0, v[132:133]
	s_mov_b32 m0, s45
	ds_read_b128 v[186:189], v158 offset:16384
	ds_read_b128 v[190:193], v158 offset:17408
	ds_read_b128 v[194:197], v158 offset:18432
	ds_read_b128 v[198:201], v158 offset:19456
	ds_read_b128 v[202:205], v158 offset:20480
	ds_read_b128 v[206:209], v158 offset:21504
	ds_read_b128 v[210:213], v158 offset:22528
	ds_read_b128 v[214:217], v158 offset:23552
	global_load_lds_dwordx4 v[218:219], off
	s_add_i32 m0, s45, 0x2000
	s_add_u32 s46, s20, 0x80000
	v_lshl_add_u64 v[220:221], s[20:21], 0, v[128:129]
	s_addc_u32 s47, s21, 0
	s_add_i32 s45, s35, s26
	global_load_lds_dwordx4 v[220:221], off
	v_lshl_add_u64 v[222:223], s[46:47], 0, v[132:133]
	s_mov_b32 m0, s45
	v_lshl_add_u64 v[224:225], s[22:23], 0, v[130:131]
	global_load_lds_dwordx4 v[222:223], off
	v_lshl_add_u64 v[222:223], s[46:47], 0, v[128:129]
	s_add_i32 m0, s45, 0x2000
	s_nop 0
	global_load_lds_dwordx4 v[222:223], off
	v_lshl_add_u64 v[222:223], s[22:23], 0, v[134:135]
	s_mov_b32 m0, s17
	s_nop 0
	global_load_lds_dwordx4 v[222:223], off
	s_mov_b32 m0, s28
	s_nop 0
	global_load_lds_dwordx4 v[224:225], off
	s_waitcnt vmcnt(8)
	s_waitcnt lgkmcnt(0)
	v_mfma_f32_16x16x32_bf16 v[60:63], v[144:147], v[186:189], v[60:63]
	v_mfma_f32_16x16x32_bf16 v[56:59], v[160:163], v[186:189], v[56:59]
	s_barrier
; #define PG8_STAGE(bufoff, gbase, voff) do { _Pragma("unroll") for (int _i = 0; _i < 2; ++_i) \
;         __builtin_amdgcn_global_load_lds((const unsigned*)((const char*)(gbase) + (voff)[_i]), (PG8_LAS unsigned*)(lds + (bufoff) + ldsw + _i * 8192), 16, 0, 0); } while (0)
; #define PG8_LDA(dst, b, h) do { _Pragma("unroll") for (int m = 0; m < 4; ++m) _Pragma("unroll") for (int k = 0; k < 2; ++k) dst[m][k] = *(const PG8_LAS bf16x8*)(lds + PG8_SA(b, h) + aoff + m * 2048 + k * 1024); } while (0)
; #define PG8_LDB(dst, b, h) do { _Pragma("unroll") for (int n = 0; n < 2; ++n) _Pragma("unroll") for (int k = 0; k < 2; ++k) dst[n][k] = *(const PG8_LAS bf16x8*)(lds + PG8_SB(b, h) + boff + n * 2048 + k * 1024); } while (0)
; #define PG8_MMA(ai, bj, At, Bt) do { __builtin_amdgcn_s_setprio(1); _Pragma("unroll") for (int m = 0; m < 4; ++m) _Pragma("unroll") for (int n = 0; n < 2; ++n) _Pragma("unroll") for (int k = 0; k < 2; ++k) \
;         acc[ai][bj][m][n] = __builtin_amdgcn_mfma_f32_16x16x32_bf16(Bt[n][k], At[m][k], acc[ai][bj][m][n], 0, 0, 0); __builtin_amdgcn_s_setprio(0); } while (0)
; #define PG8_WAIT_V(n) asm volatile("s_waitcnt vmcnt(" #n ")" ::: "memory")
; #define PG8_WAIT_L(n) asm volatile("s_waitcnt lgkmcnt(" #n ")" ::: "memory")
; #define PG8_BAR __builtin_amdgcn_s_barrier()
; #define PG8_SCHED __builtin_amdgcn_sched_barrier(0)
; template <class Epi, class Sched, bool ALIGN_EPI = false, bool SP2 = false>
; __device__ __forceinline__ void gemm_phase(PG8_LAS unsigned char* lds, const Gemm g, const Sched& S, const Epi& E) {
;     ...
;             PG8_WAIT_V(8); PG8_WAIT_L(0); PG8_BAR; PG8_MMA(1, 0, At, B0); PG8_MMA(1, 1, At, B1); PG8_BAR; PG8_SCHED;
;             PG8_LDB(B0, 1, 0); PG8_LDB(B1, 1, 1); PG8_SCHED; PG8_LDA(At, 1, 0); PG8_STAGE(PG8_SA(0, 1), a2 + hstep, voffA);
;             PG8_WAIT_V(8); PG8_WAIT_L(0); PG8_BAR; PG8_MMA(0, 0, At, B0); PG8_MMA(0, 1, At, B1); PG8_BAR; PG8_SCHED;
	s_waitcnt lgkmcnt(0)
	v_mfma_f32_16x16x32_bf16 v[44:47], v[144:147], v[194:197], v[44:47]
	v_mfma_f32_16x16x32_bf16 v[40:43], v[160:163], v[194:197], v[40:43]
	v_mfma_f32_16x16x32_bf16 v[28:31], v[144:147], v[202:205], v[28:31]
	v_mfma_f32_16x16x32_bf16 v[24:27], v[160:163], v[202:205], v[24:27]
	v_mfma_f32_16x16x32_bf16 v[12:15], v[144:147], v[210:213], v[12:15]
	v_mfma_f32_16x16x32_bf16 v[8:11], v[160:163], v[210:213], v[8:11]
	v_mfma_f32_16x16x32_bf16 v[60:63], v[148:151], v[190:193], v[60:63]
	v_mfma_f32_16x16x32_bf16 v[56:59], v[164:167], v[190:193], v[56:59]
	v_mfma_f32_16x16x32_bf16 v[44:47], v[148:151], v[198:201], v[44:47]
	v_mfma_f32_16x16x32_bf16 v[40:43], v[164:167], v[198:201], v[40:43]
	v_mfma_f32_16x16x32_bf16 v[28:31], v[148:151], v[206:209], v[28:31]
	v_mfma_f32_16x16x32_bf16 v[24:27], v[164:167], v[206:209], v[24:27]
	v_mfma_f32_16x16x32_bf16 v[12:15], v[148:151], v[214:217], v[12:15]
	v_mfma_f32_16x16x32_bf16 v[8:11], v[164:167], v[214:217], v[8:11]
	v_mfma_f32_16x16x32_bf16 v[52:55], v[168:171], v[186:189], v[52:55]
	v_mfma_f32_16x16x32_bf16 v[48:51], v[178:181], v[186:189], v[48:51]
	v_mfma_f32_16x16x32_bf16 v[36:39], v[168:171], v[194:197], v[36:39]
	v_mfma_f32_16x16x32_bf16 v[32:35], v[178:181], v[194:197], v[32:35]
	v_mfma_f32_16x16x32_bf16 v[20:23], v[168:171], v[202:205], v[20:23]
	v_mfma_f32_16x16x32_bf16 v[16:19], v[178:181], v[202:205], v[16:19]
	v_mfma_f32_16x16x32_bf16 v[4:7], v[168:171], v[210:213], v[4:7]
	v_mfma_f32_16x16x32_bf16 v[0:3], v[178:181], v[210:213], v[0:3]
	v_mfma_f32_16x16x32_bf16 v[52:55], v[174:177], v[190:193], v[52:55]
	v_mfma_f32_16x16x32_bf16 v[48:51], v[182:185], v[190:193], v[48:51]
	v_mfma_f32_16x16x32_bf16 v[36:39], v[174:177], v[198:201], v[36:39]
	v_mfma_f32_16x16x32_bf16 v[32:35], v[182:185], v[198:201], v[32:35]
	v_mfma_f32_16x16x32_bf16 v[20:23], v[174:177], v[206:209], v[20:23]
	v_mfma_f32_16x16x32_bf16 v[16:19], v[182:185], v[206:209], v[16:19]
	v_mfma_f32_16x16x32_bf16 v[4:7], v[174:177], v[214:217], v[4:7]
	v_mfma_f32_16x16x32_bf16 v[0:3], v[182:185], v[214:217], v[0:3]
	s_barrier
	s_add_i32 s45, 0, 0x18000
	v_add_u32_e32 v159, s45, v153
	s_add_i32 s46, 0, 0x1c000
	ds_read_b128 v[144:147], v159
	ds_read_b128 v[148:151], v159 offset:1024
	ds_read_b128 v[160:163], v159 offset:2048
	ds_read_b128 v[164:167], v159 offset:3072
	v_add_u32_e32 v159, s46, v153
	ds_read_b128 v[168:171], v159
	ds_read_b128 v[174:177], v159 offset:1024
	ds_read_b128 v[178:181], v159 offset:2048
	ds_read_b128 v[182:185], v159 offset:3072
	s_add_u32 s22, s22, 0x80000
	s_addc_u32 s23, s23, 0
	s_mov_b32 m0, s29
	v_lshl_add_u64 v[226:227], s[22:23], 0, v[134:135]
	ds_read_b128 v[186:189], v158 offset:32768
	ds_read_b128 v[190:193], v158 offset:33792
	ds_read_b128 v[194:197], v158 offset:34816
	ds_read_b128 v[198:201], v158 offset:35840
	ds_read_b128 v[202:205], v158 offset:36864
	ds_read_b128 v[206:209], v158 offset:37888
	ds_read_b128 v[210:213], v158 offset:38912
	ds_read_b128 v[214:217], v158 offset:39936
	global_load_lds_dwordx4 v[226:227], off
	v_lshl_add_u64 v[226:227], s[22:23], 0, v[130:131]
	s_mov_b32 m0, s30
	s_nop 0
	global_load_lds_dwordx4 v[226:227], off
	s_waitcnt vmcnt(8)
	s_waitcnt lgkmcnt(0)
	v_mfma_f32_16x16x32_bf16 v[124:127], v[144:147], v[186:189], v[124:127]
	v_mfma_f32_16x16x32_bf16 v[120:123], v[160:163], v[186:189], v[120:123]
	s_barrier
	s_waitcnt lgkmcnt(0)
	v_mfma_f32_16x16x32_bf16 v[108:111], v[144:147], v[194:197], v[108:111]
	v_mfma_f32_16x16x32_bf16 v[104:107], v[160:163], v[194:197], v[104:107]
	v_mfma_f32_16x16x32_bf16 v[92:95], v[144:147], v[202:205], v[92:95]
	v_mfma_f32_16x16x32_bf16 v[88:91], v[160:163], v[202:205], v[88:91]
	v_mfma_f32_16x16x32_bf16 v[76:79], v[144:147], v[210:213], v[76:79]
	v_mfma_f32_16x16x32_bf16 v[72:75], v[160:163], v[210:213], v[72:75]
	v_mfma_f32_16x16x32_bf16 v[124:127], v[148:151], v[190:193], v[124:127]
	v_mfma_f32_16x16x32_bf16 v[120:123], v[164:167], v[190:193], v[120:123]
	v_mfma_f32_16x16x32_bf16 v[108:111], v[148:151], v[198:201], v[108:111]
	v_mfma_f32_16x16x32_bf16 v[104:107], v[164:167], v[198:201], v[104:107]
	v_mfma_f32_16x16x32_bf16 v[92:95], v[148:151], v[206:209], v[92:95]
	v_mfma_f32_16x16x32_bf16 v[88:91], v[164:167], v[206:209], v[88:91]
	v_mfma_f32_16x16x32_bf16 v[76:79], v[148:151], v[214:217], v[76:79]
	v_mfma_f32_16x16x32_bf16 v[72:75], v[164:167], v[214:217], v[72:75]
	v_mfma_f32_16x16x32_bf16 v[116:119], v[168:171], v[186:189], v[116:119]
	v_mfma_f32_16x16x32_bf16 v[112:115], v[178:181], v[186:189], v[112:115]
	v_mfma_f32_16x16x32_bf16 v[100:103], v[168:171], v[194:197], v[100:103]
	v_mfma_f32_16x16x32_bf16 v[96:99], v[178:181], v[194:197], v[96:99]
	v_mfma_f32_16x16x32_bf16 v[84:87], v[168:171], v[202:205], v[84:87]
	v_mfma_f32_16x16x32_bf16 v[80:83], v[178:181], v[202:205], v[80:83]
	v_mfma_f32_16x16x32_bf16 v[68:71], v[168:171], v[210:213], v[68:71]
	v_mfma_f32_16x16x32_bf16 v[64:67], v[178:181], v[210:213], v[64:67]
	v_mfma_f32_16x16x32_bf16 v[116:119], v[174:177], v[190:193], v[116:119]
	v_mfma_f32_16x16x32_bf16 v[112:115], v[182:185], v[190:193], v[112:115]
	v_mfma_f32_16x16x32_bf16 v[100:103], v[174:177], v[198:201], v[100:103]
	v_mfma_f32_16x16x32_bf16 v[96:99], v[182:185], v[198:201], v[96:99]
	v_mfma_f32_16x16x32_bf16 v[84:87], v[174:177], v[206:209], v[84:87]
	v_mfma_f32_16x16x32_bf16 v[80:83], v[182:185], v[206:209], v[80:83]
	v_mfma_f32_16x16x32_bf16 v[68:71], v[174:177], v[214:217], v[68:71]
	v_mfma_f32_16x16x32_bf16 v[64:67], v[182:185], v[214:217], v[64:67]
	s_barrier
; #define PG8_STAGE(bufoff, gbase, voff) do { _Pragma("unroll") for (int _i = 0; _i < 2; ++_i) \
;         __builtin_amdgcn_global_load_lds((const unsigned*)((const char*)(gbase) + (voff)[_i]), (PG8_LAS unsigned*)(lds + (bufoff) + ldsw + _i * 8192), 16, 0, 0); } while (0)
; #define PG8_LDA(dst, b, h) do { _Pragma("unroll") for (int m = 0; m < 4; ++m) _Pragma("unroll") for (int k = 0; k < 2; ++k) dst[m][k] = *(const PG8_LAS bf16x8*)(lds + PG8_SA(b, h) + aoff + m * 2048 + k * 1024); } while (0)
; #define PG8_MMA(ai, bj, At, Bt) do { __builtin_amdgcn_s_setprio(1); _Pragma("unroll") for (int m = 0; m < 4; ++m) _Pragma("unroll") for (int n = 0; n < 2; ++n) _Pragma("unroll") for (int k = 0; k < 2; ++k) \
;         acc[ai][bj][m][n] = __builtin_amdgcn_mfma_f32_16x16x32_bf16(Bt[n][k], At[m][k], acc[ai][bj][m][n], 0, 0, 0); __builtin_amdgcn_s_setprio(0); } while (0)
; #define PG8_WAIT_V(n) asm volatile("s_waitcnt vmcnt(" #n ")" ::: "memory")
; #define PG8_WAIT_L(n) asm volatile("s_waitcnt lgkmcnt(" #n ")" ::: "memory")
; #define PG8_BAR __builtin_amdgcn_s_barrier()
; #define PG8_SCHED __builtin_amdgcn_sched_barrier(0)
; template <class Epi, class Sched, bool ALIGN_EPI = false, bool SP2 = false>
; __device__ __forceinline__ void gemm_phase(PG8_LAS unsigned char* lds, const Gemm g, const Sched& S, const Epi& E) {
;     ...
;             PG8_LDA(At, 1, 1); PG8_STAGE(PG8_SB(1, 0), b3, voffB); PG8_STAGE(PG8_SB(1, 1), b3 + hstep, voffB); PG8_STAGE(PG8_SA(1, 0), a3, voffA);
;             PG8_WAIT_V(8); PG8_WAIT_L(0); PG8_BAR; PG8_MMA(1, 0, At, B0); PG8_MMA(1, 1, At, B1); PG8_BAR; PG8_SCHED;
	s_add_i32 s22, s45, s26
	v_lshl_add_u64 v[218:219], v[218:219], 0, s[2:3]
	s_mov_b32 m0, s22
	ds_read_b128 v[186:189], v158 offset:49152
	ds_read_b128 v[190:193], v158 offset:50176
	ds_read_b128 v[194:197], v158 offset:51200
	ds_read_b128 v[198:201], v158 offset:52224
	ds_read_b128 v[202:205], v158 offset:53248
	ds_read_b128 v[206:209], v158 offset:54272
	ds_read_b128 v[210:213], v158 offset:55296
	ds_read_b128 v[214:217], v158 offset:56320
	global_load_lds_dwordx4 v[218:219], off
	s_add_i32 m0, s22, 0x2000
	s_add_u32 s20, s20, 0x80080
	v_lshl_add_u64 v[218:219], v[220:221], 0, s[2:3]
	s_addc_u32 s21, s21, 0
	s_add_i32 s22, s46, s26
	global_load_lds_dwordx4 v[218:219], off
	v_lshl_add_u64 v[218:219], s[20:21], 0, v[132:133]
	s_mov_b32 m0, s22
	s_nop 0
	global_load_lds_dwordx4 v[218:219], off
	v_lshl_add_u64 v[218:219], s[20:21], 0, v[128:129]
	s_add_i32 m0, s22, 0x2000
	s_nop 0
	global_load_lds_dwordx4 v[218:219], off
	v_lshl_add_u64 v[218:219], v[222:223], 0, s[2:3]
	s_mov_b32 m0, s31
	s_nop 0
	global_load_lds_dwordx4 v[218:219], off
	v_lshl_add_u64 v[218:219], v[224:225], 0, s[2:3]
	s_mov_b32 m0, s33
	s_nop 0
	global_load_lds_dwordx4 v[218:219], off
	s_waitcnt vmcnt(8)
	s_waitcnt lgkmcnt(0)
	v_mfma_f32_16x16x32_bf16 v[60:63], v[144:147], v[186:189], v[60:63]
	v_mfma_f32_16x16x32_bf16 v[56:59], v[160:163], v[186:189], v[56:59]
	s_barrier
	s_waitcnt lgkmcnt(0)
	v_mfma_f32_16x16x32_bf16 v[44:47], v[144:147], v[194:197], v[44:47]
	v_mfma_f32_16x16x32_bf16 v[40:43], v[160:163], v[194:197], v[40:43]
	v_mfma_f32_16x16x32_bf16 v[28:31], v[144:147], v[202:205], v[28:31]
	v_mfma_f32_16x16x32_bf16 v[24:27], v[160:163], v[202:205], v[24:27]
	v_mfma_f32_16x16x32_bf16 v[12:15], v[144:147], v[210:213], v[12:15]
	v_mfma_f32_16x16x32_bf16 v[8:11], v[160:163], v[210:213], v[8:11]
	v_mfma_f32_16x16x32_bf16 v[60:63], v[148:151], v[190:193], v[60:63]
	v_mfma_f32_16x16x32_bf16 v[56:59], v[164:167], v[190:193], v[56:59]
	v_mfma_f32_16x16x32_bf16 v[44:47], v[148:151], v[198:201], v[44:47]
	v_mfma_f32_16x16x32_bf16 v[40:43], v[164:167], v[198:201], v[40:43]
	v_mfma_f32_16x16x32_bf16 v[28:31], v[148:151], v[206:209], v[28:31]
	v_mfma_f32_16x16x32_bf16 v[24:27], v[164:167], v[206:209], v[24:27]
	v_mfma_f32_16x16x32_bf16 v[12:15], v[148:151], v[214:217], v[12:15]
	v_mfma_f32_16x16x32_bf16 v[8:11], v[164:167], v[214:217], v[8:11]
	v_mfma_f32_16x16x32_bf16 v[52:55], v[168:171], v[186:189], v[52:55]
	v_mfma_f32_16x16x32_bf16 v[48:51], v[178:181], v[186:189], v[48:51]
	v_mfma_f32_16x16x32_bf16 v[36:39], v[168:171], v[194:197], v[36:39]
	v_mfma_f32_16x16x32_bf16 v[32:35], v[178:181], v[194:197], v[32:35]
	v_mfma_f32_16x16x32_bf16 v[20:23], v[168:171], v[202:205], v[20:23]
	v_mfma_f32_16x16x32_bf16 v[16:19], v[178:181], v[202:205], v[16:19]
	v_mfma_f32_16x16x32_bf16 v[4:7], v[168:171], v[210:213], v[4:7]
	v_mfma_f32_16x16x32_bf16 v[0:3], v[178:181], v[210:213], v[0:3]
	v_mfma_f32_16x16x32_bf16 v[52:55], v[174:177], v[190:193], v[52:55]
	v_mfma_f32_16x16x32_bf16 v[48:51], v[182:185], v[190:193], v[48:51]
	v_mfma_f32_16x16x32_bf16 v[36:39], v[174:177], v[198:201], v[36:39]
	v_mfma_f32_16x16x32_bf16 v[32:35], v[182:185], v[198:201], v[32:35]
	v_mfma_f32_16x16x32_bf16 v[20:23], v[174:177], v[206:209], v[20:23]
	v_mfma_f32_16x16x32_bf16 v[16:19], v[182:185], v[206:209], v[16:19]
	v_mfma_f32_16x16x32_bf16 v[4:7], v[174:177], v[214:217], v[4:7]
	v_mfma_f32_16x16x32_bf16 v[0:3], v[182:185], v[214:217], v[0:3]
	s_barrier
	s_add_i32 s44, s44, 2
	s_add_u32 s18, s18, 0x100
	s_addc_u32 s19, s19, 0
	s_add_u32 s42, s42, 0x100
	s_addc_u32 s43, s43, 0
	s_cmp_gt_u32 s44, 29
	s_cbranch_scc0 .LBB0_1712
	s_and_b64 vcc, exec, s[6:7]
	s_cbranch_vccz .LBB0_1715
	s_barrier

; #define PG8_STAGE(bufoff, gbase, voff) do { _Pragma("unroll") for (int _i = 0; _i < 2; ++_i) \
;         __builtin_amdgcn_global_load_lds((const unsigned*)((const char*)(gbase) + (voff)[_i]), (PG8_LAS unsigned*)(lds + (bufoff) + ldsw + _i * 8192), 16, 0, 0); } while (0)
; #define PG8_LDA(dst, b, h) do { _Pragma("unroll") for (int m = 0; m < 4; ++m) _Pragma("unroll") for (int k = 0; k < 2; ++k) dst[m][k] = *(const PG8_LAS bf16x8*)(lds + PG8_SA(b, h) + aoff + m * 2048 + k * 1024); } while (0)
; #define PG8_LDB(dst, b, h) do { _Pragma("unroll") for (int n = 0; n < 2; ++n) _Pragma("unroll") for (int k = 0; k < 2; ++k) dst[n][k] = *(const PG8_LAS bf16x8*)(lds + PG8_SB(b, h) + boff + n * 2048 + k * 1024); } while (0)
; #define PG8_MMA(ai, bj, At, Bt) do { __builtin_amdgcn_s_setprio(1); _Pragma("unroll") for (int m = 0; m < 4; ++m) _Pragma("unroll") for (int n = 0; n < 2; ++n) _Pragma("unroll") for (int k = 0; k < 2; ++k) \
;         acc[ai][bj][m][n] = __builtin_amdgcn_mfma_f32_16x16x32_bf16(Bt[n][k], At[m][k], acc[ai][bj][m][n], 0, 0, 0); __builtin_amdgcn_s_setprio(0); } while (0)
; #define PG8_WAIT_V(n) asm volatile("s_waitcnt vmcnt(" #n ")" ::: "memory")
; #define PG8_WAIT_L(n) asm volatile("s_waitcnt lgkmcnt(" #n ")" ::: "memory")
; template <class Epi, class Sched, bool ALIGN_EPI = false, bool SP2 = false>
; __device__ __forceinline__ void gemm_phase(PG8_LAS unsigned char* lds, const Gemm g, const Sched& S, const Epi& E) {
;     ...
;             const bool last = (t == nt - 2);
;             const char* a1 = cA + (size_t)(t + 1) * kstep;
;             const char* a2 = last ? nA : cA + (size_t)(t + 2) * kstep; const char* b2 = last ? nB : cB + (size_t)(t + 2) * kstep;
;             const char* a3 = a2 + kstep; const char* b3 = b2 + kstep;
;             if (last && has_next) S.a_ready(nxt);
;             if constexpr (SP2) {
;             PG8_LDB(B0, 0, 0); PG8_LDB(B1, 0, 1); PG8_SCHED; PG8_LDA(At, 0, 0); PG8_STAGE(PG8_SA(1, 1), a1 + hstep, voffA);
;             PG8_WAIT_V(8); PG8_WAIT_L(0); PG8_BAR; PG8_MMA(0, 0, At, B0); PG8_MMA(0, 1, At, B1); PG8_BAR; PG8_SCHED;
;             PG8_LDA(At, 0, 1); PG8_STAGE(PG8_SB(0, 0), b2, voffB); PG8_STAGE(PG8_SB(0, 1), b2 + hstep, voffB); PG8_STAGE(PG8_SA(0, 0), a2, voffA);
;             PG8_WAIT_V(8); PG8_WAIT_L(0); PG8_BAR; PG8_MMA(1, 0, At, B0); PG8_MMA(1, 1, At, B1); PG8_BAR; PG8_SCHED;
.LBB0_1956:
	ds_read_b128 v[140:143], v149
	ds_read_b128 v[152:155], v149 offset:1024
	ds_read_b128 v[156:159], v149 offset:2048
	ds_read_b128 v[160:163], v149 offset:3072
	ds_read_b128 v[164:167], v150
	ds_read_b128 v[168:171], v150 offset:1024
	ds_read_b128 v[172:175], v150 offset:2048
	ds_read_b128 v[176:179], v150 offset:3072
	s_add_u32 s22, s20, 0x100
	s_addc_u32 s23, s21, 0
	s_cmpk_eq_i32 s47, 0x54
	s_cselect_b32 s27, s5, s23
	s_cselect_b32 s26, s4, s22
	s_cselect_b32 s25, s19, s46
	s_cselect_b32 s24, s18, s45
	v_lshl_add_u64 v[144:145], s[20:21], 0, v[132:133]
	s_add_i32 m0, s31, 0xc000
	ds_read_b128 v[180:183], v151
	ds_read_b128 v[184:187], v151 offset:1024
	ds_read_b128 v[188:191], v151 offset:2048
	ds_read_b128 v[192:195], v151 offset:3072
	ds_read_b128 v[196:199], v151 offset:4096
	ds_read_b128 v[200:203], v151 offset:5120
	ds_read_b128 v[204:207], v151 offset:6144
	ds_read_b128 v[208:211], v151 offset:7168
	global_load_lds_dwordx4 v[144:145], off
	v_lshl_add_u64 v[144:145], s[20:21], 0, v[134:135]
	s_add_i32 m0, s31, 0xe000
	s_nop 0
	global_load_lds_dwordx4 v[144:145], off
	s_waitcnt vmcnt(8)
	s_waitcnt lgkmcnt(0)
	v_mfma_f32_16x16x32_bf16 v[124:127], v[140:143], v[180:183], v[124:127]
	v_mfma_f32_16x16x32_bf16 v[120:123], v[156:159], v[180:183], v[120:123]
	s_barrier
	s_waitcnt lgkmcnt(0)
	v_mfma_f32_16x16x32_bf16 v[108:111], v[140:143], v[188:191], v[108:111]
	v_mfma_f32_16x16x32_bf16 v[104:107], v[156:159], v[188:191], v[104:107]
	v_mfma_f32_16x16x32_bf16 v[92:95], v[140:143], v[196:199], v[92:95]
	v_mfma_f32_16x16x32_bf16 v[88:91], v[156:159], v[196:199], v[88:91]
	v_mfma_f32_16x16x32_bf16 v[76:79], v[140:143], v[204:207], v[76:79]
	v_mfma_f32_16x16x32_bf16 v[72:75], v[156:159], v[204:207], v[72:75]
	v_mfma_f32_16x16x32_bf16 v[124:127], v[152:155], v[184:187], v[124:127]
	v_mfma_f32_16x16x32_bf16 v[120:123], v[160:163], v[184:187], v[120:123]
	v_mfma_f32_16x16x32_bf16 v[108:111], v[152:155], v[192:195], v[108:111]
	v_mfma_f32_16x16x32_bf16 v[104:107], v[160:163], v[192:195], v[104:107]
	v_mfma_f32_16x16x32_bf16 v[92:95], v[152:155], v[200:203], v[92:95]
	v_mfma_f32_16x16x32_bf16 v[88:91], v[160:163], v[200:203], v[88:91]
	v_mfma_f32_16x16x32_bf16 v[76:79], v[152:155], v[208:211], v[76:79]
	v_mfma_f32_16x16x32_bf16 v[72:75], v[160:163], v[208:211], v[72:75]
	v_mfma_f32_16x16x32_bf16 v[116:119], v[164:167], v[180:183], v[116:119]
	v_mfma_f32_16x16x32_bf16 v[112:115], v[172:175], v[180:183], v[112:115]
	v_mfma_f32_16x16x32_bf16 v[100:103], v[164:167], v[188:191], v[100:103]
	v_mfma_f32_16x16x32_bf16 v[96:99], v[172:175], v[188:191], v[96:99]
	v_mfma_f32_16x16x32_bf16 v[84:87], v[164:167], v[196:199], v[84:87]
	v_mfma_f32_16x16x32_bf16 v[80:83], v[172:175], v[196:199], v[80:83]
	v_mfma_f32_16x16x32_bf16 v[68:71], v[164:167], v[204:207], v[68:71]
	v_mfma_f32_16x16x32_bf16 v[64:67], v[172:175], v[204:207], v[64:67]
	v_mfma_f32_16x16x32_bf16 v[116:119], v[168:171], v[184:187], v[116:119]
	v_mfma_f32_16x16x32_bf16 v[112:115], v[176:179], v[184:187], v[112:115]
	v_mfma_f32_16x16x32_bf16 v[100:103], v[168:171], v[192:195], v[100:103]
	v_mfma_f32_16x16x32_bf16 v[96:99], v[176:179], v[192:195], v[96:99]
	v_mfma_f32_16x16x32_bf16 v[84:87], v[168:171], v[200:203], v[84:87]
	v_mfma_f32_16x16x32_bf16 v[80:83], v[176:179], v[200:203], v[80:83]
	v_mfma_f32_16x16x32_bf16 v[68:71], v[168:171], v[208:211], v[68:71]
	v_mfma_f32_16x16x32_bf16 v[64:67], v[176:179], v[208:211], v[64:67]
	s_barrier
	s_add_i32 s20, s39, s30
	v_lshl_add_u64 v[144:145], s[24:25], 0, v[128:129]
	s_mov_b32 m0, s20
	ds_read_b128 v[180:183], v151 offset:16384
	ds_read_b128 v[184:187], v151 offset:17408
	ds_read_b128 v[188:191], v151 offset:18432
	ds_read_b128 v[192:195], v151 offset:19456
	ds_read_b128 v[196:199], v151 offset:20480
	ds_read_b128 v[200:203], v151 offset:21504
	ds_read_b128 v[204:207], v151 offset:22528
	ds_read_b128 v[208:211], v151 offset:23552
	global_load_lds_dwordx4 v[144:145], off
	s_add_i32 m0, s20, 0x2000
	s_add_u32 s20, s24, 0x160000
	v_lshl_add_u64 v[212:213], s[24:25], 0, v[130:131]
	s_addc_u32 s21, s25, 0
	s_add_i32 s48, s40, s30
	global_load_lds_dwordx4 v[212:213], off
	v_lshl_add_u64 v[214:215], s[20:21], 0, v[128:129]
	s_mov_b32 m0, s48
	v_lshl_add_u64 v[216:217], s[26:27], 0, v[130:131]
	global_load_lds_dwordx4 v[214:215], off
	v_lshl_add_u64 v[214:215], s[20:21], 0, v[130:131]
	s_add_i32 m0, s48, 0x2000
	s_nop 0
	global_load_lds_dwordx4 v[214:215], off
	v_lshl_add_u64 v[214:215], s[26:27], 0, v[128:129]
	s_mov_b32 m0, s31
	s_nop 0
	global_load_lds_dwordx4 v[214:215], off
	s_mov_b32 m0, s33
	s_nop 0
	global_load_lds_dwordx4 v[216:217], off
	s_waitcnt vmcnt(8)
	s_waitcnt lgkmcnt(0)
	v_mfma_f32_16x16x32_bf16 v[60:63], v[140:143], v[180:183], v[60:63]
	v_mfma_f32_16x16x32_bf16 v[56:59], v[156:159], v[180:183], v[56:59]
	s_barrier
; #define PG8_STAGE(bufoff, gbase, voff) do { _Pragma("unroll") for (int _i = 0; _i < 2; ++_i) \
;         __builtin_amdgcn_global_load_lds((const unsigned*)((const char*)(gbase) + (voff)[_i]), (PG8_LAS unsigned*)(lds + (bufoff) + ldsw + _i * 8192), 16, 0, 0); } while (0)
; #define PG8_LDA(dst, b, h) do { _Pragma("unroll") for (int m = 0; m < 4; ++m) _Pragma("unroll") for (int k = 0; k < 2; ++k) dst[m][k] = *(const PG8_LAS bf16x8*)(lds + PG8_SA(b, h) + aoff + m * 2048 + k * 1024); } while (0)
; #define PG8_LDB(dst, b, h) do { _Pragma("unroll") for (int n = 0; n < 2; ++n) _Pragma("unroll") for (int k = 0; k < 2; ++k) dst[n][k] = *(const PG8_LAS bf16x8*)(lds + PG8_SB(b, h) + boff + n * 2048 + k * 1024); } while (0)
; #define PG8_MMA(ai, bj, At, Bt) do { __builtin_amdgcn_s_setprio(1); _Pragma("unroll") for (int m = 0; m < 4; ++m) _Pragma("unroll") for (int n = 0; n < 2; ++n) _Pragma("unroll") for (int k = 0; k < 2; ++k) \
;         acc[ai][bj][m][n] = __builtin_amdgcn_mfma_f32_16x16x32_bf16(Bt[n][k], At[m][k], acc[ai][bj][m][n], 0, 0, 0); __builtin_amdgcn_s_setprio(0); } while (0)
; #define PG8_WAIT_V(n) asm volatile("s_waitcnt vmcnt(" #n ")" ::: "memory")
; #define PG8_WAIT_L(n) asm volatile("s_waitcnt lgkmcnt(" #n ")" ::: "memory")
; #define PG8_BAR __builtin_amdgcn_s_barrier()
; #define PG8_SCHED __builtin_amdgcn_sched_barrier(0)
; template <class Epi, class Sched, bool ALIGN_EPI = false, bool SP2 = false>
; __device__ __forceinline__ void gemm_phase(PG8_LAS unsigned char* lds, const Gemm g, const Sched& S, const Epi& E) {
;     ...
;             PG8_WAIT_V(8); PG8_WAIT_L(0); PG8_BAR; PG8_MMA(1, 0, At, B0); PG8_MMA(1, 1, At, B1); PG8_BAR; PG8_SCHED;
;             PG8_LDB(B0, 1, 0); PG8_LDB(B1, 1, 1); PG8_SCHED; PG8_LDA(At, 1, 0); PG8_STAGE(PG8_SA(0, 1), a2 + hstep, voffA);
;             PG8_WAIT_V(8); PG8_WAIT_L(0); PG8_BAR; PG8_MMA(0, 0, At, B0); PG8_MMA(0, 1, At, B1); PG8_BAR; PG8_SCHED;
	s_waitcnt lgkmcnt(0)
	v_mfma_f32_16x16x32_bf16 v[44:47], v[140:143], v[188:191], v[44:47]
	v_mfma_f32_16x16x32_bf16 v[40:43], v[156:159], v[188:191], v[40:43]
	v_mfma_f32_16x16x32_bf16 v[28:31], v[140:143], v[196:199], v[28:31]
	v_mfma_f32_16x16x32_bf16 v[24:27], v[156:159], v[196:199], v[24:27]
	v_mfma_f32_16x16x32_bf16 v[12:15], v[140:143], v[204:207], v[12:15]
	v_mfma_f32_16x16x32_bf16 v[8:11], v[156:159], v[204:207], v[8:11]
	v_mfma_f32_16x16x32_bf16 v[60:63], v[152:155], v[184:187], v[60:63]
	v_mfma_f32_16x16x32_bf16 v[56:59], v[160:163], v[184:187], v[56:59]
	v_mfma_f32_16x16x32_bf16 v[44:47], v[152:155], v[192:195], v[44:47]
	v_mfma_f32_16x16x32_bf16 v[40:43], v[160:163], v[192:195], v[40:43]
	v_mfma_f32_16x16x32_bf16 v[28:31], v[152:155], v[200:203], v[28:31]
	v_mfma_f32_16x16x32_bf16 v[24:27], v[160:163], v[200:203], v[24:27]
	v_mfma_f32_16x16x32_bf16 v[12:15], v[152:155], v[208:211], v[12:15]
	v_mfma_f32_16x16x32_bf16 v[8:11], v[160:163], v[208:211], v[8:11]
	v_mfma_f32_16x16x32_bf16 v[52:55], v[164:167], v[180:183], v[52:55]
	v_mfma_f32_16x16x32_bf16 v[48:51], v[172:175], v[180:183], v[48:51]
	v_mfma_f32_16x16x32_bf16 v[36:39], v[164:167], v[188:191], v[36:39]
	v_mfma_f32_16x16x32_bf16 v[32:35], v[172:175], v[188:191], v[32:35]
	v_mfma_f32_16x16x32_bf16 v[20:23], v[164:167], v[196:199], v[20:23]
	v_mfma_f32_16x16x32_bf16 v[16:19], v[172:175], v[196:199], v[16:19]
	v_mfma_f32_16x16x32_bf16 v[4:7], v[164:167], v[204:207], v[4:7]
	v_mfma_f32_16x16x32_bf16 v[0:3], v[172:175], v[204:207], v[0:3]
	v_mfma_f32_16x16x32_bf16 v[52:55], v[168:171], v[184:187], v[52:55]
	v_mfma_f32_16x16x32_bf16 v[48:51], v[176:179], v[184:187], v[48:51]
	v_mfma_f32_16x16x32_bf16 v[36:39], v[168:171], v[192:195], v[36:39]
	v_mfma_f32_16x16x32_bf16 v[32:35], v[176:179], v[192:195], v[32:35]
	v_mfma_f32_16x16x32_bf16 v[20:23], v[168:171], v[200:203], v[20:23]
	v_mfma_f32_16x16x32_bf16 v[16:19], v[176:179], v[200:203], v[16:19]
	v_mfma_f32_16x16x32_bf16 v[4:7], v[168:171], v[208:211], v[4:7]
	v_mfma_f32_16x16x32_bf16 v[0:3], v[176:179], v[208:211], v[0:3]
	s_barrier
	s_add_i32 s48, 0, 0x18000
	s_add_i32 s49, 0, 0x1c000
	v_add_u32_e32 v160, s48, v147
	v_add_u32_e32 v176, s49, v147
	ds_read_b128 v[140:143], v160
	ds_read_b128 v[152:155], v160 offset:1024
	ds_read_b128 v[156:159], v160 offset:2048
	ds_read_b128 v[160:163], v160 offset:3072
	ds_read_b128 v[164:167], v176
	ds_read_b128 v[168:171], v176 offset:1024
	ds_read_b128 v[172:175], v176 offset:2048
	ds_read_b128 v[176:179], v176 offset:3072
	s_add_u32 s20, s26, 0x160000
	s_addc_u32 s21, s27, 0
	s_mov_b32 m0, s34
	v_lshl_add_u64 v[218:219], s[20:21], 0, v[128:129]
	ds_read_b128 v[180:183], v151 offset:32768
	ds_read_b128 v[184:187], v151 offset:33792
	ds_read_b128 v[188:191], v151 offset:34816
	ds_read_b128 v[192:195], v151 offset:35840
	ds_read_b128 v[196:199], v151 offset:36864
	ds_read_b128 v[200:203], v151 offset:37888
	ds_read_b128 v[204:207], v151 offset:38912
	ds_read_b128 v[208:211], v151 offset:39936
	global_load_lds_dwordx4 v[218:219], off
	v_lshl_add_u64 v[218:219], s[20:21], 0, v[130:131]
	s_mov_b32 m0, s35
	s_nop 0
	global_load_lds_dwordx4 v[218:219], off
	s_waitcnt vmcnt(8)
	s_waitcnt lgkmcnt(0)
	v_mfma_f32_16x16x32_bf16 v[124:127], v[140:143], v[180:183], v[124:127]
	v_mfma_f32_16x16x32_bf16 v[120:123], v[156:159], v[180:183], v[120:123]
	s_barrier
	s_waitcnt lgkmcnt(0)
	v_mfma_f32_16x16x32_bf16 v[108:111], v[140:143], v[188:191], v[108:111]
	v_mfma_f32_16x16x32_bf16 v[104:107], v[156:159], v[188:191], v[104:107]
	v_mfma_f32_16x16x32_bf16 v[92:95], v[140:143], v[196:199], v[92:95]
	v_mfma_f32_16x16x32_bf16 v[88:91], v[156:159], v[196:199], v[88:91]
	v_mfma_f32_16x16x32_bf16 v[76:79], v[140:143], v[204:207], v[76:79]
	v_mfma_f32_16x16x32_bf16 v[72:75], v[156:159], v[204:207], v[72:75]
	v_mfma_f32_16x16x32_bf16 v[124:127], v[152:155], v[184:187], v[124:127]
	v_mfma_f32_16x16x32_bf16 v[120:123], v[160:163], v[184:187], v[120:123]
	v_mfma_f32_16x16x32_bf16 v[108:111], v[152:155], v[192:195], v[108:111]
	v_mfma_f32_16x16x32_bf16 v[104:107], v[160:163], v[192:195], v[104:107]
	v_mfma_f32_16x16x32_bf16 v[92:95], v[152:155], v[200:203], v[92:95]
	v_mfma_f32_16x16x32_bf16 v[88:91], v[160:163], v[200:203], v[88:91]
	v_mfma_f32_16x16x32_bf16 v[76:79], v[152:155], v[208:211], v[76:79]
	v_mfma_f32_16x16x32_bf16 v[72:75], v[160:163], v[208:211], v[72:75]
	v_mfma_f32_16x16x32_bf16 v[116:119], v[164:167], v[180:183], v[116:119]
	v_mfma_f32_16x16x32_bf16 v[112:115], v[172:175], v[180:183], v[112:115]
	v_mfma_f32_16x16x32_bf16 v[100:103], v[164:167], v[188:191], v[100:103]
	v_mfma_f32_16x16x32_bf16 v[96:99], v[172:175], v[188:191], v[96:99]
	v_mfma_f32_16x16x32_bf16 v[84:87], v[164:167], v[196:199], v[84:87]
	v_mfma_f32_16x16x32_bf16 v[80:83], v[172:175], v[196:199], v[80:83]
	v_mfma_f32_16x16x32_bf16 v[68:71], v[164:167], v[204:207], v[68:71]
	v_mfma_f32_16x16x32_bf16 v[64:67], v[172:175], v[204:207], v[64:67]
	v_mfma_f32_16x16x32_bf16 v[116:119], v[168:171], v[184:187], v[116:119]
	v_mfma_f32_16x16x32_bf16 v[112:115], v[176:179], v[184:187], v[112:115]
	v_mfma_f32_16x16x32_bf16 v[100:103], v[168:171], v[192:195], v[100:103]
	v_mfma_f32_16x16x32_bf16 v[96:99], v[176:179], v[192:195], v[96:99]
	v_mfma_f32_16x16x32_bf16 v[84:87], v[168:171], v[200:203], v[84:87]
	v_mfma_f32_16x16x32_bf16 v[80:83], v[176:179], v[200:203], v[80:83]
	v_mfma_f32_16x16x32_bf16 v[68:71], v[168:171], v[208:211], v[68:71]
	v_mfma_f32_16x16x32_bf16 v[64:67], v[176:179], v[208:211], v[64:67]
	s_barrier
; #define PG8_STAGE(bufoff, gbase, voff) do { _Pragma("unroll") for (int _i = 0; _i < 2; ++_i) \
;         __builtin_amdgcn_global_load_lds((const unsigned*)((const char*)(gbase) + (voff)[_i]), (PG8_LAS unsigned*)(lds + (bufoff) + ldsw + _i * 8192), 16, 0, 0); } while (0)
; #define PG8_LDA(dst, b, h) do { _Pragma("unroll") for (int m = 0; m < 4; ++m) _Pragma("unroll") for (int k = 0; k < 2; ++k) dst[m][k] = *(const PG8_LAS bf16x8*)(lds + PG8_SA(b, h) + aoff + m * 2048 + k * 1024); } while (0)
; #define PG8_MMA(ai, bj, At, Bt) do { __builtin_amdgcn_s_setprio(1); _Pragma("unroll") for (int m = 0; m < 4; ++m) _Pragma("unroll") for (int n = 0; n < 2; ++n) _Pragma("unroll") for (int k = 0; k < 2; ++k) \
;         acc[ai][bj][m][n] = __builtin_amdgcn_mfma_f32_16x16x32_bf16(Bt[n][k], At[m][k], acc[ai][bj][m][n], 0, 0, 0); __builtin_amdgcn_s_setprio(0); } while (0)
; #define PG8_WAIT_V(n) asm volatile("s_waitcnt vmcnt(" #n ")" ::: "memory")
; #define PG8_WAIT_L(n) asm volatile("s_waitcnt lgkmcnt(" #n ")" ::: "memory")
; #define PG8_BAR __builtin_amdgcn_s_barrier()
; #define PG8_SCHED __builtin_amdgcn_sched_barrier(0)
; template <class Epi, class Sched, bool ALIGN_EPI = false, bool SP2 = false>
; __device__ __forceinline__ void gemm_phase(PG8_LAS unsigned char* lds, const Gemm g, const Sched& S, const Epi& E) {
;     ...
;             PG8_LDA(At, 1, 1); PG8_STAGE(PG8_SB(1, 0), b3, voffB); PG8_STAGE(PG8_SB(1, 1), b3 + hstep, voffB); PG8_STAGE(PG8_SA(1, 0), a3, voffA);
;             PG8_WAIT_V(8); PG8_WAIT_L(0); PG8_BAR; PG8_MMA(1, 0, At, B0); PG8_MMA(1, 1, At, B1); PG8_BAR; PG8_SCHED;
	s_add_i32 s20, s48, s30
	v_lshl_add_u64 v[144:145], v[144:145], 0, s[6:7]
	s_mov_b32 m0, s20
	ds_read_b128 v[180:183], v151 offset:49152
	ds_read_b128 v[184:187], v151 offset:50176
	ds_read_b128 v[188:191], v151 offset:51200
	ds_read_b128 v[192:195], v151 offset:52224
	ds_read_b128 v[196:199], v151 offset:53248
	ds_read_b128 v[200:203], v151 offset:54272
	ds_read_b128 v[204:207], v151 offset:55296
	ds_read_b128 v[208:211], v151 offset:56320
	global_load_lds_dwordx4 v[144:145], off
	s_add_i32 m0, s20, 0x2000
	s_add_u32 s20, s24, 0x160080
	v_lshl_add_u64 v[144:145], v[212:213], 0, s[6:7]
	s_addc_u32 s21, s25, 0
	s_add_i32 s24, s49, s30
	global_load_lds_dwordx4 v[144:145], off
	v_lshl_add_u64 v[144:145], s[20:21], 0, v[128:129]
	s_mov_b32 m0, s24
	s_nop 0
	global_load_lds_dwordx4 v[144:145], off
	v_lshl_add_u64 v[144:145], s[20:21], 0, v[130:131]
	s_add_i32 m0, s24, 0x2000
	s_nop 0
	global_load_lds_dwordx4 v[144:145], off
	v_lshl_add_u64 v[144:145], v[214:215], 0, s[6:7]
	s_mov_b32 m0, s37
	s_nop 0
	global_load_lds_dwordx4 v[144:145], off
	v_lshl_add_u64 v[144:145], v[216:217], 0, s[6:7]
	s_mov_b32 m0, s38
	s_nop 0
	global_load_lds_dwordx4 v[144:145], off
	s_waitcnt vmcnt(8)
	s_waitcnt lgkmcnt(0)
	v_mfma_f32_16x16x32_bf16 v[60:63], v[140:143], v[180:183], v[60:63]
	v_mfma_f32_16x16x32_bf16 v[56:59], v[156:159], v[180:183], v[56:59]
	s_barrier
	s_waitcnt lgkmcnt(0)
	v_mfma_f32_16x16x32_bf16 v[44:47], v[140:143], v[188:191], v[44:47]
	v_mfma_f32_16x16x32_bf16 v[40:43], v[156:159], v[188:191], v[40:43]
	v_mfma_f32_16x16x32_bf16 v[28:31], v[140:143], v[196:199], v[28:31]
	v_mfma_f32_16x16x32_bf16 v[24:27], v[156:159], v[196:199], v[24:27]
	v_mfma_f32_16x16x32_bf16 v[12:15], v[140:143], v[204:207], v[12:15]
	v_mfma_f32_16x16x32_bf16 v[8:11], v[156:159], v[204:207], v[8:11]
	v_mfma_f32_16x16x32_bf16 v[60:63], v[152:155], v[184:187], v[60:63]
	v_mfma_f32_16x16x32_bf16 v[56:59], v[160:163], v[184:187], v[56:59]
	v_mfma_f32_16x16x32_bf16 v[44:47], v[152:155], v[192:195], v[44:47]
	v_mfma_f32_16x16x32_bf16 v[40:43], v[160:163], v[192:195], v[40:43]
	v_mfma_f32_16x16x32_bf16 v[28:31], v[152:155], v[200:203], v[28:31]
	v_mfma_f32_16x16x32_bf16 v[24:27], v[160:163], v[200:203], v[24:27]
	v_mfma_f32_16x16x32_bf16 v[12:15], v[152:155], v[208:211], v[12:15]
	v_mfma_f32_16x16x32_bf16 v[8:11], v[160:163], v[208:211], v[8:11]
	v_mfma_f32_16x16x32_bf16 v[52:55], v[164:167], v[180:183], v[52:55]
	v_mfma_f32_16x16x32_bf16 v[48:51], v[172:175], v[180:183], v[48:51]
	v_mfma_f32_16x16x32_bf16 v[36:39], v[164:167], v[188:191], v[36:39]
	v_mfma_f32_16x16x32_bf16 v[32:35], v[172:175], v[188:191], v[32:35]
	v_mfma_f32_16x16x32_bf16 v[20:23], v[164:167], v[196:199], v[20:23]
	v_mfma_f32_16x16x32_bf16 v[16:19], v[172:175], v[196:199], v[16:19]
	v_mfma_f32_16x16x32_bf16 v[4:7], v[164:167], v[204:207], v[4:7]
	v_mfma_f32_16x16x32_bf16 v[0:3], v[172:175], v[204:207], v[0:3]
	v_mfma_f32_16x16x32_bf16 v[52:55], v[168:171], v[184:187], v[52:55]
	v_mfma_f32_16x16x32_bf16 v[48:51], v[176:179], v[184:187], v[48:51]
	v_mfma_f32_16x16x32_bf16 v[36:39], v[168:171], v[192:195], v[36:39]
	v_mfma_f32_16x16x32_bf16 v[32:35], v[176:179], v[192:195], v[32:35]
	v_mfma_f32_16x16x32_bf16 v[20:23], v[168:171], v[200:203], v[20:23]
	v_mfma_f32_16x16x32_bf16 v[16:19], v[176:179], v[200:203], v[16:19]
	v_mfma_f32_16x16x32_bf16 v[4:7], v[168:171], v[208:211], v[4:7]
	v_mfma_f32_16x16x32_bf16 v[0:3], v[176:179], v[208:211], v[0:3]
	s_barrier
	s_add_i32 s47, s47, 2
	s_add_u32 s45, s45, 0x100
	s_addc_u32 s46, s46, 0
	s_cmpk_gt_u32 s47, 0x55
	s_mov_b64 s[20:21], s[22:23]
	s_cbranch_scc0 .LBB0_1956
	s_and_b64 vcc, exec, s[8:9]
	s_cbranch_vccz .LBB0_1959
	s_barrier
